# speedup vs baseline: 1.0364x; 1.0118x over previous
.LBB0_52:
	ds_read_b128 v[142:145], v166
	ds_read_b128 v[170:173], v166 offset:1024
	ds_read_b128 v[174:177], v166 offset:2048
	ds_read_b128 v[178:181], v166 offset:3072
	v_add_u32_e32 v167, 0xc000, v152
	v_lshl_add_u64 v[236:237], v[138:139], 0, s[76:77]
	v_readfirstlane_b32 s5, v167
	v_lshl_add_u64 v[168:169], v[236:237], 0, s[42:43]
	s_mov_b32 m0, s5
	ds_read_b128 v[182:185], v150
	ds_read_b128 v[192:195], v150 offset:1024
	ds_read_b128 v[196:199], v149
	ds_read_b128 v[200:203], v149 offset:1024
	ds_read_b128 v[204:207], v148
	ds_read_b128 v[208:211], v148 offset:1024
	ds_read_b128 v[212:215], v147
	ds_read_b128 v[216:219], v147 offset:1024
	global_load_lds_dwordx4 v[168:169], off
	v_add_u32_e32 v168, 0xe000, v152
	v_lshl_add_u64 v[238:239], v[140:141], 0, s[76:77]
	v_readfirstlane_b32 s5, v168
	v_lshl_add_u64 v[220:221], v[238:239], 0, s[42:43]
	s_mov_b32 m0, s5
	s_nop 0
	global_load_lds_dwordx4 v[220:221], off
	s_waitcnt lgkmcnt(8)
	s_barrier
	s_waitcnt lgkmcnt(0)
	s_setprio 1
	v_mfma_f32_16x16x32_bf16 v[126:129], v[182:185], v[142:145], v[126:129]
	v_mfma_f32_16x16x32_bf16 v[122:125], v[182:185], v[174:177], v[122:125]
	v_mfma_f32_16x16x32_bf16 v[118:121], v[196:199], v[142:145], v[118:121]
	v_mfma_f32_16x16x32_bf16 v[114:117], v[196:199], v[174:177], v[114:117]
	v_mfma_f32_16x16x32_bf16 v[108:111], v[204:207], v[142:145], v[108:111]
	v_mfma_f32_16x16x32_bf16 v[104:107], v[204:207], v[174:177], v[104:107]
	v_mfma_f32_16x16x32_bf16 v[100:103], v[212:215], v[142:145], v[100:103]
	v_mfma_f32_16x16x32_bf16 v[96:99], v[212:215], v[174:177], v[96:99]
	v_mfma_f32_16x16x32_bf16 v[126:129], v[192:195], v[170:173], v[126:129]
	v_mfma_f32_16x16x32_bf16 v[122:125], v[192:195], v[178:181], v[122:125]
	v_mfma_f32_16x16x32_bf16 v[118:121], v[200:203], v[170:173], v[118:121]
	v_mfma_f32_16x16x32_bf16 v[114:117], v[200:203], v[178:181], v[114:117]
	v_mfma_f32_16x16x32_bf16 v[108:111], v[208:211], v[170:173], v[108:111]
	v_mfma_f32_16x16x32_bf16 v[104:107], v[208:211], v[178:181], v[104:107]
	v_mfma_f32_16x16x32_bf16 v[100:103], v[216:219], v[170:173], v[100:103]
	v_mfma_f32_16x16x32_bf16 v[96:99], v[216:219], v[178:181], v[96:99]
	s_setprio 0
	s_barrier
	v_lshl_add_u64 v[240:241], v[134:135], 0, s[76:77]
	v_readfirstlane_b32 s5, v146
	v_lshl_add_u64 v[242:243], v[240:241], 0, s[44:45]
	s_mov_b32 m0, s5
	v_add_u32_e32 v169, 0x2000, v146
	ds_read_b128 v[220:223], v165
	ds_read_b128 v[224:227], v165 offset:1024
	ds_read_b128 v[228:231], v165 offset:2048
	ds_read_b128 v[232:235], v165 offset:3072
	global_load_lds_dwordx4 v[242:243], off
	v_lshl_add_u64 v[242:243], v[136:137], 0, s[76:77]
	v_readfirstlane_b32 s5, v169
	v_lshl_add_u64 v[244:245], v[242:243], 0, s[44:45]
	s_mov_b32 m0, s5
	s_nop 0
	global_load_lds_dwordx4 v[244:245], off
	s_barrier
	s_waitcnt lgkmcnt(0)
	s_setprio 1
	v_mfma_f32_16x16x32_bf16 v[88:91], v[182:185], v[220:223], v[88:91]
	v_mfma_f32_16x16x32_bf16 v[72:75], v[182:185], v[228:231], v[72:75]
	v_mfma_f32_16x16x32_bf16 v[56:59], v[196:199], v[220:223], v[56:59]
	v_mfma_f32_16x16x32_bf16 v[48:51], v[196:199], v[228:231], v[48:51]
	v_mfma_f32_16x16x32_bf16 v[44:47], v[204:207], v[220:223], v[44:47]
	v_mfma_f32_16x16x32_bf16 v[40:43], v[204:207], v[228:231], v[40:43]
	v_mfma_f32_16x16x32_bf16 v[36:39], v[212:215], v[220:223], v[36:39]
	v_mfma_f32_16x16x32_bf16 v[32:35], v[212:215], v[228:231], v[32:35]
	v_mfma_f32_16x16x32_bf16 v[88:91], v[192:195], v[224:227], v[88:91]
	v_mfma_f32_16x16x32_bf16 v[72:75], v[192:195], v[232:235], v[72:75]
	v_mfma_f32_16x16x32_bf16 v[56:59], v[200:203], v[224:227], v[56:59]
	v_mfma_f32_16x16x32_bf16 v[48:51], v[200:203], v[232:235], v[48:51]
	v_mfma_f32_16x16x32_bf16 v[44:47], v[208:211], v[224:227], v[44:47]
	v_mfma_f32_16x16x32_bf16 v[40:43], v[208:211], v[232:235], v[40:43]
	v_mfma_f32_16x16x32_bf16 v[36:39], v[216:219], v[224:227], v[36:39]
	v_mfma_f32_16x16x32_bf16 v[32:35], v[216:219], v[232:235], v[32:35]
	s_setprio 0
	v_readfirstlane_b32 s5, v152
	v_lshl_add_u64 v[244:245], v[236:237], 0, s[44:45]
	s_mov_b32 m0, s5
	v_readfirstlane_b32 s5, v153
	s_barrier
	ds_read_b128 v[182:185], v150 offset:16384
	ds_read_b128 v[192:195], v150 offset:17408
	ds_read_b128 v[196:199], v149 offset:16384
	ds_read_b128 v[200:203], v149 offset:17408
	ds_read_b128 v[204:207], v148 offset:16384
	ds_read_b128 v[208:211], v148 offset:17408
	ds_read_b128 v[212:215], v147 offset:16384
	ds_read_b128 v[216:219], v147 offset:17408
	global_load_lds_dwordx4 v[244:245], off
	v_lshl_add_u64 v[244:245], v[238:239], 0, s[44:45]
	s_mov_b32 m0, s5
	s_nop 0
	global_load_lds_dwordx4 v[244:245], off
	s_barrier
	s_waitcnt lgkmcnt(0)
	s_setprio 1
	v_mfma_f32_16x16x32_bf16 v[28:31], v[182:185], v[142:145], v[28:31]
	v_mfma_f32_16x16x32_bf16 v[24:27], v[182:185], v[174:177], v[24:27]
	v_mfma_f32_16x16x32_bf16 v[20:23], v[196:199], v[142:145], v[20:23]
	v_mfma_f32_16x16x32_bf16 v[16:19], v[196:199], v[174:177], v[16:19]
	v_mfma_f32_16x16x32_bf16 v[12:15], v[204:207], v[142:145], v[12:15]
	v_mfma_f32_16x16x32_bf16 v[8:11], v[204:207], v[174:177], v[8:11]
	v_mfma_f32_16x16x32_bf16 v[4:7], v[212:215], v[142:145], v[4:7]
	v_mfma_f32_16x16x32_bf16 v[0:3], v[212:215], v[174:177], v[0:3]
	v_mfma_f32_16x16x32_bf16 v[28:31], v[192:195], v[170:173], v[28:31]
	v_mfma_f32_16x16x32_bf16 v[24:27], v[192:195], v[178:181], v[24:27]
	v_mfma_f32_16x16x32_bf16 v[20:23], v[200:203], v[170:173], v[20:23]
	v_mfma_f32_16x16x32_bf16 v[16:19], v[200:203], v[178:181], v[16:19]
	v_mfma_f32_16x16x32_bf16 v[12:15], v[208:211], v[170:173], v[12:15]
	v_mfma_f32_16x16x32_bf16 v[8:11], v[208:211], v[178:181], v[8:11]
	v_mfma_f32_16x16x32_bf16 v[4:7], v[216:219], v[170:173], v[4:7]
	v_mfma_f32_16x16x32_bf16 v[0:3], v[216:219], v[178:181], v[0:3]
	s_setprio 0
	s_barrier
	v_readfirstlane_b32 s5, v154
	v_add_u32_e32 v144, 0x2000, v154
	v_lshl_add_u64 v[142:143], v[240:241], 0, s[46:47]
	s_mov_b32 m0, s5
	v_readfirstlane_b32 s5, v144
	global_load_lds_dwordx4 v[142:143], off
	v_lshl_add_u64 v[142:143], v[242:243], 0, s[46:47]
	s_mov_b32 m0, s5
	s_nop 0
	global_load_lds_dwordx4 v[142:143], off
	s_waitcnt vmcnt(6)
	s_barrier
	s_setprio 1
	v_mfma_f32_16x16x32_bf16 v[52:55], v[182:185], v[220:223], v[52:55]
	v_mfma_f32_16x16x32_bf16 v[60:63], v[182:185], v[228:231], v[60:63]
	v_mfma_f32_16x16x32_bf16 v[64:67], v[196:199], v[220:223], v[64:67]
	v_mfma_f32_16x16x32_bf16 v[68:71], v[196:199], v[228:231], v[68:71]
	v_mfma_f32_16x16x32_bf16 v[76:79], v[204:207], v[220:223], v[76:79]
	v_mfma_f32_16x16x32_bf16 v[80:83], v[204:207], v[228:231], v[80:83]
	v_mfma_f32_16x16x32_bf16 v[84:87], v[212:215], v[220:223], v[84:87]
	v_mfma_f32_16x16x32_bf16 v[92:95], v[212:215], v[228:231], v[92:95]
	v_mfma_f32_16x16x32_bf16 v[52:55], v[192:195], v[224:227], v[52:55]
	v_mfma_f32_16x16x32_bf16 v[60:63], v[192:195], v[232:235], v[60:63]
	v_mfma_f32_16x16x32_bf16 v[64:67], v[200:203], v[224:227], v[64:67]
	v_mfma_f32_16x16x32_bf16 v[68:71], v[200:203], v[232:235], v[68:71]
	v_mfma_f32_16x16x32_bf16 v[76:79], v[208:211], v[224:227], v[76:79]
	v_mfma_f32_16x16x32_bf16 v[80:83], v[208:211], v[232:235], v[80:83]
	v_mfma_f32_16x16x32_bf16 v[84:87], v[216:219], v[224:227], v[84:87]
	v_mfma_f32_16x16x32_bf16 v[92:95], v[216:219], v[232:235], v[92:95]
	s_setprio 0
	s_barrier
	ds_read_b128 v[142:145], v155
	ds_read_b128 v[170:173], v155 offset:1024
	ds_read_b128 v[174:177], v155 offset:2048
	ds_read_b128 v[178:181], v155 offset:3072
	v_readfirstlane_b32 s5, v156
	v_lshl_add_u64 v[220:221], v[236:237], 0, s[46:47]
	s_mov_b32 m0, s5
	v_readfirstlane_b32 s5, v157
	ds_read_b128 v[182:185], v150 offset:32768
	ds_read_b128 v[192:195], v150 offset:33792
	ds_read_b128 v[196:199], v149 offset:32768
	ds_read_b128 v[200:203], v149 offset:33792
	ds_read_b128 v[204:207], v148 offset:32768
	ds_read_b128 v[208:211], v148 offset:33792
	ds_read_b128 v[212:215], v147 offset:32768
	ds_read_b128 v[216:219], v147 offset:33792
	global_load_lds_dwordx4 v[220:221], off
	v_lshl_add_u64 v[220:221], v[238:239], 0, s[46:47]
	s_mov_b32 m0, s5
	s_nop 0
	global_load_lds_dwordx4 v[220:221], off
	s_waitcnt lgkmcnt(8)
	s_barrier
	s_waitcnt lgkmcnt(0)
	s_setprio 1
	v_mfma_f32_16x16x32_bf16 v[126:129], v[182:185], v[142:145], v[126:129]
	v_mfma_f32_16x16x32_bf16 v[122:125], v[182:185], v[174:177], v[122:125]
	v_mfma_f32_16x16x32_bf16 v[118:121], v[196:199], v[142:145], v[118:121]
	v_mfma_f32_16x16x32_bf16 v[114:117], v[196:199], v[174:177], v[114:117]
	v_mfma_f32_16x16x32_bf16 v[108:111], v[204:207], v[142:145], v[108:111]
	v_mfma_f32_16x16x32_bf16 v[104:107], v[204:207], v[174:177], v[104:107]
	v_mfma_f32_16x16x32_bf16 v[100:103], v[212:215], v[142:145], v[100:103]
	v_mfma_f32_16x16x32_bf16 v[96:99], v[212:215], v[174:177], v[96:99]
	v_mfma_f32_16x16x32_bf16 v[126:129], v[192:195], v[170:173], v[126:129]
	v_mfma_f32_16x16x32_bf16 v[122:125], v[192:195], v[178:181], v[122:125]
	v_mfma_f32_16x16x32_bf16 v[118:121], v[200:203], v[170:173], v[118:121]
	v_mfma_f32_16x16x32_bf16 v[114:117], v[200:203], v[178:181], v[114:117]
	v_mfma_f32_16x16x32_bf16 v[108:111], v[208:211], v[170:173], v[108:111]
	v_mfma_f32_16x16x32_bf16 v[104:107], v[208:211], v[178:181], v[104:107]
	v_mfma_f32_16x16x32_bf16 v[100:103], v[216:219], v[170:173], v[100:103]
	v_mfma_f32_16x16x32_bf16 v[96:99], v[216:219], v[178:181], v[96:99]
	s_setprio 0
	s_barrier
	v_readfirstlane_b32 s5, v158
	v_lshl_add_u64 v[244:245], v[240:241], 0, s[48:49]
	s_mov_b32 m0, s5
	v_readfirstlane_b32 s5, v159
	ds_read_b128 v[220:223], v151
	ds_read_b128 v[224:227], v151 offset:1024
	ds_read_b128 v[228:231], v151 offset:2048
	ds_read_b128 v[232:235], v151 offset:3072
	global_load_lds_dwordx4 v[244:245], off
	v_lshl_add_u64 v[244:245], v[242:243], 0, s[48:49]
	s_mov_b32 m0, s5
	s_nop 0
	global_load_lds_dwordx4 v[244:245], off
	s_barrier
	s_waitcnt lgkmcnt(0)
	s_setprio 1
	v_mfma_f32_16x16x32_bf16 v[88:91], v[182:185], v[220:223], v[88:91]
	v_mfma_f32_16x16x32_bf16 v[72:75], v[182:185], v[228:231], v[72:75]
	v_mfma_f32_16x16x32_bf16 v[56:59], v[196:199], v[220:223], v[56:59]
	v_mfma_f32_16x16x32_bf16 v[48:51], v[196:199], v[228:231], v[48:51]
	v_mfma_f32_16x16x32_bf16 v[44:47], v[204:207], v[220:223], v[44:47]
	v_mfma_f32_16x16x32_bf16 v[40:43], v[204:207], v[228:231], v[40:43]
	v_mfma_f32_16x16x32_bf16 v[36:39], v[212:215], v[220:223], v[36:39]
	v_mfma_f32_16x16x32_bf16 v[32:35], v[212:215], v[228:231], v[32:35]
	v_mfma_f32_16x16x32_bf16 v[88:91], v[192:195], v[224:227], v[88:91]
	v_mfma_f32_16x16x32_bf16 v[72:75], v[192:195], v[232:235], v[72:75]
	v_mfma_f32_16x16x32_bf16 v[56:59], v[200:203], v[224:227], v[56:59]
	v_mfma_f32_16x16x32_bf16 v[48:51], v[200:203], v[232:235], v[48:51]
	v_mfma_f32_16x16x32_bf16 v[44:47], v[208:211], v[224:227], v[44:47]
	v_mfma_f32_16x16x32_bf16 v[40:43], v[208:211], v[232:235], v[40:43]
	v_mfma_f32_16x16x32_bf16 v[36:39], v[216:219], v[224:227], v[36:39]
	v_mfma_f32_16x16x32_bf16 v[32:35], v[216:219], v[232:235], v[32:35]
	s_setprio 0
	v_readfirstlane_b32 s5, v160
	v_lshl_add_u64 v[236:237], v[236:237], 0, s[48:49]
	s_mov_b32 m0, s5
	v_readfirstlane_b32 s5, v161
	s_barrier
	ds_read_b128 v[182:185], v150 offset:49152
	ds_read_b128 v[192:195], v150 offset:50176
	ds_read_b128 v[196:199], v149 offset:49152
	ds_read_b128 v[200:203], v149 offset:50176
	ds_read_b128 v[204:207], v148 offset:49152
	ds_read_b128 v[208:211], v148 offset:50176
	ds_read_b128 v[212:215], v147 offset:49152
	ds_read_b128 v[216:219], v147 offset:50176
	global_load_lds_dwordx4 v[236:237], off
	v_lshl_add_u64 v[236:237], v[238:239], 0, s[48:49]
	s_mov_b32 m0, s5
	s_nop 0
	global_load_lds_dwordx4 v[236:237], off
	s_barrier
	s_waitcnt lgkmcnt(0)
	s_setprio 1
	v_mfma_f32_16x16x32_bf16 v[28:31], v[182:185], v[142:145], v[28:31]
	v_mfma_f32_16x16x32_bf16 v[24:27], v[182:185], v[174:177], v[24:27]
	v_mfma_f32_16x16x32_bf16 v[20:23], v[196:199], v[142:145], v[20:23]
	v_mfma_f32_16x16x32_bf16 v[16:19], v[196:199], v[174:177], v[16:19]
	v_mfma_f32_16x16x32_bf16 v[12:15], v[204:207], v[142:145], v[12:15]
	v_mfma_f32_16x16x32_bf16 v[8:11], v[204:207], v[174:177], v[8:11]
	v_mfma_f32_16x16x32_bf16 v[4:7], v[212:215], v[142:145], v[4:7]
	v_mfma_f32_16x16x32_bf16 v[0:3], v[212:215], v[174:177], v[0:3]
	v_mfma_f32_16x16x32_bf16 v[28:31], v[192:195], v[170:173], v[28:31]
	v_mfma_f32_16x16x32_bf16 v[24:27], v[192:195], v[178:181], v[24:27]
	v_mfma_f32_16x16x32_bf16 v[20:23], v[200:203], v[170:173], v[20:23]
	v_mfma_f32_16x16x32_bf16 v[16:19], v[200:203], v[178:181], v[16:19]
	v_mfma_f32_16x16x32_bf16 v[12:15], v[208:211], v[170:173], v[12:15]
	v_mfma_f32_16x16x32_bf16 v[8:11], v[208:211], v[178:181], v[8:11]
	v_mfma_f32_16x16x32_bf16 v[4:7], v[216:219], v[170:173], v[4:7]
	v_mfma_f32_16x16x32_bf16 v[0:3], v[216:219], v[178:181], v[0:3]
	s_setprio 0
	s_barrier
	v_readfirstlane_b32 s5, v162
	v_lshl_add_u64 v[142:143], v[240:241], 0, s[50:51]
	s_mov_b32 m0, s5
	v_readfirstlane_b32 s5, v164
	global_load_lds_dwordx4 v[142:143], off
	v_lshl_add_u64 v[142:143], v[242:243], 0, s[50:51]
	s_mov_b32 m0, s5
	s_nop 0
	global_load_lds_dwordx4 v[142:143], off
	s_waitcnt vmcnt(6)
	s_barrier
	s_setprio 1
	v_mfma_f32_16x16x32_bf16 v[52:55], v[182:185], v[220:223], v[52:55]
	v_mfma_f32_16x16x32_bf16 v[60:63], v[182:185], v[228:231], v[60:63]
	v_mfma_f32_16x16x32_bf16 v[64:67], v[196:199], v[220:223], v[64:67]
	v_mfma_f32_16x16x32_bf16 v[68:71], v[196:199], v[228:231], v[68:71]
	v_mfma_f32_16x16x32_bf16 v[76:79], v[204:207], v[220:223], v[76:79]
	v_mfma_f32_16x16x32_bf16 v[80:83], v[204:207], v[228:231], v[80:83]
	v_mfma_f32_16x16x32_bf16 v[84:87], v[212:215], v[220:223], v[84:87]
	v_mfma_f32_16x16x32_bf16 v[92:95], v[212:215], v[228:231], v[92:95]
	v_mfma_f32_16x16x32_bf16 v[52:55], v[192:195], v[224:227], v[52:55]
	v_mfma_f32_16x16x32_bf16 v[60:63], v[192:195], v[232:235], v[60:63]
	v_mfma_f32_16x16x32_bf16 v[64:67], v[200:203], v[224:227], v[64:67]
	v_mfma_f32_16x16x32_bf16 v[68:71], v[200:203], v[232:235], v[68:71]
	v_mfma_f32_16x16x32_bf16 v[76:79], v[208:211], v[224:227], v[76:79]
	v_mfma_f32_16x16x32_bf16 v[80:83], v[208:211], v[232:235], v[80:83]
	v_mfma_f32_16x16x32_bf16 v[84:87], v[216:219], v[224:227], v[84:87]
	v_mfma_f32_16x16x32_bf16 v[92:95], v[216:219], v[232:235], v[92:95]
	s_setprio 0
	s_add_i32 s4, s4, 2
	s_add_u32 s76, s76, 0x100
	s_addc_u32 s77, s77, 0
	s_cmp_gt_u32 s4, 27
	s_barrier
	s_cbranch_scc0 .LBB0_52
	s_mov_b64 s[60:61], 0xf80
	v_readfirstlane_b32 s4, v167
	v_lshl_add_u64 v[130:131], v[130:131], 0, s[60:61]
	s_mov_b32 m0, s4
	v_readfirstlane_b32 s4, v168
	ds_read_b128 v[134:137], v166
	ds_read_b128 v[138:141], v166 offset:1024
	ds_read_b128 v[156:159], v166 offset:2048
	ds_read_b128 v[170:173], v166 offset:3072
	ds_read_b128 v[174:177], v150
	ds_read_b128 v[178:181], v150 offset:1024
	ds_read_b128 v[182:185], v149
	ds_read_b128 v[192:195], v149 offset:1024
	ds_read_b128 v[196:199], v148
	ds_read_b128 v[200:203], v148 offset:1024
	ds_read_b128 v[204:207], v147
	ds_read_b128 v[208:211], v147 offset:1024
	global_load_lds_dwordx4 v[130:131], off
	v_lshl_add_u64 v[130:131], v[132:133], 0, s[60:61]
	s_mov_b32 m0, s4
	s_nop 0
	global_load_lds_dwordx4 v[130:131], off
	s_barrier
	s_waitcnt lgkmcnt(0)
	s_setprio 1
	v_mfma_f32_16x16x32_bf16 v[126:129], v[174:177], v[134:137], v[126:129]
	v_mfma_f32_16x16x32_bf16 v[122:125], v[174:177], v[156:159], v[122:125]
	v_mfma_f32_16x16x32_bf16 v[118:121], v[182:185], v[134:137], v[118:121]
	v_mfma_f32_16x16x32_bf16 v[114:117], v[182:185], v[156:159], v[114:117]
	v_mfma_f32_16x16x32_bf16 v[108:111], v[196:199], v[134:137], v[108:111]
	v_mfma_f32_16x16x32_bf16 v[104:107], v[196:199], v[156:159], v[104:107]
	v_mfma_f32_16x16x32_bf16 v[100:103], v[204:207], v[134:137], v[100:103]
	v_mfma_f32_16x16x32_bf16 v[96:99], v[204:207], v[156:159], v[96:99]
	v_mfma_f32_16x16x32_bf16 v[126:129], v[178:181], v[138:141], v[126:129]
	v_mfma_f32_16x16x32_bf16 v[122:125], v[178:181], v[170:173], v[122:125]
	v_mfma_f32_16x16x32_bf16 v[118:121], v[192:195], v[138:141], v[118:121]
	v_mfma_f32_16x16x32_bf16 v[114:117], v[192:195], v[170:173], v[114:117]
	v_mfma_f32_16x16x32_bf16 v[108:111], v[200:203], v[138:141], v[108:111]
	v_mfma_f32_16x16x32_bf16 v[104:107], v[200:203], v[170:173], v[104:107]
	v_mfma_f32_16x16x32_bf16 v[100:103], v[208:211], v[138:141], v[100:103]
	v_mfma_f32_16x16x32_bf16 v[96:99], v[208:211], v[170:173], v[96:99]
	s_setprio 0
	s_barrier
	ds_read_b128 v[130:133], v165
	ds_read_b128 v[166:169], v165 offset:1024
	ds_read_b128 v[212:215], v165 offset:2048
	ds_read_b128 v[216:219], v165 offset:3072
	s_barrier
	s_waitcnt lgkmcnt(0)
	s_setprio 1
	v_mfma_f32_16x16x32_bf16 v[88:91], v[174:177], v[130:133], v[88:91]
	v_mfma_f32_16x16x32_bf16 v[72:75], v[174:177], v[212:215], v[72:75]
	v_mfma_f32_16x16x32_bf16 v[56:59], v[182:185], v[130:133], v[56:59]
	v_mfma_f32_16x16x32_bf16 v[48:51], v[182:185], v[212:215], v[48:51]
	v_mfma_f32_16x16x32_bf16 v[88:91], v[178:181], v[166:169], v[88:91]
	v_mfma_f32_16x16x32_bf16 v[72:75], v[178:181], v[216:219], v[72:75]
	v_mfma_f32_16x16x32_bf16 v[56:59], v[192:195], v[166:169], v[56:59]
	v_mfma_f32_16x16x32_bf16 v[48:51], v[192:195], v[216:219], v[48:51]
	v_mfma_f32_16x16x32_bf16 v[44:47], v[196:199], v[130:133], v[44:47]
	v_mfma_f32_16x16x32_bf16 v[40:43], v[196:199], v[212:215], v[40:43]
	v_mfma_f32_16x16x32_bf16 v[36:39], v[204:207], v[130:133], v[36:39]
	v_mfma_f32_16x16x32_bf16 v[32:35], v[204:207], v[212:215], v[32:35]
	v_mfma_f32_16x16x32_bf16 v[174:177], v[200:203], v[166:169], v[44:47]
	v_mfma_f32_16x16x32_bf16 v[178:181], v[200:203], v[216:219], v[40:43]
	v_mfma_f32_16x16x32_bf16 v[182:185], v[208:211], v[166:169], v[36:39]
	v_mfma_f32_16x16x32_bf16 v[192:195], v[208:211], v[216:219], v[32:35]
	s_setprio 0
	s_barrier
	s_nop 1
	ds_read_b128 v[32:35], v150 offset:16384
	ds_read_b128 v[36:39], v150 offset:17408
	ds_read_b128 v[40:43], v149 offset:16384
	ds_read_b128 v[44:47], v149 offset:17408
	ds_read_b128 v[196:199], v148 offset:16384
	ds_read_b128 v[200:203], v148 offset:17408
	ds_read_b128 v[204:207], v147 offset:16384
	ds_read_b128 v[208:211], v147 offset:17408
	s_waitcnt vmcnt(4)
	s_barrier
	s_waitcnt lgkmcnt(0)
	s_setprio 1
	v_mfma_f32_16x16x32_bf16 v[28:31], v[32:35], v[134:137], v[28:31]
	v_mfma_f32_16x16x32_bf16 v[24:27], v[32:35], v[156:159], v[24:27]
	v_mfma_f32_16x16x32_bf16 v[20:23], v[40:43], v[134:137], v[20:23]
	v_mfma_f32_16x16x32_bf16 v[16:19], v[40:43], v[156:159], v[16:19]
	v_mfma_f32_16x16x32_bf16 v[12:15], v[196:199], v[134:137], v[12:15]
	v_mfma_f32_16x16x32_bf16 v[8:11], v[196:199], v[156:159], v[8:11]
	v_mfma_f32_16x16x32_bf16 v[4:7], v[204:207], v[134:137], v[4:7]
	v_mfma_f32_16x16x32_bf16 v[0:3], v[204:207], v[156:159], v[0:3]
	v_mfma_f32_16x16x32_bf16 v[220:223], v[36:39], v[138:141], v[28:31]
	v_mfma_f32_16x16x32_bf16 v[224:227], v[36:39], v[170:173], v[24:27]
	v_mfma_f32_16x16x32_bf16 v[228:231], v[44:47], v[138:141], v[20:23]
	v_mfma_f32_16x16x32_bf16 v[232:235], v[44:47], v[170:173], v[16:19]
	v_mfma_f32_16x16x32_bf16 v[236:239], v[200:203], v[138:141], v[12:15]
	v_mfma_f32_16x16x32_bf16 v[240:243], v[200:203], v[170:173], v[8:11]
	v_mfma_f32_16x16x32_bf16 v[134:137], v[208:211], v[138:141], v[4:7]
	v_mfma_f32_16x16x32_bf16 v[138:141], v[208:211], v[170:173], v[0:3]
	s_setprio 0
	s_setprio 1
	v_mfma_f32_16x16x32_bf16 v[0:3], v[32:35], v[130:133], v[52:55]
	v_mfma_f32_16x16x32_bf16 v[156:159], v[36:39], v[166:169], v[0:3]
	v_mfma_f32_16x16x32_bf16 v[0:3], v[32:35], v[212:215], v[60:63]
	v_mfma_f32_16x16x32_bf16 v[170:173], v[36:39], v[216:219], v[0:3]
	v_mfma_f32_16x16x32_bf16 v[0:3], v[40:43], v[130:133], v[64:67]
	v_mfma_f32_16x16x32_bf16 v[244:247], v[44:47], v[166:169], v[0:3]
	v_mfma_f32_16x16x32_bf16 v[0:3], v[40:43], v[212:215], v[68:71]
	v_mfma_f32_16x16x32_bf16 v[248:251], v[44:47], v[216:219], v[0:3]
	v_mfma_f32_16x16x32_bf16 v[0:3], v[196:199], v[130:133], v[76:79]
	v_mfma_f32_16x16x32_bf16 v[142:145], v[200:203], v[166:169], v[0:3]
	v_mfma_f32_16x16x32_bf16 v[0:3], v[196:199], v[212:215], v[80:83]
	v_mfma_f32_16x16x32_bf16 v[196:199], v[200:203], v[216:219], v[0:3]
	v_mfma_f32_16x16x32_bf16 v[0:3], v[204:207], v[130:133], v[84:87]
	v_mfma_f32_16x16x32_bf16 v[130:133], v[208:211], v[166:169], v[0:3]
	v_mfma_f32_16x16x32_bf16 v[0:3], v[204:207], v[212:215], v[92:95]
	v_mfma_f32_16x16x32_bf16 v[164:167], v[208:211], v[216:219], v[0:3]
	s_setprio 0
	s_barrier
	ds_read_b128 v[92:95], v155
	ds_read_b128 v[200:203], v155 offset:1024
	ds_read_b128 v[204:207], v155 offset:2048
	ds_read_b128 v[152:155], v155 offset:3072
	ds_read_b128 v[36:39], v150 offset:32768
	ds_read_b128 v[40:43], v150 offset:33792
	ds_read_b128 v[44:47], v149 offset:32768
	ds_read_b128 v[52:55], v149 offset:33792
	ds_read_b128 v[60:63], v148 offset:32768
	ds_read_b128 v[64:67], v148 offset:33792
	ds_read_b128 v[68:71], v147 offset:32768
	ds_read_b128 v[76:79], v147 offset:33792
	s_waitcnt vmcnt(2)
	s_barrier
	s_waitcnt lgkmcnt(0)
	s_setprio 1
	v_mfma_f32_16x16x32_bf16 v[0:3], v[36:39], v[92:95], v[126:129]
	v_mfma_f32_16x16x32_bf16 v[4:7], v[36:39], v[204:207], v[122:125]
	v_mfma_f32_16x16x32_bf16 v[8:11], v[44:47], v[92:95], v[118:121]
	v_mfma_f32_16x16x32_bf16 v[12:15], v[44:47], v[204:207], v[114:117]
	v_mfma_f32_16x16x32_bf16 v[16:19], v[60:63], v[92:95], v[108:111]
	v_mfma_f32_16x16x32_bf16 v[20:23], v[60:63], v[204:207], v[104:107]
	v_mfma_f32_16x16x32_bf16 v[24:27], v[68:71], v[92:95], v[100:103]
	v_mfma_f32_16x16x32_bf16 v[28:31], v[68:71], v[204:207], v[96:99]
	v_mfma_f32_16x16x32_bf16 v[0:3], v[40:43], v[200:203], v[0:3]
	v_mfma_f32_16x16x32_bf16 v[4:7], v[40:43], v[152:155], v[4:7]
	v_mfma_f32_16x16x32_bf16 v[8:11], v[52:55], v[200:203], v[8:11]
	v_mfma_f32_16x16x32_bf16 v[12:15], v[52:55], v[152:155], v[12:15]
	v_mfma_f32_16x16x32_bf16 v[16:19], v[64:67], v[200:203], v[16:19]
	v_mfma_f32_16x16x32_bf16 v[20:23], v[64:67], v[152:155], v[20:23]
	v_mfma_f32_16x16x32_bf16 v[24:27], v[76:79], v[200:203], v[24:27]
	v_mfma_f32_16x16x32_bf16 v[28:31], v[76:79], v[152:155], v[28:31]
	s_setprio 0
	s_barrier
	ds_read_b128 v[122:125], v151
	ds_read_b128 v[126:129], v151 offset:1024
	ds_read_b128 v[208:211], v151 offset:2048
	ds_read_b128 v[212:215], v151 offset:3072
	s_waitcnt vmcnt(0)
	s_barrier
	s_waitcnt lgkmcnt(0)
	s_setprio 1
	v_mfma_f32_16x16x32_bf16 v[32:35], v[36:39], v[122:125], v[88:91]
	v_mfma_f32_16x16x32_bf16 v[36:39], v[36:39], v[208:211], v[72:75]
	v_mfma_f32_16x16x32_bf16 v[32:35], v[40:43], v[126:129], v[32:35]
	v_mfma_f32_16x16x32_bf16 v[36:39], v[40:43], v[212:215], v[36:39]
	v_mfma_f32_16x16x32_bf16 v[40:43], v[44:47], v[122:125], v[56:59]
	v_mfma_f32_16x16x32_bf16 v[44:47], v[44:47], v[208:211], v[48:51]
	v_mfma_f32_16x16x32_bf16 v[40:43], v[52:55], v[126:129], v[40:43]
	v_mfma_f32_16x16x32_bf16 v[44:47], v[52:55], v[212:215], v[44:47]
	v_mfma_f32_16x16x32_bf16 v[48:51], v[60:63], v[122:125], v[174:177]
	v_mfma_f32_16x16x32_bf16 v[52:55], v[60:63], v[208:211], v[178:181]
	v_mfma_f32_16x16x32_bf16 v[56:59], v[68:71], v[122:125], v[182:185]
	v_mfma_f32_16x16x32_bf16 v[60:63], v[68:71], v[208:211], v[192:195]
	v_mfma_f32_16x16x32_bf16 v[48:51], v[64:67], v[126:129], v[48:51]
	v_mfma_f32_16x16x32_bf16 v[52:55], v[64:67], v[212:215], v[52:55]
	v_mfma_f32_16x16x32_bf16 v[56:59], v[76:79], v[126:129], v[56:59]
	v_mfma_f32_16x16x32_bf16 v[60:63], v[76:79], v[212:215], v[60:63]
	s_setprio 0
	s_barrier
	ds_read_b128 v[100:103], v150 offset:49152
	ds_read_b128 v[104:107], v150 offset:50176
	ds_read_b128 v[108:111], v149 offset:49152
	ds_read_b128 v[114:117], v149 offset:50176
	ds_read_b128 v[118:121], v148 offset:49152
	ds_read_b128 v[148:151], v148 offset:50176
	ds_read_b128 v[174:177], v147 offset:49152
	ds_read_b128 v[178:181], v147 offset:50176
	s_barrier
	s_waitcnt lgkmcnt(0)
	s_setprio 1
	v_mfma_f32_16x16x32_bf16 v[64:67], v[100:103], v[92:95], v[220:223]
	v_mfma_f32_16x16x32_bf16 v[68:71], v[100:103], v[204:207], v[224:227]
	v_mfma_f32_16x16x32_bf16 v[72:75], v[108:111], v[92:95], v[228:231]
	v_mfma_f32_16x16x32_bf16 v[76:79], v[108:111], v[204:207], v[232:235]
	v_mfma_f32_16x16x32_bf16 v[80:83], v[118:121], v[92:95], v[236:239]
	v_mfma_f32_16x16x32_bf16 v[84:87], v[118:121], v[204:207], v[240:243]
	v_mfma_f32_16x16x32_bf16 v[88:91], v[174:177], v[92:95], v[134:137]
	v_mfma_f32_16x16x32_bf16 v[92:95], v[174:177], v[204:207], v[138:141]
	v_mfma_f32_16x16x32_bf16 v[64:67], v[104:107], v[200:203], v[64:67]
	v_mfma_f32_16x16x32_bf16 v[68:71], v[104:107], v[152:155], v[68:71]
	v_mfma_f32_16x16x32_bf16 v[72:75], v[114:117], v[200:203], v[72:75]
	v_mfma_f32_16x16x32_bf16 v[76:79], v[114:117], v[152:155], v[76:79]
	v_mfma_f32_16x16x32_bf16 v[80:83], v[148:151], v[200:203], v[80:83]
	v_mfma_f32_16x16x32_bf16 v[84:87], v[148:151], v[152:155], v[84:87]
	v_mfma_f32_16x16x32_bf16 v[88:91], v[178:181], v[200:203], v[88:91]
	v_mfma_f32_16x16x32_bf16 v[92:95], v[178:181], v[152:155], v[92:95]
	s_setprio 0
	s_setprio 1
	v_mfma_f32_16x16x32_bf16 v[96:99], v[100:103], v[122:125], v[156:159]
	v_mfma_f32_16x16x32_bf16 v[100:103], v[100:103], v[208:211], v[170:173]
	v_mfma_f32_16x16x32_bf16 v[96:99], v[104:107], v[126:129], v[96:99]
	v_mfma_f32_16x16x32_bf16 v[100:103], v[104:107], v[212:215], v[100:103]
	v_mfma_f32_16x16x32_bf16 v[104:107], v[108:111], v[122:125], v[244:247]
	v_mfma_f32_16x16x32_bf16 v[108:111], v[108:111], v[208:211], v[248:251]
	v_mfma_f32_16x16x32_bf16 v[104:107], v[114:117], v[126:129], v[104:107]
	v_mfma_f32_16x16x32_bf16 v[108:111], v[114:117], v[212:215], v[108:111]
	v_mfma_f32_16x16x32_bf16 v[114:117], v[118:121], v[122:125], v[142:145]
	v_mfma_f32_16x16x32_bf16 v[122:125], v[174:177], v[122:125], v[130:133]
	v_mfma_f32_16x16x32_bf16 v[114:117], v[148:151], v[126:129], v[114:117]
	v_mfma_f32_16x16x32_bf16 v[118:121], v[118:121], v[208:211], v[196:199]
	v_mfma_f32_16x16x32_bf16 v[122:125], v[178:181], v[126:129], v[122:125]
	v_mfma_f32_16x16x32_bf16 v[126:129], v[174:177], v[208:211], v[164:167]
	v_mfma_f32_16x16x32_bf16 v[118:121], v[148:151], v[212:215], v[118:121]
	v_mfma_f32_16x16x32_bf16 v[126:129], v[178:181], v[212:215], v[126:129]
	s_setprio 0
	s_movk_i32 s4, 0x100
	v_cmp_gt_u32_e32 vcc, s4, v113
	s_barrier
	s_and_saveexec_b64 s[4:5], vcc
	s_cbranch_execz .LBB0_55
	s_barrier

.LBB0_88:
	ds_read_b128 v[8:11], v204
	ds_read_b128 v[12:15], v204 offset:1024
	ds_read_b128 v[0:3], v204 offset:2048
	ds_read_b128 v[4:7], v204 offset:3072
	v_add_u32_e32 v205, 0xc000, v192
	v_lshl_add_u64 v[168:169], v[164:165], 0, s[70:71]
	v_readfirstlane_b32 s5, v205
	v_add_u32_e32 v206, 0xe000, v192
	v_lshl_add_u64 v[16:17], v[168:169], 0, s[54:55]
	s_mov_b32 m0, s5
	v_lshl_add_u64 v[170:171], v[166:167], 0, s[70:71]
	v_readfirstlane_b32 s5, v206
	ds_read_b128 v[208:211], v182
	ds_read_b128 v[212:215], v182 offset:1024
	ds_read_b128 v[216:219], v181
	ds_read_b128 v[220:223], v181 offset:1024
	ds_read_b128 v[224:227], v180
	ds_read_b128 v[228:231], v180 offset:1024
	ds_read_b128 v[232:235], v179
	ds_read_b128 v[236:239], v179 offset:1024
	global_load_lds_dwordx4 v[16:17], off
	v_lshl_add_u64 v[16:17], v[170:171], 0, s[54:55]
	s_mov_b32 m0, s5
	s_nop 0
	global_load_lds_dwordx4 v[16:17], off
	s_waitcnt lgkmcnt(8)
	s_barrier
	s_waitcnt lgkmcnt(0)
	s_setprio 1
	v_mfma_f32_16x16x128_f8f6f4 v[118:121], v[208:215], v[8:15], v[118:121]
	v_mfma_f32_16x16x128_f8f6f4 v[114:117], v[208:215], v[0:7], v[114:117]
	v_mfma_f32_16x16x128_f8f6f4 v[108:111], v[216:223], v[8:15], v[108:111]
	v_mfma_f32_16x16x128_f8f6f4 v[104:107], v[216:223], v[0:7], v[104:107]
	v_mfma_f32_16x16x128_f8f6f4 v[100:103], v[224:231], v[8:15], v[100:103]
	v_mfma_f32_16x16x128_f8f6f4 v[96:99], v[224:231], v[0:7], v[96:99]
	v_mfma_f32_16x16x128_f8f6f4 v[92:95], v[232:239], v[8:15], v[92:95]
	v_mfma_f32_16x16x128_f8f6f4 v[88:91], v[232:239], v[0:7], v[88:91]
	s_setprio 0
	s_barrier
	v_lshl_add_u64 v[172:173], v[158:159], 0, s[70:71]
	v_readfirstlane_b32 s5, v185
	v_lshl_add_u64 v[174:175], v[172:173], 0, s[44:45]
	s_mov_b32 m0, s5
	v_add_u32_e32 v187, 0x2000, v185
	ds_read_b128 v[240:243], v195
	ds_read_b128 v[244:247], v195 offset:1024
	ds_read_b128 v[16:19], v195 offset:2048
	ds_read_b128 v[20:23], v195 offset:3072
	global_load_lds_dwordx4 v[174:175], off
	v_lshl_add_u64 v[174:175], v[160:161], 0, s[70:71]
	v_readfirstlane_b32 s5, v187
	v_lshl_add_u64 v[248:249], v[174:175], 0, s[44:45]
	s_mov_b32 m0, s5
	s_nop 0
	global_load_lds_dwordx4 v[248:249], off
	s_barrier
	s_waitcnt lgkmcnt(0)
	s_setprio 1
	v_mfma_f32_16x16x128_f8f6f4 v[84:87], v[208:215], v[240:247], v[84:87]
	v_mfma_f32_16x16x128_f8f6f4 v[80:83], v[208:215], v[16:23], v[80:83]
	v_mfma_f32_16x16x128_f8f6f4 v[76:79], v[216:223], v[240:247], v[76:79]
	v_mfma_f32_16x16x128_f8f6f4 v[72:75], v[216:223], v[16:23], v[72:75]
	v_mfma_f32_16x16x128_f8f6f4 v[68:71], v[224:231], v[240:247], v[68:71]
	v_mfma_f32_16x16x128_f8f6f4 v[64:67], v[224:231], v[16:23], v[64:67]
	v_mfma_f32_16x16x128_f8f6f4 v[60:63], v[232:239], v[240:247], v[60:63]
	v_mfma_f32_16x16x128_f8f6f4 v[56:59], v[232:239], v[16:23], v[56:59]
	s_setprio 0
	v_readfirstlane_b32 s5, v192
	v_lshl_add_u64 v[248:249], v[168:169], 0, s[44:45]
	s_mov_b32 m0, s5
	v_readfirstlane_b32 s5, v193
	s_barrier
	ds_read_b128 v[208:211], v182 offset:16384
	ds_read_b128 v[212:215], v182 offset:17408
	ds_read_b128 v[216:219], v181 offset:16384
	ds_read_b128 v[220:223], v181 offset:17408
	ds_read_b128 v[224:227], v180 offset:16384
	ds_read_b128 v[228:231], v180 offset:17408
	ds_read_b128 v[232:235], v179 offset:16384
	ds_read_b128 v[236:239], v179 offset:17408
	global_load_lds_dwordx4 v[248:249], off
	v_lshl_add_u64 v[248:249], v[170:171], 0, s[44:45]
	s_mov_b32 m0, s5
	s_nop 0
	global_load_lds_dwordx4 v[248:249], off
	s_barrier
	s_waitcnt lgkmcnt(0)
	s_setprio 1
	v_mfma_f32_16x16x128_f8f6f4 v[52:55], v[208:215], v[8:15], v[52:55]
	v_mfma_f32_16x16x128_f8f6f4 v[48:51], v[208:215], v[0:7], v[48:51]
	v_mfma_f32_16x16x128_f8f6f4 v[44:47], v[216:223], v[8:15], v[44:47]
	v_mfma_f32_16x16x128_f8f6f4 v[40:43], v[216:223], v[0:7], v[40:43]
	v_mfma_f32_16x16x128_f8f6f4 v[36:39], v[224:231], v[8:15], v[36:39]
	v_mfma_f32_16x16x128_f8f6f4 v[32:35], v[224:231], v[0:7], v[32:35]
	v_mfma_f32_16x16x128_f8f6f4 v[28:31], v[232:239], v[8:15], v[28:31]
	v_mfma_f32_16x16x128_f8f6f4 v[24:27], v[232:239], v[0:7], v[24:27]
	s_setprio 0
	s_barrier
	v_readfirstlane_b32 s5, v194
	v_add_u32_e32 v2, 0x2000, v194
	v_lshl_add_u64 v[0:1], v[172:173], 0, s[56:57]
	s_mov_b32 m0, s5
	v_readfirstlane_b32 s5, v2
	global_load_lds_dwordx4 v[0:1], off
	v_lshl_add_u64 v[0:1], v[174:175], 0, s[56:57]
	s_mov_b32 m0, s5
	s_nop 0
	global_load_lds_dwordx4 v[0:1], off
	s_waitcnt vmcnt(6)
	s_barrier
	s_setprio 1
	v_mfma_f32_16x16x128_f8f6f4 v[122:125], v[208:215], v[240:247], v[122:125]
	v_mfma_f32_16x16x128_f8f6f4 v[126:129], v[208:215], v[16:23], v[126:129]
	v_mfma_f32_16x16x128_f8f6f4 v[130:133], v[216:223], v[240:247], v[130:133]
	v_mfma_f32_16x16x128_f8f6f4 v[134:137], v[216:223], v[16:23], v[134:137]
	v_mfma_f32_16x16x128_f8f6f4 v[138:141], v[224:231], v[240:247], v[138:141]
	v_mfma_f32_16x16x128_f8f6f4 v[142:145], v[224:231], v[16:23], v[142:145]
	v_mfma_f32_16x16x128_f8f6f4 v[146:149], v[232:239], v[240:247], v[146:149]
	v_mfma_f32_16x16x128_f8f6f4 v[150:153], v[232:239], v[16:23], v[150:153]
	s_setprio 0
	s_barrier
	ds_read_b128 v[0:3], v184
	ds_read_b128 v[4:7], v184 offset:1024
	ds_read_b128 v[8:11], v184 offset:2048
	ds_read_b128 v[12:15], v184 offset:3072
	v_readfirstlane_b32 s5, v196
	v_lshl_add_u64 v[232:233], v[168:169], 0, s[56:57]
	s_mov_b32 m0, s5
	v_readfirstlane_b32 s5, v197
	ds_read_b128 v[16:19], v182 offset:32768
	ds_read_b128 v[20:23], v182 offset:33792
	ds_read_b128 v[208:211], v181 offset:32768
	ds_read_b128 v[212:215], v181 offset:33792
	ds_read_b128 v[216:219], v180 offset:32768
	ds_read_b128 v[220:223], v180 offset:33792
	ds_read_b128 v[224:227], v179 offset:32768
	ds_read_b128 v[228:231], v179 offset:33792
	global_load_lds_dwordx4 v[232:233], off
	v_lshl_add_u64 v[232:233], v[170:171], 0, s[56:57]
	s_mov_b32 m0, s5
	s_nop 0
	global_load_lds_dwordx4 v[232:233], off
	s_waitcnt lgkmcnt(8)
	s_barrier
	s_waitcnt lgkmcnt(0)
	s_setprio 1
	v_mfma_f32_16x16x128_f8f6f4 v[118:121], v[16:23], v[0:7], v[118:121]
	v_mfma_f32_16x16x128_f8f6f4 v[114:117], v[16:23], v[8:15], v[114:117]
	v_mfma_f32_16x16x128_f8f6f4 v[108:111], v[208:215], v[0:7], v[108:111]
	v_mfma_f32_16x16x128_f8f6f4 v[104:107], v[208:215], v[8:15], v[104:107]
	v_mfma_f32_16x16x128_f8f6f4 v[100:103], v[216:223], v[0:7], v[100:103]
	v_mfma_f32_16x16x128_f8f6f4 v[96:99], v[216:223], v[8:15], v[96:99]
	v_mfma_f32_16x16x128_f8f6f4 v[92:95], v[224:231], v[0:7], v[92:95]
	v_mfma_f32_16x16x128_f8f6f4 v[88:91], v[224:231], v[8:15], v[88:91]
	s_setprio 0
	s_barrier
	v_readfirstlane_b32 s5, v198
	v_lshl_add_u64 v[248:249], v[172:173], 0, s[48:49]
	s_mov_b32 m0, s5
	v_readfirstlane_b32 s5, v199
	ds_read_b128 v[232:235], v183
	ds_read_b128 v[236:239], v183 offset:1024
	ds_read_b128 v[240:243], v183 offset:2048
	ds_read_b128 v[244:247], v183 offset:3072
	global_load_lds_dwordx4 v[248:249], off
	v_lshl_add_u64 v[248:249], v[174:175], 0, s[48:49]
	s_mov_b32 m0, s5
	s_nop 0
	global_load_lds_dwordx4 v[248:249], off
	s_barrier
	s_waitcnt lgkmcnt(0)
	s_setprio 1
	v_mfma_f32_16x16x128_f8f6f4 v[84:87], v[16:23], v[232:239], v[84:87]
	v_mfma_f32_16x16x128_f8f6f4 v[80:83], v[16:23], v[240:247], v[80:83]
	v_mfma_f32_16x16x128_f8f6f4 v[76:79], v[208:215], v[232:239], v[76:79]
	v_mfma_f32_16x16x128_f8f6f4 v[72:75], v[208:215], v[240:247], v[72:75]
	v_mfma_f32_16x16x128_f8f6f4 v[68:71], v[216:223], v[232:239], v[68:71]
	v_mfma_f32_16x16x128_f8f6f4 v[64:67], v[216:223], v[240:247], v[64:67]
	v_mfma_f32_16x16x128_f8f6f4 v[60:63], v[224:231], v[232:239], v[60:63]
	v_mfma_f32_16x16x128_f8f6f4 v[56:59], v[224:231], v[240:247], v[56:59]
	s_setprio 0
	v_readfirstlane_b32 s5, v200
	v_lshl_add_u64 v[168:169], v[168:169], 0, s[48:49]
	s_mov_b32 m0, s5
	v_readfirstlane_b32 s5, v201
	s_barrier
	ds_read_b128 v[16:19], v182 offset:49152
	ds_read_b128 v[20:23], v182 offset:50176
	ds_read_b128 v[208:211], v181 offset:49152
	ds_read_b128 v[212:215], v181 offset:50176
	ds_read_b128 v[216:219], v180 offset:49152
	ds_read_b128 v[220:223], v180 offset:50176
	ds_read_b128 v[224:227], v179 offset:49152
	ds_read_b128 v[228:231], v179 offset:50176
	global_load_lds_dwordx4 v[168:169], off
	v_lshl_add_u64 v[168:169], v[170:171], 0, s[48:49]
	s_mov_b32 m0, s5
	s_nop 0
	global_load_lds_dwordx4 v[168:169], off
	s_barrier
	s_waitcnt lgkmcnt(0)
	s_setprio 1
	v_mfma_f32_16x16x128_f8f6f4 v[52:55], v[16:23], v[0:7], v[52:55]
	v_mfma_f32_16x16x128_f8f6f4 v[48:51], v[16:23], v[8:15], v[48:51]
	v_mfma_f32_16x16x128_f8f6f4 v[44:47], v[208:215], v[0:7], v[44:47]
	v_mfma_f32_16x16x128_f8f6f4 v[40:43], v[208:215], v[8:15], v[40:43]
	v_mfma_f32_16x16x128_f8f6f4 v[36:39], v[216:223], v[0:7], v[36:39]
	v_mfma_f32_16x16x128_f8f6f4 v[32:35], v[216:223], v[8:15], v[32:35]
	v_mfma_f32_16x16x128_f8f6f4 v[28:31], v[224:231], v[0:7], v[28:31]
	v_mfma_f32_16x16x128_f8f6f4 v[24:27], v[224:231], v[8:15], v[24:27]
	s_setprio 0
	s_barrier
	v_readfirstlane_b32 s5, v202
	v_lshl_add_u64 v[0:1], v[172:173], 0, s[58:59]
	s_mov_b32 m0, s5
	v_readfirstlane_b32 s5, v203
	global_load_lds_dwordx4 v[0:1], off
	v_lshl_add_u64 v[0:1], v[174:175], 0, s[58:59]
	s_mov_b32 m0, s5
	s_nop 0
	global_load_lds_dwordx4 v[0:1], off
	s_waitcnt vmcnt(6)
	s_barrier
	s_setprio 1
	v_mfma_f32_16x16x128_f8f6f4 v[122:125], v[16:23], v[232:239], v[122:125]
	v_mfma_f32_16x16x128_f8f6f4 v[126:129], v[16:23], v[240:247], v[126:129]
	v_mfma_f32_16x16x128_f8f6f4 v[130:133], v[208:215], v[232:239], v[130:133]
	v_mfma_f32_16x16x128_f8f6f4 v[134:137], v[208:215], v[240:247], v[134:137]
	v_mfma_f32_16x16x128_f8f6f4 v[138:141], v[216:223], v[232:239], v[138:141]
	v_mfma_f32_16x16x128_f8f6f4 v[142:145], v[216:223], v[240:247], v[142:145]
	v_mfma_f32_16x16x128_f8f6f4 v[146:149], v[224:231], v[232:239], v[146:149]
	v_mfma_f32_16x16x128_f8f6f4 v[150:153], v[224:231], v[240:247], v[150:153]
	s_setprio 0
	s_add_i32 s4, s4, 2
	s_add_u32 s70, s70, 0x100
	s_addc_u32 s71, s71, 0
	s_cmp_gt_u32 s4, 11
	s_barrier
	s_cbranch_scc0 .LBB0_88
	s_mov_b64 s[60:61], 0x780
	v_readfirstlane_b32 s4, v205
	v_lshl_add_u64 v[154:155], v[154:155], 0, s[60:61]
	s_mov_b32 m0, s4
	v_readfirstlane_b32 s4, v206
	ds_read_b128 v[0:3], v204
	ds_read_b128 v[4:7], v204 offset:1024
	ds_read_b128 v[8:11], v204 offset:2048
	ds_read_b128 v[12:15], v204 offset:3072
	ds_read_b128 v[16:19], v182
	ds_read_b128 v[20:23], v182 offset:1024
	ds_read_b128 v[164:167], v181
	ds_read_b128 v[168:171], v181 offset:1024
	ds_read_b128 v[196:199], v180
	ds_read_b128 v[200:203], v180 offset:1024
	ds_read_b128 v[208:211], v179
	ds_read_b128 v[212:215], v179 offset:1024
	global_load_lds_dwordx4 v[154:155], off
	v_lshl_add_u64 v[154:155], v[156:157], 0, s[60:61]
	s_mov_b32 m0, s4
	s_nop 0
	global_load_lds_dwordx4 v[154:155], off
	s_barrier
	s_waitcnt lgkmcnt(0)
	s_setprio 1
	v_mfma_f32_16x16x128_f8f6f4 v[118:121], v[16:23], v[0:7], v[118:121]
	v_mfma_f32_16x16x128_f8f6f4 v[114:117], v[16:23], v[8:15], v[114:117]
	v_mfma_f32_16x16x128_f8f6f4 v[108:111], v[164:171], v[0:7], v[108:111]
	v_mfma_f32_16x16x128_f8f6f4 v[104:107], v[164:171], v[8:15], v[104:107]
	v_mfma_f32_16x16x128_f8f6f4 v[100:103], v[196:203], v[0:7], v[100:103]
	v_mfma_f32_16x16x128_f8f6f4 v[96:99], v[196:203], v[8:15], v[96:99]
	v_mfma_f32_16x16x128_f8f6f4 v[92:95], v[208:215], v[0:7], v[92:95]
	v_mfma_f32_16x16x128_f8f6f4 v[88:91], v[208:215], v[8:15], v[88:91]
	s_setprio 0
	s_barrier
	ds_read_b128 v[154:157], v195
	ds_read_b128 v[158:161], v195 offset:1024
	ds_read_b128 v[216:219], v195 offset:2048
	ds_read_b128 v[220:223], v195 offset:3072
	s_barrier
	s_waitcnt lgkmcnt(0)
	s_setprio 1
	v_mfma_f32_16x16x128_f8f6f4 v[84:87], v[16:23], v[154:161], v[84:87]
	v_mfma_f32_16x16x128_f8f6f4 v[80:83], v[16:23], v[216:223], v[80:83]
	v_mfma_f32_16x16x128_f8f6f4 v[76:79], v[164:171], v[154:161], v[76:79]
	v_mfma_f32_16x16x128_f8f6f4 v[72:75], v[164:171], v[216:223], v[72:75]
	v_mfma_f32_16x16x128_f8f6f4 v[68:71], v[196:203], v[154:161], v[68:71]
	v_mfma_f32_16x16x128_f8f6f4 v[64:67], v[196:203], v[216:223], v[64:67]
	v_mfma_f32_16x16x128_f8f6f4 v[60:63], v[208:215], v[154:161], v[60:63]
	v_mfma_f32_16x16x128_f8f6f4 v[56:59], v[208:215], v[216:223], v[56:59]
	s_setprio 0
	s_barrier
	ds_read_b128 v[16:19], v182 offset:16384
	ds_read_b128 v[20:23], v182 offset:17408
	ds_read_b128 v[164:167], v181 offset:16384
	ds_read_b128 v[168:171], v181 offset:17408
	ds_read_b128 v[192:195], v180 offset:16384
	ds_read_b128 v[196:199], v180 offset:17408
	ds_read_b128 v[200:203], v179 offset:16384
	ds_read_b128 v[204:207], v179 offset:17408
	s_waitcnt vmcnt(4)
	s_barrier
	s_waitcnt lgkmcnt(0)
	s_setprio 1
	v_mfma_f32_16x16x128_f8f6f4 v[52:55], v[16:23], v[0:7], v[52:55]
	v_mfma_f32_16x16x128_f8f6f4 v[48:51], v[16:23], v[8:15], v[48:51]
	v_mfma_f32_16x16x128_f8f6f4 v[44:47], v[164:171], v[0:7], v[44:47]
	v_mfma_f32_16x16x128_f8f6f4 v[40:43], v[164:171], v[8:15], v[40:43]
	v_mfma_f32_16x16x128_f8f6f4 v[36:39], v[192:199], v[0:7], v[36:39]
	v_mfma_f32_16x16x128_f8f6f4 v[32:35], v[192:199], v[8:15], v[32:35]
	v_mfma_f32_16x16x128_f8f6f4 v[28:31], v[200:207], v[0:7], v[28:31]
	v_mfma_f32_16x16x128_f8f6f4 v[24:27], v[200:207], v[8:15], v[24:27]
	s_setprio 0
	s_setprio 1
	v_mfma_f32_16x16x128_f8f6f4 v[122:125], v[16:23], v[154:161], v[122:125]
	v_mfma_f32_16x16x128_f8f6f4 v[126:129], v[16:23], v[216:223], v[126:129]
	v_mfma_f32_16x16x128_f8f6f4 v[130:133], v[164:171], v[154:161], v[130:133]
	v_mfma_f32_16x16x128_f8f6f4 v[134:137], v[164:171], v[216:223], v[134:137]
	v_mfma_f32_16x16x128_f8f6f4 v[138:141], v[192:199], v[154:161], v[138:141]
	v_mfma_f32_16x16x128_f8f6f4 v[142:145], v[192:199], v[216:223], v[142:145]
	v_mfma_f32_16x16x128_f8f6f4 v[146:149], v[200:207], v[154:161], v[146:149]
	v_mfma_f32_16x16x128_f8f6f4 v[150:153], v[200:207], v[216:223], v[150:153]
	s_setprio 0
	s_barrier
	ds_read_b128 v[0:3], v184
	ds_read_b128 v[4:7], v184 offset:1024
	ds_read_b128 v[8:11], v184 offset:2048
	ds_read_b128 v[12:15], v184 offset:3072
	ds_read_b128 v[16:19], v182 offset:32768
	ds_read_b128 v[20:23], v182 offset:33792
	ds_read_b128 v[154:157], v181 offset:32768
	ds_read_b128 v[158:161], v181 offset:33792
	ds_read_b128 v[164:167], v180 offset:32768
	ds_read_b128 v[168:171], v180 offset:33792
	ds_read_b128 v[192:195], v179 offset:32768
	ds_read_b128 v[196:199], v179 offset:33792
	s_waitcnt vmcnt(2)
	s_barrier
	s_waitcnt lgkmcnt(0)
	s_setprio 1
	v_mfma_f32_16x16x128_f8f6f4 v[118:121], v[16:23], v[0:7], v[118:121]
	v_mfma_f32_16x16x128_f8f6f4 v[114:117], v[16:23], v[8:15], v[114:117]
	v_mfma_f32_16x16x128_f8f6f4 v[108:111], v[154:161], v[0:7], v[108:111]
	v_mfma_f32_16x16x128_f8f6f4 v[104:107], v[154:161], v[8:15], v[104:107]
	v_mfma_f32_16x16x128_f8f6f4 v[100:103], v[164:171], v[0:7], v[100:103]
	v_mfma_f32_16x16x128_f8f6f4 v[96:99], v[164:171], v[8:15], v[96:99]
	v_mfma_f32_16x16x128_f8f6f4 v[92:95], v[192:199], v[0:7], v[92:95]
	v_mfma_f32_16x16x128_f8f6f4 v[88:91], v[192:199], v[8:15], v[88:91]
	s_setprio 0
	s_barrier
	ds_read_b128 v[200:203], v183
	ds_read_b128 v[204:207], v183 offset:1024
	ds_read_b128 v[208:211], v183 offset:2048
	ds_read_b128 v[212:215], v183 offset:3072
	s_waitcnt vmcnt(0)
	s_barrier
	s_waitcnt lgkmcnt(0)
	s_setprio 1
	v_mfma_f32_16x16x128_f8f6f4 v[84:87], v[16:23], v[200:207], v[84:87]
	v_mfma_f32_16x16x128_f8f6f4 v[80:83], v[16:23], v[208:215], v[80:83]
	v_mfma_f32_16x16x128_f8f6f4 v[76:79], v[154:161], v[200:207], v[76:79]
	v_mfma_f32_16x16x128_f8f6f4 v[72:75], v[154:161], v[208:215], v[72:75]
	v_mfma_f32_16x16x128_f8f6f4 v[68:71], v[164:171], v[200:207], v[68:71]
	v_mfma_f32_16x16x128_f8f6f4 v[64:67], v[164:171], v[208:215], v[64:67]
	v_mfma_f32_16x16x128_f8f6f4 v[60:63], v[192:199], v[200:207], v[60:63]
	v_mfma_f32_16x16x128_f8f6f4 v[56:59], v[192:199], v[208:215], v[56:59]
	s_setprio 0
	s_barrier
	ds_read_b128 v[16:19], v182 offset:49152
	ds_read_b128 v[20:23], v182 offset:50176
	ds_read_b128 v[154:157], v181 offset:49152
	ds_read_b128 v[158:161], v181 offset:50176
	ds_read_b128 v[164:167], v180 offset:49152
	ds_read_b128 v[168:171], v180 offset:50176
	ds_read_b128 v[192:195], v179 offset:49152
	ds_read_b128 v[196:199], v179 offset:50176
	s_barrier
	s_waitcnt lgkmcnt(0)
	s_setprio 1
	v_mfma_f32_16x16x128_f8f6f4 v[52:55], v[16:23], v[0:7], v[52:55]
	v_mfma_f32_16x16x128_f8f6f4 v[48:51], v[16:23], v[8:15], v[48:51]
	v_mfma_f32_16x16x128_f8f6f4 v[44:47], v[154:161], v[0:7], v[44:47]
	v_mfma_f32_16x16x128_f8f6f4 v[40:43], v[154:161], v[8:15], v[40:43]
	v_mfma_f32_16x16x128_f8f6f4 v[36:39], v[164:171], v[0:7], v[36:39]
	v_mfma_f32_16x16x128_f8f6f4 v[32:35], v[164:171], v[8:15], v[32:35]
	v_mfma_f32_16x16x128_f8f6f4 v[28:31], v[192:199], v[0:7], v[28:31]
	v_mfma_f32_16x16x128_f8f6f4 v[24:27], v[192:199], v[8:15], v[24:27]
	s_setprio 0
	s_setprio 1
	v_mfma_f32_16x16x128_f8f6f4 v[122:125], v[16:23], v[200:207], v[122:125]
	v_mfma_f32_16x16x128_f8f6f4 v[126:129], v[16:23], v[208:215], v[126:129]
	v_mfma_f32_16x16x128_f8f6f4 v[130:133], v[154:161], v[200:207], v[130:133]
	v_mfma_f32_16x16x128_f8f6f4 v[134:137], v[154:161], v[208:215], v[134:137]
	v_mfma_f32_16x16x128_f8f6f4 v[138:141], v[164:171], v[200:207], v[138:141]
	v_mfma_f32_16x16x128_f8f6f4 v[142:145], v[164:171], v[208:215], v[142:145]
	v_mfma_f32_16x16x128_f8f6f4 v[146:149], v[192:199], v[200:207], v[146:149]
	v_mfma_f32_16x16x128_f8f6f4 v[150:153], v[192:199], v[208:215], v[150:153]
	s_setprio 0
	s_movk_i32 s4, 0x100
	v_cmp_gt_u32_e32 vcc, s4, v113
	s_barrier
	s_and_saveexec_b64 s[4:5], vcc
	s_cbranch_execz .LBB0_91
	s_barrier

.LBB0_122:
	s_mov_b64 s[4:5], -1
	s_and_b64 vcc, exec, s[84:85]
	s_barrier
	s_cbranch_vccz .LBB0_171
	s_mov_b32 s4, -1
	s_sub_i32 s20, 0, s11
	v_mbcnt_lo_u32_b32 v0, s4, 0
	v_mbcnt_hi_u32_b32 v0, s4, v0
	v_readlane_b32 s4, v255, 0
	v_mov_b32_e32 v114, v112
	v_mov_b32_e32 v115, v112
	v_or_b32_e32 v40, s4, v0
	s_movk_i32 s4, 0xffe0
	v_ashrrev_i32_e32 v41, 1, v40
	v_bfi_b32 v0, s4, v41, v40
	s_lshl_b64 s[4:5], s[20:21], 15
	v_ashrrev_i32_e32 v1, 31, v0
	s_add_u32 s6, s94, s4
	v_bfe_u32 v193, v40, 5, 1
	v_lshlrev_b64 v[0:1], 11, v[0:1]
	s_addc_u32 s7, s95, s5
	v_lshl_add_u64 v[0:1], s[98:99], 0, v[0:1]
	v_lshlrev_b32_e32 v162, 5, v193
	s_add_u32 s4, s96, s4
	v_lshl_add_u64 v[0:1], v[0:1], 0, v[162:163]
	v_lshlrev_b32_e32 v166, 4, v40
	s_addc_u32 s5, s97, s5
	global_load_dwordx4 v[126:129], v[0:1], off offset:16 nt
	global_load_dwordx4 v[122:125], v[0:1], off nt
	global_load_dwordx4 v[134:137], v[0:1], off offset:80 nt
	global_load_dwordx4 v[130:133], v[0:1], off offset:64 nt
	v_ashrrev_i32_e32 v2, 3, v40
	v_and_b32_e32 v0, 0x70, v166
	v_mov_b32_e32 v116, v112
	v_mov_b32_e32 v117, v112
	v_mov_b32_e32 v118, v112
	v_mov_b32_e32 v119, v112
	s_cmp_gt_i32 s11, 0
	v_lshl_or_b32 v168, v2, 9, v0
	v_mov_b32_e32 v113, v112
	v_mov_b64_e32 v[120:121], v[118:119]
	s_cselect_b32 s5, s93, s5
	s_cselect_b32 s4, s92, s4
	v_ashrrev_i32_e32 v167, 31, v166
	v_mov_b64_e32 v[118:119], v[116:117]
	v_mov_b64_e32 v[116:117], v[114:115]
	v_mov_b64_e32 v[114:115], v[112:113]
	s_cselect_b32 s7, s91, s7
	s_cselect_b32 s6, s90, s6
	v_lshl_add_u64 v[0:1], s[4:5], 0, v[166:167]
	v_ashrrev_i32_e32 v169, 31, v168
	global_load_dwordx4 v[146:149], v[0:1], off
	v_lshl_add_u64 v[0:1], s[6:7], 0, v[168:169]
	global_load_dwordx4 v[150:153], v[0:1], off
	v_and_b32_e32 v113, 31, v40
	v_lshlrev_b32_e32 v42, 1, v193
	v_and_b32_e32 v0, 7, v41
	v_lshlrev_b32_e32 v1, 7, v2
	v_lshrrev_b32_e32 v2, 1, v2
	v_xor_b32_e32 v2, v2, v40
	v_lshlrev_b32_e32 v165, 7, v113
	v_bitop3_b32 v4, v42, v41, 7 bitop3:0x78
	v_lshlrev_b32_e32 v2, 4, v2
	v_add_u32_e32 v5, 0, v165
	v_bitop3_b32 v6, v42, v0, 1 bitop3:0x36
	v_bitop3_b32 v7, v42, v0, 4 bitop3:0x36
	v_bitop3_b32 v0, v42, v0, 5 bitop3:0x36
	s_movk_i32 s4, 0x70
	v_lshlrev_b32_e32 v197, 4, v4
	v_add_u32_e32 v3, 0, v166
	v_and_or_b32 v1, v2, s4, v1
	v_lshlrev_b32_e32 v196, 4, v6
	v_lshlrev_b32_e32 v195, 4, v7
	v_lshlrev_b32_e32 v194, 4, v0
	v_add_u32_e32 v202, v5, v197
	v_add_u32_e32 v201, 0, v1
	v_add_u32_e32 v203, v5, v196
	v_add_u32_e32 v204, v5, v195
	v_add_u32_e32 v205, v5, v194
	s_waitcnt vmcnt(0)
	s_waitcnt vmcnt(1)
	ds_write_b128 v3, v[146:149]
	s_waitcnt vmcnt(0)
	ds_write_b128 v201, v[150:153] offset:32768
	s_waitcnt lgkmcnt(0)
	s_barrier
	ds_read_b128 v[0:3], v202 offset:32768
	ds_read_b128 v[32:35], v202 offset:36864
	ds_read_b128 v[4:7], v203 offset:32768
	ds_read_b128 v[36:39], v203 offset:36864
	ds_read_b128 v[44:47], v204 offset:32768
	ds_read_b128 v[52:55], v204 offset:36864
	ds_read_b128 v[48:51], v205 offset:32768
	ds_read_b128 v[56:59], v205 offset:36864
	s_waitcnt lgkmcnt(5)
	v_mfma_f32_32x32x64_f8f6f4 v[16:31], v[0:7], v[122:129], 0
	s_waitcnt lgkmcnt(4)
	v_mfma_f32_32x32x64_f8f6f4 v[0:15], v[32:39], v[122:129], 0
	s_waitcnt lgkmcnt(1)
	v_mfma_f32_32x32x64_f8f6f4 v[16:31], v[44:51], v[130:137], v[16:31]
	s_waitcnt lgkmcnt(0)
	v_mfma_f32_32x32x64_f8f6f4 v[0:15], v[52:59], v[130:137], v[0:15]
	s_nop 15
	s_nop 7
	v_max_f32_e32 v32, v17, v17
	v_max_f32_e32 v33, v16, v16
	v_max_f32_e32 v32, v33, v32
	v_max3_f32 v32, v32, v18, v19
	v_max3_f32 v32, v32, v20, v21
	v_max3_f32 v32, v32, v22, v23
	v_max3_f32 v32, v32, v24, v25
	v_max3_f32 v32, v32, v26, v27
	v_max3_f32 v32, v32, v28, v29
	v_max3_f32 v32, v32, v30, v31
	v_max3_f32 v32, v32, v0, v1
	v_max3_f32 v32, v32, v2, v3
	v_max3_f32 v32, v32, v4, v5
	v_max3_f32 v32, v32, v6, v7
	v_max3_f32 v32, v32, v8, v9
	v_max3_f32 v32, v32, v10, v11
	v_max3_f32 v32, v32, v12, v13
	v_max3_f32 v32, v32, v14, v15
	v_mov_b32_e32 v33, v32
	s_nop 1
	v_permlane32_swap_b32_e32 v32, v33
	v_max_f32_e32 v33, v33, v33
	v_max_f32_e32 v32, v32, v32
	v_max_f32_e32 v32, v32, v33
	v_add_f32_e32 v33, 0x7149f2ca, v32
	v_cmp_ge_f32_e32 vcc, s63, v33
	s_cmp_eq_u64 vcc, exec
	s_cbranch_scc0 .LBB0_234
	v_mov_b32_e32 v217, 1.0
	v_mov_b32_e32 v138, 0
	v_mov_b32_e32 v172, 0xf149f2ca
	s_cmp_lt_i32 s11, 2
	s_mov_b64 s[8:9], -1
	s_cbranch_scc0 .LBB0_126

.LBB0_138:
	ds_read_b128 v[80:83], v213 offset:49152
	ds_read_b128 v[84:87], v214 offset:49152
	ds_read_b128 v[222:225], v202 offset:53248
	ds_read_b128 v[226:229], v203 offset:53248
	ds_read_b128 v[230:233], v215 offset:49152
	ds_read_b128 v[234:237], v216 offset:49152
	ds_read_b128 v[238:241], v204 offset:53248
	ds_read_b128 v[242:245], v205 offset:53248
	s_waitcnt lgkmcnt(6)
	v_mfma_f32_32x32x64_f8f6f4 v[96:111], v[80:87], v[122:129], 0
	s_waitcnt lgkmcnt(4)
	v_mfma_f32_32x32x64_f8f6f4 v[80:95], v[222:229], v[122:129], 0
	s_waitcnt lgkmcnt(2)
	v_mfma_f32_32x32x64_f8f6f4 v[96:111], v[230:237], v[130:137], v[96:111]
	s_waitcnt lgkmcnt(0)
	v_mfma_f32_32x32x64_f8f6f4 v[80:95], v[238:245], v[130:137], v[80:95]
	v_exp_f32_e32 v139, v170
	v_exp_f32_e32 v162, v171
	v_exp_f32_e32 v158, v158
	v_exp_f32_e32 v159, v159
	v_exp_f32_e32 v154, v154
	v_exp_f32_e32 v155, v155
	v_exp_f32_e32 v142, v142
	v_exp_f32_e32 v143, v143
	v_exp_f32_e32 v160, v160
	v_exp_f32_e32 v161, v161
	v_exp_f32_e32 v156, v156
	v_exp_f32_e32 v157, v157
	v_exp_f32_e32 v144, v144
	v_exp_f32_e32 v145, v145
	v_exp_f32_e32 v140, v140
	v_exp_f32_e32 v141, v141
	v_cvt_pk_fp8_f32 v222, v219, v220
	v_cvt_pk_fp8_f32 v226, v139, v162
	v_cvt_pk_fp8_f32 v223, v185, v218
	v_cvt_pk_fp8_f32 v227, v158, v159
	v_cvt_pk_fp8_f32 v224, v180, v182
	v_cvt_pk_fp8_f32 v228, v154, v155
	v_cvt_pk_fp8_f32 v225, v177, v178
	v_cvt_pk_fp8_f32 v229, v142, v143
	v_cvt_pk_fp8_f32 v222, v179, v181 op_sel:[0,0,1]
	v_cvt_pk_fp8_f32 v226, v160, v161 op_sel:[0,0,1]
	v_cvt_pk_fp8_f32 v223, v183, v184 op_sel:[0,0,1]
	v_cvt_pk_fp8_f32 v227, v156, v157 op_sel:[0,0,1]
	v_cvt_pk_fp8_f32 v224, v173, v174 op_sel:[0,0,1]
	v_cvt_pk_fp8_f32 v228, v144, v145 op_sel:[0,0,1]
	v_cvt_pk_fp8_f32 v225, v175, v176 op_sel:[0,0,1]
	v_cvt_pk_fp8_f32 v229, v140, v141 op_sel:[0,0,1]
	s_add_i32 s4, s13, -1
	s_cmp_lt_i32 s4, s11
	s_cselect_b32 s5, 0, s11
	s_cselect_b32 s9, s91, s95
	s_cselect_b32 s8, s90, s94
	s_cselect_b32 s14, s92, s96
	s_cselect_b32 s15, s93, s97
	s_sub_i32 s20, s4, s5
	s_lshl_b64 s[4:5], s[20:21], 15
	s_add_u32 s8, s8, s4
	s_addc_u32 s9, s9, s5
	s_add_u32 s4, s14, s4
	s_addc_u32 s5, s15, s5
	v_lshl_add_u64 v[140:141], s[4:5], 0, v[166:167]
	global_load_dwordx4 v[158:161], v[140:141], off
	v_lshl_add_u64 v[140:141], s[8:9], 0, v[168:169]
	global_load_dwordx4 v[154:157], v[140:141], off
	v_add_u32_e32 v162, v210, v199
	v_add_u32_e32 v218, v210, v200
	ds_read_b128 v[174:177], v162
	ds_read_b128 v[230:233], v162 offset:2048
	ds_read_b128 v[178:181], v218
	ds_read_b128 v[234:237], v218 offset:2048
	ds_read_b128 v[238:241], v162 offset:4096
	ds_read_b128 v[246:249], v162 offset:6144
	ds_read_b128 v[242:245], v218 offset:4096
	ds_read_b128 v[250:253], v218 offset:6144
	s_waitcnt lgkmcnt(5)
	s_nop 3
	v_mfma_f32_32x32x64_f8f6f4 v[48:63], v[222:229], v[174:181], v[48:63]
	s_waitcnt lgkmcnt(4)
	v_mfma_f32_32x32x64_f8f6f4 v[32:47], v[222:229], v[230:237], v[32:47]
	s_waitcnt lgkmcnt(1)
	v_mfma_f32_32x32x64_f8f6f4 v[16:31], v[222:229], v[238:245], v[16:31]
	s_waitcnt lgkmcnt(0)
	v_mfma_f32_32x32x64_f8f6f4 v[0:15], v[222:229], v[246:253], v[0:15]
	v_mfma_f32_32x32x64_f8f6f4 v[64:79], v[222:229], v[114:121], v[64:79]
	v_max_f32_e32 v139, v97, v97
	v_max_f32_e32 v140, v96, v96
	v_max_f32_e32 v139, v140, v139
	v_max3_f32 v139, v139, v98, v99
	v_max3_f32 v139, v139, v100, v101
	v_max3_f32 v139, v139, v102, v103
	v_max3_f32 v139, v139, v104, v105
	v_max3_f32 v139, v139, v106, v107
	v_max3_f32 v139, v139, v108, v109
	v_max3_f32 v139, v139, v110, v111
	v_max3_f32 v139, v139, v80, v81
	v_max3_f32 v139, v139, v82, v83
	v_max3_f32 v139, v139, v84, v85
	v_max3_f32 v139, v139, v86, v87
	v_max3_f32 v139, v139, v88, v89
	v_max3_f32 v139, v139, v90, v91
	v_max3_f32 v139, v139, v92, v93
	v_max3_f32 v139, v139, v94, v95
	v_mov_b32_e32 v140, v139
	s_nop 1
	v_permlane32_swap_b32_e32 v139, v140
	v_max_f32_e32 v140, v140, v140
	v_max_f32_e32 v139, v139, v139
	v_max_f32_e32 v139, v139, v140
	v_sub_f32_e32 v140, v139, v172
	v_cmp_ge_f32_e32 vcc, s63, v140
	s_cmp_lg_u64 vcc, exec
	s_cselect_b64 s[8:9], -1, 0
	s_mov_b64 vcc, s[8:9]
	s_cbranch_vccnz .LBB0_156
	v_mov_b32_e32 v140, v138

.LBB0_145:
	v_pk_fma_f32 v[96:97], v[96:97], s[62:63], v[140:141] op_sel_hi:[1,0,0]
	v_pk_fma_f32 v[170:171], v[80:81], s[62:63], v[140:141] op_sel_hi:[1,0,0]
	v_pk_fma_f32 v[80:81], v[98:99], s[62:63], v[140:141] op_sel_hi:[1,0,0]
	v_pk_fma_f32 v[172:173], v[82:83], s[62:63], v[140:141] op_sel_hi:[1,0,0]
	v_pk_fma_f32 v[82:83], v[100:101], s[62:63], v[140:141] op_sel_hi:[1,0,0]
	v_pk_fma_f32 v[174:175], v[84:85], s[62:63], v[140:141] op_sel_hi:[1,0,0]
	v_pk_fma_f32 v[84:85], v[102:103], s[62:63], v[140:141] op_sel_hi:[1,0,0]
	v_pk_fma_f32 v[176:177], v[86:87], s[62:63], v[140:141] op_sel_hi:[1,0,0]
	v_pk_fma_f32 v[86:87], v[104:105], s[62:63], v[140:141] op_sel_hi:[1,0,0]
	v_pk_fma_f32 v[178:179], v[88:89], s[62:63], v[140:141] op_sel_hi:[1,0,0]
	v_pk_fma_f32 v[88:89], v[106:107], s[62:63], v[140:141] op_sel_hi:[1,0,0]
	v_pk_fma_f32 v[98:99], v[108:109], s[62:63], v[140:141] op_sel_hi:[1,0,0]
	v_pk_fma_f32 v[100:101], v[110:111], s[62:63], v[140:141] op_sel_hi:[1,0,0]
	v_exp_f32_e32 v235, v96
	v_exp_f32_e32 v236, v97
	v_exp_f32_e32 v227, v80
	v_exp_f32_e32 v229, v81
	v_exp_f32_e32 v233, v82
	v_exp_f32_e32 v234, v83
	v_exp_f32_e32 v231, v84
	v_exp_f32_e32 v232, v85
	v_exp_f32_e32 v228, v86
	v_exp_f32_e32 v230, v87
	v_exp_f32_e32 v221, v88
	v_exp_f32_e32 v222, v89
	v_exp_f32_e32 v225, v98
	v_exp_f32_e32 v226, v99
	v_exp_f32_e32 v223, v100
	v_exp_f32_e32 v224, v101
	v_pk_fma_f32 v[184:185], v[90:91], s[62:63], v[140:141] op_sel_hi:[1,0,0]
	v_pk_fma_f32 v[182:183], v[92:93], s[62:63], v[140:141] op_sel_hi:[1,0,0]
	v_pk_fma_f32 v[180:181], v[94:95], s[62:63], v[140:141] op_sel_hi:[1,0,0]
	s_waitcnt lgkmcnt(0)
	s_barrier
	ds_read_b128 v[80:83], v213 offset:32768
	ds_read_b128 v[84:87], v214 offset:32768
	ds_read_b128 v[138:141], v202 offset:36864
	ds_read_b128 v[142:145], v203 offset:36864
	ds_read_b128 v[238:241], v215 offset:32768
	ds_read_b128 v[242:245], v216 offset:32768
	ds_read_b128 v[246:249], v204 offset:36864
	ds_read_b128 v[250:253], v205 offset:36864
	s_waitcnt lgkmcnt(6)
	v_mfma_f32_32x32x64_f8f6f4 v[96:111], v[80:87], v[122:129], 0
	s_waitcnt lgkmcnt(4)
	v_mfma_f32_32x32x64_f8f6f4 v[80:95], v[138:145], v[122:129], 0
	s_waitcnt lgkmcnt(2)
	v_mfma_f32_32x32x64_f8f6f4 v[96:111], v[238:245], v[130:137], v[96:111]
	s_waitcnt lgkmcnt(0)
	v_mfma_f32_32x32x64_f8f6f4 v[80:95], v[246:253], v[130:137], v[80:95]
	s_cmp_ge_i32 s13, s12
	s_cselect_b64 s[4:5], -1, 0
	s_and_b64 vcc, exec, s[4:5]
	s_cbranch_vccnz .LBB0_147
	s_cmp_lt_i32 s13, s11
	s_cselect_b32 s8, 0, s11
	s_cselect_b32 s14, s91, s95
	s_cselect_b32 s15, s90, s94
	s_cselect_b32 s22, s92, s96
	s_cselect_b32 s23, s93, s97
	s_sub_i32 s20, s13, s8
	s_lshl_b64 s[8:9], s[20:21], 15
	s_add_u32 s18, s15, s8
	s_addc_u32 s19, s14, s9
	s_add_u32 s8, s22, s8
	s_addc_u32 s9, s23, s9
	v_lshl_add_u64 v[146:147], s[8:9], 0, v[166:167]
	v_lshl_add_u64 v[150:151], s[18:19], 0, v[168:169]
	global_load_dwordx4 v[146:149], v[146:147], off
	s_nop 0
	global_load_dwordx4 v[150:153], v[150:151], off
.LBB0_147:
	v_exp_f32_e32 v170, v170
	v_exp_f32_e32 v171, v171
	v_exp_f32_e32 v174, v174
	v_exp_f32_e32 v175, v175
	v_exp_f32_e32 v178, v178
	v_exp_f32_e32 v179, v179
	v_exp_f32_e32 v182, v182
	v_exp_f32_e32 v183, v183
	v_cvt_pk_fp8_f32 v138, v235, v236
	v_exp_f32_e32 v172, v172
	v_exp_f32_e32 v173, v173
	v_exp_f32_e32 v176, v176
	v_exp_f32_e32 v177, v177
	v_exp_f32_e32 v184, v184
	v_exp_f32_e32 v185, v185
	v_exp_f32_e32 v180, v180
	v_exp_f32_e32 v181, v181
	v_cvt_pk_fp8_f32 v142, v170, v171
	v_cvt_pk_fp8_f32 v139, v233, v234
	v_cvt_pk_fp8_f32 v143, v174, v175
	v_cvt_pk_fp8_f32 v138, v227, v229 op_sel:[0,0,1]
	v_cvt_pk_fp8_f32 v140, v228, v230
	v_cvt_pk_fp8_f32 v144, v178, v179
	v_cvt_pk_fp8_f32 v141, v225, v226
	v_cvt_pk_fp8_f32 v145, v182, v183
	v_cvt_pk_fp8_f32 v142, v172, v173 op_sel:[0,0,1]
	v_cvt_pk_fp8_f32 v139, v231, v232 op_sel:[0,0,1]
	v_cvt_pk_fp8_f32 v143, v176, v177 op_sel:[0,0,1]
	v_cvt_pk_fp8_f32 v140, v221, v222 op_sel:[0,0,1]
	v_cvt_pk_fp8_f32 v144, v184, v185 op_sel:[0,0,1]
	v_cvt_pk_fp8_f32 v141, v223, v224 op_sel:[0,0,1]
	v_cvt_pk_fp8_f32 v145, v180, v181 op_sel:[0,0,1]
	ds_read_b128 v[170:173], v162 offset:16384
	ds_read_b128 v[178:181], v162 offset:18432
	ds_read_b128 v[174:177], v218 offset:16384
	ds_read_b128 v[182:185], v218 offset:18432
	ds_read_b128 v[222:225], v162 offset:20480
	ds_read_b128 v[230:233], v162 offset:22528
	ds_read_b128 v[226:229], v218 offset:20480
	ds_read_b128 v[234:237], v218 offset:22528
	s_waitcnt lgkmcnt(5)
	s_nop 3
	v_mfma_f32_32x32x64_f8f6f4 v[48:63], v[138:145], v[170:177], v[48:63]
	s_waitcnt lgkmcnt(4)
	v_mfma_f32_32x32x64_f8f6f4 v[32:47], v[138:145], v[178:185], v[32:47]
	s_waitcnt lgkmcnt(1)
	v_mfma_f32_32x32x64_f8f6f4 v[16:31], v[138:145], v[222:229], v[16:31]
	s_waitcnt lgkmcnt(0)
	v_mfma_f32_32x32x64_f8f6f4 v[0:15], v[138:145], v[230:237], v[0:15]
	v_mfma_f32_32x32x64_f8f6f4 v[64:79], v[138:145], v[114:121], v[64:79]
	v_max_f32_e32 v138, v97, v97
	v_max_f32_e32 v139, v96, v96
	v_max_f32_e32 v138, v139, v138
	v_max3_f32 v138, v138, v98, v99
	v_max3_f32 v138, v138, v100, v101
	v_max3_f32 v138, v138, v102, v103
	v_max3_f32 v138, v138, v104, v105
	v_max3_f32 v138, v138, v106, v107
	v_max3_f32 v138, v138, v108, v109
	v_max3_f32 v138, v138, v110, v111
	v_max3_f32 v138, v138, v80, v81
	v_max3_f32 v138, v138, v82, v83
	v_max3_f32 v138, v138, v84, v85
	v_max3_f32 v138, v138, v86, v87
	v_max3_f32 v138, v138, v88, v89
	v_max3_f32 v138, v138, v90, v91
	v_max3_f32 v138, v138, v92, v93
	v_max3_f32 v138, v138, v94, v95
	v_mov_b32_e32 v139, v138
	s_nop 1
	v_permlane32_swap_b32_e32 v138, v139
	v_max_f32_e32 v139, v139, v139
	v_max_f32_e32 v138, v138, v138
	v_max_f32_e32 v138, v138, v139
	v_sub_f32_e32 v139, v138, v219
	v_cmp_ge_f32_e32 vcc, s63, v139
	s_cmp_lg_u64 vcc, exec
	s_cselect_b64 s[8:9], -1, 0
	s_mov_b64 vcc, s[8:9]
	s_cbranch_vccnz .LBB0_157
	v_mov_b32_e32 v162, v220

.LBB0_160:
	v_add_u32_e32 v81, 0, v197
	v_add_u32_e32 v90, 0, v196
	v_add_u32_e32 v82, v81, v165
	v_add_u32_e32 v86, v90, v165
	v_add_u32_e32 v81, v81, v80
	ds_read_b128 v[82:85], v82 offset:49152
	ds_read_b128 v[86:89], v86 offset:49152
	v_add_u32_e32 v90, v90, v80
	ds_read_b128 v[146:149], v81 offset:49152
	ds_read_b128 v[150:153], v90 offset:49152
	v_add_u32_e32 v81, 0, v195
	v_add_u32_e32 v90, v81, v165
	v_add_u32_e32 v91, 0, v194
	v_add_u32_e32 v81, v81, v80
	v_add_u32_e32 v92, v91, v165
	ds_read_b128 v[210:213], v90 offset:49152
	ds_read_b128 v[214:217], v92 offset:49152
	v_add_u32_e32 v80, v91, v80
	ds_read_b128 v[222:225], v81 offset:49152
	ds_read_b128 v[226:229], v80 offset:49152
	s_waitcnt lgkmcnt(6)
	v_mfma_f32_32x32x64_f8f6f4 v[96:111], v[82:89], v[122:129], 0
	s_waitcnt lgkmcnt(4)
	v_mfma_f32_32x32x64_f8f6f4 v[80:95], v[146:153], v[122:129], 0
	s_waitcnt lgkmcnt(2)
	v_mfma_f32_32x32x64_f8f6f4 v[96:111], v[210:217], v[130:137], v[96:111]
	s_waitcnt lgkmcnt(0)
	v_mfma_f32_32x32x64_f8f6f4 v[80:95], v[222:229], v[130:137], v[80:95]
	v_exp_f32_e32 v122, v170
	v_exp_f32_e32 v123, v171
	v_exp_f32_e32 v134, v158
	v_exp_f32_e32 v135, v159
	v_exp_f32_e32 v139, v154
	v_exp_f32_e32 v146, v155
	v_exp_f32_e32 v142, v142
	v_exp_f32_e32 v143, v143
	v_cvt_pk_fp8_f32 v124, v219, v220
	v_cvt_pk_fp8_f32 v125, v185, v218
	v_exp_f32_e32 v132, v160
	v_exp_f32_e32 v133, v161
	v_exp_f32_e32 v136, v156
	v_exp_f32_e32 v137, v157
	v_exp_f32_e32 v144, v144
	v_exp_f32_e32 v145, v145
	v_exp_f32_e32 v140, v140
	v_exp_f32_e32 v141, v141
	v_cvt_pk_fp8_f32 v128, v122, v123
	v_cvt_pk_fp8_f32 v129, v134, v135
	v_cvt_pk_fp8_f32 v124, v179, v181 op_sel:[0,0,1]
	v_cvt_pk_fp8_f32 v125, v183, v184 op_sel:[0,0,1]
	v_cvt_pk_fp8_f32 v126, v180, v182
	v_cvt_pk_fp8_f32 v130, v139, v146
	v_cvt_pk_fp8_f32 v127, v177, v178
	v_cvt_pk_fp8_f32 v131, v142, v143
	v_cvt_pk_fp8_f32 v128, v132, v133 op_sel:[0,0,1]
	v_cvt_pk_fp8_f32 v129, v136, v137 op_sel:[0,0,1]
	v_cvt_pk_fp8_f32 v126, v173, v174 op_sel:[0,0,1]
	v_cvt_pk_fp8_f32 v130, v144, v145 op_sel:[0,0,1]
	v_cvt_pk_fp8_f32 v127, v175, v176 op_sel:[0,0,1]
	v_cvt_pk_fp8_f32 v131, v140, v141 op_sel:[0,0,1]
	v_add_u32_e32 v123, 0, v162
	v_add_u32_e32 v122, v123, v199
	v_add_u32_e32 v123, v123, v200
	ds_read_b128 v[140:143], v122
	ds_read_b128 v[148:151], v122 offset:2048
	ds_read_b128 v[144:147], v123
	ds_read_b128 v[152:155], v123 offset:2048
	ds_read_b128 v[174:177], v122 offset:4096
	ds_read_b128 v[200:203], v122 offset:6144
	ds_read_b128 v[178:181], v123 offset:4096
	ds_read_b128 v[204:207], v123 offset:6144
	s_waitcnt lgkmcnt(5)
	s_nop 3
	v_mfma_f32_32x32x64_f8f6f4 v[48:63], v[124:131], v[140:147], v[48:63]
	s_waitcnt lgkmcnt(4)
	v_mfma_f32_32x32x64_f8f6f4 v[32:47], v[124:131], v[148:155], v[32:47]
	s_waitcnt lgkmcnt(1)
	v_mfma_f32_32x32x64_f8f6f4 v[16:31], v[124:131], v[174:181], v[16:31]
	s_waitcnt lgkmcnt(0)
	v_mfma_f32_32x32x64_f8f6f4 v[0:15], v[124:131], v[200:207], v[0:15]
	v_mfma_f32_32x32x64_f8f6f4 v[64:79], v[124:131], v[114:121], v[64:79]
	s_nop 15
	s_nop 7
	v_max_f32_e32 v124, v97, v97
	v_max_f32_e32 v125, v96, v96
	v_max_f32_e32 v124, v125, v124
	v_max3_f32 v124, v124, v98, v99
	v_max3_f32 v124, v124, v100, v101
	v_max3_f32 v124, v124, v102, v103
	v_max3_f32 v124, v124, v104, v105
	v_max3_f32 v124, v124, v106, v107
	v_max3_f32 v124, v124, v108, v109
	v_max3_f32 v124, v124, v110, v111
	v_max3_f32 v124, v124, v80, v81
	v_max3_f32 v124, v124, v82, v83
	v_max3_f32 v124, v124, v84, v85
	v_max3_f32 v124, v124, v86, v87
	v_max3_f32 v124, v124, v88, v89
	v_max3_f32 v124, v124, v90, v91
	v_max3_f32 v124, v124, v92, v93
	v_max3_f32 v124, v124, v94, v95
	v_mov_b32_e32 v125, v124
	s_nop 1
	v_permlane32_swap_b32_e32 v124, v125
	v_max_f32_e32 v125, v125, v125
	v_max_f32_e32 v124, v124, v124
	v_max_f32_e32 v125, v124, v125
	v_sub_f32_e32 v124, v125, v172
	v_cmp_ge_f32_e32 vcc, s63, v124
	s_cmp_lg_u64 vcc, exec
	s_cselect_b64 s[6:7], -1, 0
	s_mov_b64 s[4:5], -1
	s_mov_b64 vcc, s[6:7]
	s_cbranch_vccnz .LBB0_235
	s_andn2_b64 vcc, exec, s[4:5]
	s_cbranch_vccnz .LBB0_163

.LBB0_167:
	v_pk_fma_f32 v[96:97], v[96:97], s[62:63], v[138:139] op_sel_hi:[1,0,0]
	v_pk_fma_f32 v[80:81], v[80:81], s[62:63], v[138:139] op_sel_hi:[1,0,0]
	v_pk_fma_f32 v[98:99], v[98:99], s[62:63], v[138:139] op_sel_hi:[1,0,0]
	v_pk_fma_f32 v[100:101], v[100:101], s[62:63], v[138:139] op_sel_hi:[1,0,0]
	v_pk_fma_f32 v[84:85], v[84:85], s[62:63], v[138:139] op_sel_hi:[1,0,0]
	v_pk_fma_f32 v[126:127], v[104:105], s[62:63], v[138:139] op_sel_hi:[1,0,0]
	v_pk_fma_f32 v[88:89], v[88:89], s[62:63], v[138:139] op_sel_hi:[1,0,0]
	v_pk_fma_f32 v[128:129], v[106:107], s[62:63], v[138:139] op_sel_hi:[1,0,0]
	v_pk_fma_f32 v[92:93], v[92:93], s[62:63], v[138:139] op_sel_hi:[1,0,0]
	v_pk_fma_f32 v[132:133], v[110:111], s[62:63], v[138:139] op_sel_hi:[1,0,0]
	v_exp_f32_e32 v124, v96
	v_exp_f32_e32 v125, v97
	v_exp_f32_e32 v104, v98
	v_exp_f32_e32 v106, v99
	v_exp_f32_e32 v110, v100
	v_exp_f32_e32 v111, v101
	v_exp_f32_e32 v105, v126
	v_exp_f32_e32 v107, v127
	v_exp_f32_e32 v98, v128
	v_exp_f32_e32 v99, v129
	v_pk_fma_f32 v[96:97], v[90:91], s[62:63], v[138:139] op_sel_hi:[1,0,0]
	v_pk_fma_f32 v[90:91], v[94:95], s[62:63], v[138:139] op_sel_hi:[1,0,0]
	v_exp_f32_e32 v94, v80
	v_exp_f32_e32 v95, v81
	v_exp_f32_e32 v128, v84
	v_exp_f32_e32 v129, v85
	v_exp_f32_e32 v88, v88
	v_exp_f32_e32 v89, v89
	v_exp_f32_e32 v92, v92
	v_exp_f32_e32 v93, v93
	v_pk_fma_f32 v[82:83], v[82:83], s[62:63], v[138:139] op_sel_hi:[1,0,0]
	v_pk_fma_f32 v[102:103], v[102:103], s[62:63], v[138:139] op_sel_hi:[1,0,0]
	v_pk_fma_f32 v[86:87], v[86:87], s[62:63], v[138:139] op_sel_hi:[1,0,0]
	v_pk_fma_f32 v[130:131], v[108:109], s[62:63], v[138:139] op_sel_hi:[1,0,0]
	v_exp_f32_e32 v108, v102
	v_exp_f32_e32 v109, v103
	v_exp_f32_e32 v102, v130
	v_exp_f32_e32 v103, v131
	v_exp_f32_e32 v126, v82
	v_exp_f32_e32 v127, v83
	v_exp_f32_e32 v130, v86
	v_exp_f32_e32 v131, v87
	v_exp_f32_e32 v96, v96
	v_exp_f32_e32 v97, v97
	v_exp_f32_e32 v90, v90
	v_exp_f32_e32 v91, v91
	v_cvt_pk_fp8_f32 v80, v124, v125
	v_cvt_pk_fp8_f32 v84, v94, v95
	v_cvt_pk_fp8_f32 v81, v110, v111
	v_cvt_pk_fp8_f32 v85, v128, v129
	v_cvt_pk_fp8_f32 v82, v105, v107
	v_cvt_pk_fp8_f32 v86, v88, v89
	v_cvt_pk_fp8_f32 v87, v92, v93
	v_exp_f32_e32 v100, v132
	v_exp_f32_e32 v101, v133
	v_cvt_pk_fp8_f32 v80, v104, v106 op_sel:[0,0,1]
	v_cvt_pk_fp8_f32 v84, v126, v127 op_sel:[0,0,1]
	v_cvt_pk_fp8_f32 v81, v108, v109 op_sel:[0,0,1]
	v_cvt_pk_fp8_f32 v85, v130, v131 op_sel:[0,0,1]
	v_cvt_pk_fp8_f32 v83, v102, v103
	v_cvt_pk_fp8_f32 v82, v98, v99 op_sel:[0,0,1]
	v_cvt_pk_fp8_f32 v86, v96, v97 op_sel:[0,0,1]
	v_cvt_pk_fp8_f32 v87, v90, v91 op_sel:[0,0,1]
	v_cvt_pk_fp8_f32 v83, v100, v101 op_sel:[0,0,1]
	s_cmp_eq_u32 s60, 0
	ds_read_b128 v[88:91], v122 offset:16384
	ds_read_b128 v[96:99], v122 offset:18432
	ds_read_b128 v[92:95], v123 offset:16384
	ds_read_b128 v[100:103], v123 offset:18432
	ds_read_b128 v[104:107], v122 offset:20480
	ds_read_b128 v[124:127], v122 offset:22528
	ds_read_b128 v[108:111], v123 offset:20480
	ds_read_b128 v[128:131], v123 offset:22528
	v_ashrrev_i32_e32 v165, 31, v164
	s_waitcnt lgkmcnt(5)
	s_nop 3
	v_mfma_f32_32x32x64_f8f6f4 v[48:63], v[80:87], v[88:95], v[48:63]
	s_waitcnt lgkmcnt(4)
	v_mfma_f32_32x32x64_f8f6f4 v[32:47], v[80:87], v[96:103], v[32:47]
	s_waitcnt lgkmcnt(1)
	v_mfma_f32_32x32x64_f8f6f4 v[16:31], v[80:87], v[104:111], v[16:31]
	s_waitcnt lgkmcnt(0)
	v_mfma_f32_32x32x64_f8f6f4 v[0:15], v[80:87], v[124:131], v[0:15]
	v_mfma_f32_32x32x64_f8f6f4 v[64:79], v[80:87], v[114:121], v[64:79]
	s_nop 15
	s_nop 7
	s_cmp_eq_u32 s60, 0
	s_cbranch_scc1 .Lepi8_d

.LBB0_171:
	s_and_b64 vcc, exec, s[4:5]
	s_cbranch_vccz .LBB0_115
	s_mov_b32 s6, -1
	s_cmp_lg_u32 s35, 0
	v_mbcnt_lo_u32_b32 v0, s6, 0
	v_mbcnt_hi_u32_b32 v0, s6, v0
	v_readlane_b32 s6, v255, 0
	s_cselect_b64 s[22:23], -1, 0
	s_cmp_eq_u32 s35, 0
	v_or_b32_e32 v40, s6, v0
	s_cselect_b64 s[4:5], -1, 0
	v_ashrrev_i32_e32 v4, 6, v40
	v_and_b32_e32 v193, 31, v40
	v_readfirstlane_b32 s6, v4
	s_lshl_b32 s13, s6, 5
	s_sub_i32 s18, 0, s13
	s_cmp_gt_i32 s11, 0
	v_lshlrev_b32_e32 v164, 5, v4
	s_cselect_b64 s[6:7], -1, 0
	s_sub_i32 s20, 0, s11
	v_or_b32_e32 v0, v164, v193
	s_lshl_b64 s[8:9], s[20:21], 15
	v_ashrrev_i32_e32 v1, 31, v0
	s_add_u32 s12, s94, s8
	v_bfe_u32 v194, v40, 5, 1
	v_lshlrev_b64 v[2:3], 11, v[0:1]
	s_addc_u32 s19, s95, s9
	v_lshl_add_u64 v[2:3], s[98:99], 0, v[2:3]
	v_lshlrev_b32_e32 v162, 5, v194
	s_add_u32 s20, s96, s8
	v_lshl_add_u64 v[2:3], v[2:3], 0, v[162:163]
	v_lshlrev_b32_e32 v168, 4, v40
	s_addc_u32 s29, s97, s9
	global_load_dwordx4 v[126:129], v[2:3], off offset:16 nt
	global_load_dwordx4 v[122:125], v[2:3], off nt
	global_load_dwordx4 v[134:137], v[2:3], off offset:80 nt
	global_load_dwordx4 v[130:133], v[2:3], off offset:64 nt
	v_ashrrev_i32_e32 v1, 3, v40
	v_and_b32_e32 v2, 0x70, v168
	v_mov_b32_e32 v114, v112
	v_mov_b32_e32 v115, v112
	v_mov_b32_e32 v116, v112
	v_mov_b32_e32 v117, v112
	v_mov_b32_e32 v118, v112
	v_mov_b32_e32 v119, v112
	s_and_b64 s[8:9], s[6:7], exec
	v_lshl_or_b32 v170, v1, 9, v2
	v_mov_b32_e32 v113, v112
	v_mov_b64_e32 v[120:121], v[118:119]
	s_cselect_b32 s9, s93, s29
	s_cselect_b32 s8, s92, s20
	v_ashrrev_i32_e32 v169, 31, v168
	v_mov_b64_e32 v[118:119], v[116:117]
	v_mov_b64_e32 v[116:117], v[114:115]
	v_mov_b64_e32 v[114:115], v[112:113]
	s_cselect_b32 s35, s91, s19
	s_cselect_b32 s34, s90, s12
	v_lshl_add_u64 v[2:3], s[8:9], 0, v[168:169]
	v_ashrrev_i32_e32 v171, 31, v170
	global_load_dwordx4 v[146:149], v[2:3], off
	v_lshl_add_u64 v[2:3], s[34:35], 0, v[170:171]
	global_load_dwordx4 v[150:153], v[2:3], off
	v_lshlrev_b32_e32 v41, 1, v194
	s_waitcnt vmcnt(6)
	v_readfirstlane_b32 s35, v192
	v_lshrrev_b32_e32 v7, 1, v40
	v_and_b32_e32 v2, 7, v7
	v_lshlrev_b32_e32 v3, 7, v1
	v_lshrrev_b32_e32 v1, 1, v1
	v_xor_b32_e32 v1, v1, v40
	v_lshlrev_b32_e32 v192, 7, v193
	v_bitop3_b32 v5, v41, v7, 7 bitop3:0x78
	v_lshlrev_b32_e32 v1, 4, v1
	v_add_u32_e32 v6, 0, v192
	v_bitop3_b32 v7, v41, v2, 1 bitop3:0x36
	v_bitop3_b32 v8, v41, v2, 4 bitop3:0x36
	v_bitop3_b32 v2, v41, v2, 5 bitop3:0x36
	s_movk_i32 s8, 0x70
	v_lshlrev_b32_e32 v198, 4, v5
	v_add_u32_e32 v4, 0, v168
	v_and_or_b32 v1, v1, s8, v3
	v_lshlrev_b32_e32 v197, 4, v7
	v_lshlrev_b32_e32 v196, 4, v8
	v_lshlrev_b32_e32 v195, 4, v2
	v_add_u32_e32 v203, v6, v198
	v_sub_u32_e32 v165, s52, v0
	v_add_u32_e32 v202, 0, v1
	v_add_u32_e32 v204, v6, v197
	v_add_u32_e32 v205, v6, v196
	v_add_u32_e32 v206, v6, v195
	s_waitcnt vmcnt(0)
	s_or_b64 s[4:5], s[6:7], s[4:5]
	s_and_b64 vcc, exec, s[4:5]
	s_waitcnt vmcnt(1)
	ds_write_b128 v4, v[146:149]
	s_waitcnt vmcnt(0)
	ds_write_b128 v202, v[150:153] offset:32768
	s_waitcnt lgkmcnt(0)
	s_barrier
	ds_read_b128 v[0:3], v203 offset:32768
	ds_read_b128 v[32:35], v203 offset:36864
	ds_read_b128 v[4:7], v204 offset:32768
	ds_read_b128 v[36:39], v204 offset:36864
	ds_read_b128 v[42:45], v205 offset:32768
	ds_read_b128 v[50:53], v205 offset:36864
	ds_read_b128 v[46:49], v206 offset:32768
	ds_read_b128 v[54:57], v206 offset:36864
	s_waitcnt lgkmcnt(5)
	v_mfma_f32_32x32x64_f8f6f4 v[16:31], v[0:7], v[122:129], 0
	s_waitcnt lgkmcnt(4)
	v_mfma_f32_32x32x64_f8f6f4 v[0:15], v[32:39], v[122:129], 0
	s_waitcnt lgkmcnt(1)
	v_mfma_f32_32x32x64_f8f6f4 v[16:31], v[42:49], v[130:137], v[16:31]
	s_waitcnt lgkmcnt(0)
	v_mfma_f32_32x32x64_f8f6f4 v[0:15], v[50:57], v[130:137], v[0:15]
	s_nop 15
	s_nop 7
	s_cbranch_vccnz .LBB0_175
	s_lshl_b32 s4, s11, 6
	s_sub_i32 s5, s52, s4
	s_add_i32 s5, s5, s18
	s_addk_i32 s5, 0xffbe
	s_cmp_gt_u32 s5, 0xffffff5c
	s_cbranch_scc1 .LBB0_175
	s_sub_i32 s4, 0, s4
	v_lshl_or_b32 v32, v194, 2, s4
	v_add_u32_e32 v32, v32, v165
	v_add_u32_e32 v33, 0xffffff7f, v32
	v_cmp_lt_u32_e32 vcc, s67, v33
	v_add_u32_e32 v33, 0xffffff9f, v32
	s_nop 0
	v_cndmask_b32_e32 v16, v191, v16, vcc
	v_cmp_lt_u32_e32 vcc, s67, v33
	v_add_u32_e32 v33, 0xffffff80, v32
	s_nop 0
	v_cndmask_b32_e32 v0, v191, v0, vcc
	v_cmp_lt_u32_e32 vcc, s67, v33
	v_add_u32_e32 v33, 0xffffffa0, v32
	s_nop 0
	v_cndmask_b32_e32 v17, v191, v17, vcc
	v_cmp_lt_u32_e32 vcc, s67, v33
	v_add_u32_e32 v33, 0xffffff81, v32
	s_nop 0
	v_cndmask_b32_e32 v1, v191, v1, vcc
	v_cmp_lt_u32_e32 vcc, s67, v33
	v_add_u32_e32 v33, 0xffffffa1, v32
	s_nop 0
	v_cndmask_b32_e32 v18, v191, v18, vcc
	v_cmp_lt_u32_e32 vcc, s67, v33
	v_add_u32_e32 v33, 0xffffff82, v32
	s_nop 0
	v_cndmask_b32_e32 v2, v191, v2, vcc
	v_cmp_lt_u32_e32 vcc, s67, v33
	v_add_u32_e32 v33, 0xffffffa2, v32
	s_nop 0
	v_cndmask_b32_e32 v19, v191, v19, vcc
	v_cmp_lt_u32_e32 vcc, s67, v33
	v_add_u32_e32 v33, 0xffffff87, v32
	s_nop 0
	v_cndmask_b32_e32 v3, v191, v3, vcc
	v_cmp_lt_u32_e32 vcc, s67, v33
	v_add_u32_e32 v33, 0xffffffa7, v32
	s_nop 0
	v_cndmask_b32_e32 v20, v191, v20, vcc
	v_cmp_lt_u32_e32 vcc, s67, v33
	v_add_u32_e32 v33, 0xffffff88, v32
	s_nop 0
	v_cndmask_b32_e32 v4, v191, v4, vcc
	v_cmp_lt_u32_e32 vcc, s67, v33
	v_add_u32_e32 v33, 0xffffffa8, v32
	s_nop 0
	v_cndmask_b32_e32 v21, v191, v21, vcc
	v_cmp_lt_u32_e32 vcc, s67, v33
	v_add_u32_e32 v33, 0xffffff89, v32
	s_nop 0
	v_cndmask_b32_e32 v5, v191, v5, vcc
	v_cmp_lt_u32_e32 vcc, s67, v33
	v_add_u32_e32 v33, 0xffffffa9, v32
	s_nop 0
	v_cndmask_b32_e32 v22, v191, v22, vcc
	v_cmp_lt_u32_e32 vcc, s67, v33
	v_add_u32_e32 v33, 0xffffff8a, v32
	s_nop 0
	v_cndmask_b32_e32 v6, v191, v6, vcc
	v_cmp_lt_u32_e32 vcc, s67, v33
	v_add_u32_e32 v33, 0xffffffaa, v32
	s_nop 0
	v_cndmask_b32_e32 v23, v191, v23, vcc
	v_cmp_lt_u32_e32 vcc, s67, v33
	v_add_u32_e32 v33, 0xffffff8f, v32
	s_nop 0
	v_cndmask_b32_e32 v7, v191, v7, vcc
	v_cmp_lt_u32_e32 vcc, s67, v33
	v_add_u32_e32 v33, 0xffffffaf, v32
	s_nop 0
	v_cndmask_b32_e32 v24, v191, v24, vcc
	v_cmp_lt_u32_e32 vcc, s67, v33
	v_add_u32_e32 v33, 0xffffff90, v32
	s_nop 0
	v_cndmask_b32_e32 v8, v191, v8, vcc
	v_cmp_lt_u32_e32 vcc, s67, v33
	v_add_u32_e32 v33, 0xffffffb0, v32
	s_nop 0
	v_cndmask_b32_e32 v25, v191, v25, vcc
	v_cmp_lt_u32_e32 vcc, s67, v33
	v_add_u32_e32 v33, 0xffffff91, v32
	s_nop 0
	v_cndmask_b32_e32 v9, v191, v9, vcc
	v_cmp_lt_u32_e32 vcc, s67, v33
	v_add_u32_e32 v33, 0xffffffb1, v32
	s_nop 0
	v_cndmask_b32_e32 v26, v191, v26, vcc
	v_cmp_lt_u32_e32 vcc, s67, v33
	v_add_u32_e32 v33, 0xffffff92, v32
	s_nop 0
	v_cndmask_b32_e32 v10, v191, v10, vcc
	v_cmp_lt_u32_e32 vcc, s67, v33
	v_add_u32_e32 v33, 0xffffffb2, v32
	s_nop 0
	v_cndmask_b32_e32 v27, v191, v27, vcc
	v_cmp_lt_u32_e32 vcc, s67, v33
	v_add_u32_e32 v33, 0xffffff97, v32
	s_nop 0
	v_cndmask_b32_e32 v11, v191, v11, vcc
	v_cmp_lt_u32_e32 vcc, s67, v33
	v_add_u32_e32 v33, 0xffffffb7, v32
	s_nop 0
	v_cndmask_b32_e32 v28, v191, v28, vcc
	v_cmp_lt_u32_e32 vcc, s67, v33
	v_add_u32_e32 v33, 0xffffff98, v32
	s_nop 0
	v_cndmask_b32_e32 v12, v191, v12, vcc
	v_cmp_lt_u32_e32 vcc, s67, v33
	v_add_u32_e32 v33, 0xffffffb8, v32
	s_nop 0
	v_cndmask_b32_e32 v29, v191, v29, vcc
	v_cmp_lt_u32_e32 vcc, s67, v33
	v_add_u32_e32 v33, 0xffffff99, v32
	s_nop 0
	v_cndmask_b32_e32 v13, v191, v13, vcc
	v_cmp_lt_u32_e32 vcc, s67, v33
	v_add_u32_e32 v33, 0xffffffb9, v32
	s_nop 0
	v_cndmask_b32_e32 v30, v191, v30, vcc
	v_cmp_lt_u32_e32 vcc, s67, v33
	v_add_u32_e32 v33, 0xffffff9a, v32
	v_add_u32_e32 v32, 0xffffffba, v32
	v_cndmask_b32_e32 v14, v191, v14, vcc
	v_cmp_lt_u32_e32 vcc, s67, v33
	s_nop 1
	v_cndmask_b32_e32 v31, v191, v31, vcc
	v_cmp_lt_u32_e32 vcc, s67, v32
	s_nop 1
	v_cndmask_b32_e32 v15, v191, v15, vcc

.LBB0_190:
	s_add_i32 s4, s33, -3
	ds_read_b128 v[80:83], v211 offset:49152
	ds_read_b128 v[84:87], v212 offset:49152
	ds_read_b128 v[138:141], v203 offset:53248
	ds_read_b128 v[142:145], v204 offset:53248
	ds_read_b128 v[230:233], v213 offset:49152
	ds_read_b128 v[234:237], v214 offset:49152
	ds_read_b128 v[238:241], v205 offset:53248
	ds_read_b128 v[242:245], v206 offset:53248
	s_waitcnt lgkmcnt(6)
	v_mfma_f32_32x32x64_f8f6f4 v[96:111], v[80:87], v[122:129], 0
	s_waitcnt lgkmcnt(4)
	v_mfma_f32_32x32x64_f8f6f4 v[80:95], v[138:145], v[122:129], 0
	s_waitcnt lgkmcnt(2)
	v_mfma_f32_32x32x64_f8f6f4 v[96:111], v[230:237], v[130:137], v[96:111]
	s_waitcnt lgkmcnt(0)
	v_mfma_f32_32x32x64_f8f6f4 v[80:95], v[238:245], v[130:137], v[80:95]
	s_cmp_lt_i32 s4, s11
	s_cselect_b64 s[4:5], -1, 0
	s_or_b64 s[4:5], s[98:99], s[4:5]
	s_and_b64 vcc, exec, s[4:5]
	s_cbranch_vccnz .LBB0_193
	s_add_i32 s4, s12, s13
	s_add_i32 s4, s4, -2
	s_cmp_gt_u32 s4, 0xffffff5c
	s_cbranch_scc1 .LBB0_193
	v_add_u32_e32 v187, s12, v209
	v_add_u32_e32 v217, 0xffffffbf, v187
	v_cmp_lt_u32_e32 vcc, s67, v217
	v_subrev_u32_e32 v217, 33, v187
	s_nop 0
	v_cndmask_b32_e32 v96, v191, v96, vcc
	v_cmp_lt_u32_e32 vcc, s67, v217
	v_subrev_u32_e32 v217, 64, v187
	s_nop 0
	v_cndmask_b32_e32 v80, v191, v80, vcc
	v_cmp_lt_u32_e32 vcc, s67, v217
	v_subrev_u32_e32 v217, 32, v187
	s_nop 0
	v_cndmask_b32_e32 v97, v191, v97, vcc
	v_cmp_lt_u32_e32 vcc, s67, v217
	v_subrev_u32_e32 v217, 63, v187
	s_nop 0
	v_cndmask_b32_e32 v81, v191, v81, vcc
	v_cmp_lt_u32_e32 vcc, s67, v217
	v_subrev_u32_e32 v217, 31, v187
	s_nop 0
	v_cndmask_b32_e32 v98, v191, v98, vcc
	v_cmp_lt_u32_e32 vcc, s67, v217
	v_subrev_u32_e32 v217, 62, v187
	s_nop 0
	v_cndmask_b32_e32 v82, v191, v82, vcc
	v_cmp_lt_u32_e32 vcc, s67, v217
	v_subrev_u32_e32 v217, 30, v187
	s_nop 0
	v_cndmask_b32_e32 v99, v191, v99, vcc
	v_cmp_lt_u32_e32 vcc, s67, v217
	v_subrev_u32_e32 v217, 57, v187
	s_nop 0
	v_cndmask_b32_e32 v83, v191, v83, vcc
	v_cmp_lt_u32_e32 vcc, s67, v217
	v_subrev_u32_e32 v217, 25, v187
	s_nop 0
	v_cndmask_b32_e32 v100, v191, v100, vcc
	v_cmp_lt_u32_e32 vcc, s67, v217
	v_subrev_u32_e32 v217, 56, v187
	s_nop 0
	v_cndmask_b32_e32 v84, v191, v84, vcc
	v_cmp_lt_u32_e32 vcc, s67, v217
	v_subrev_u32_e32 v217, 24, v187
	s_nop 0
	v_cndmask_b32_e32 v101, v191, v101, vcc
	v_cmp_lt_u32_e32 vcc, s67, v217
	v_subrev_u32_e32 v217, 55, v187
	s_nop 0
	v_cndmask_b32_e32 v85, v191, v85, vcc
	v_cmp_lt_u32_e32 vcc, s67, v217
	v_subrev_u32_e32 v217, 23, v187
	s_nop 0
	v_cndmask_b32_e32 v102, v191, v102, vcc
	v_cmp_lt_u32_e32 vcc, s67, v217
	v_subrev_u32_e32 v217, 54, v187
	s_nop 0
	v_cndmask_b32_e32 v86, v191, v86, vcc
	v_cmp_lt_u32_e32 vcc, s67, v217
	v_subrev_u32_e32 v217, 22, v187
	s_nop 0
	v_cndmask_b32_e32 v103, v191, v103, vcc
	v_cmp_lt_u32_e32 vcc, s67, v217
	v_subrev_u32_e32 v217, 49, v187
	s_nop 0
	v_cndmask_b32_e32 v87, v191, v87, vcc
	v_cmp_lt_u32_e32 vcc, s67, v217
	v_subrev_u32_e32 v217, 17, v187
	s_nop 0
	v_cndmask_b32_e32 v104, v191, v104, vcc
	v_cmp_lt_u32_e32 vcc, s67, v217
	v_subrev_u32_e32 v217, 48, v187
	s_nop 0
	v_cndmask_b32_e32 v88, v191, v88, vcc
	v_cmp_lt_u32_e32 vcc, s67, v217
	v_add_u32_e32 v217, -16, v187
	s_nop 0
	v_cndmask_b32_e32 v105, v191, v105, vcc
	v_cmp_lt_u32_e32 vcc, s67, v217
	v_subrev_u32_e32 v217, 47, v187
	s_nop 0
	v_cndmask_b32_e32 v89, v191, v89, vcc
	v_cmp_lt_u32_e32 vcc, s67, v217
	v_add_u32_e32 v217, -15, v187
	s_nop 0
	v_cndmask_b32_e32 v106, v191, v106, vcc
	v_cmp_lt_u32_e32 vcc, s67, v217
	v_subrev_u32_e32 v217, 46, v187
	s_nop 0
	v_cndmask_b32_e32 v90, v191, v90, vcc
	v_cmp_lt_u32_e32 vcc, s67, v217
	v_add_u32_e32 v217, -14, v187
	s_nop 0
	v_cndmask_b32_e32 v107, v191, v107, vcc
	v_cmp_lt_u32_e32 vcc, s67, v217
	v_subrev_u32_e32 v217, 41, v187
	s_nop 0
	v_cndmask_b32_e32 v91, v191, v91, vcc
	v_cmp_lt_u32_e32 vcc, s67, v217
	v_add_u32_e32 v217, -9, v187
	s_nop 0
	v_cndmask_b32_e32 v108, v191, v108, vcc
	v_cmp_lt_u32_e32 vcc, s67, v217
	v_subrev_u32_e32 v217, 40, v187
	s_nop 0
	v_cndmask_b32_e32 v92, v191, v92, vcc
	v_cmp_lt_u32_e32 vcc, s67, v217
	v_add_u32_e32 v217, -8, v187
	s_nop 0
	v_cndmask_b32_e32 v109, v191, v109, vcc
	v_cmp_lt_u32_e32 vcc, s67, v217
	v_subrev_u32_e32 v217, 39, v187
	s_nop 0
	v_cndmask_b32_e32 v93, v191, v93, vcc
	v_cmp_lt_u32_e32 vcc, s67, v217
	v_add_u32_e32 v217, -7, v187
	s_nop 0
	v_cndmask_b32_e32 v110, v191, v110, vcc
	v_cmp_lt_u32_e32 vcc, s67, v217
	v_subrev_u32_e32 v217, 38, v187
	v_add_u32_e32 v187, -6, v187
	v_cndmask_b32_e32 v94, v191, v94, vcc
	v_cmp_lt_u32_e32 vcc, s67, v217
	s_nop 1
	v_cndmask_b32_e32 v111, v191, v111, vcc
	v_cmp_lt_u32_e32 vcc, s67, v187
	s_nop 1
	v_cndmask_b32_e32 v95, v191, v95, vcc
.LBB0_193:
	s_add_i32 s4, s33, -1
	v_exp_f32_e32 v156, v156
	v_exp_f32_e32 v157, v157
	s_cmp_lt_i32 s4, s11
	v_exp_f32_e32 v160, v160
	v_exp_f32_e32 v161, v161
	s_cselect_b32 s5, 0, s11
	s_cselect_b32 s9, s91, s95
	s_cselect_b32 s8, s90, s94
	s_cselect_b32 s29, s92, s96
	s_cselect_b32 s34, s93, s97
	s_sub_i32 s20, s4, s5
	s_lshl_b64 s[4:5], s[20:21], 15
	v_exp_f32_e32 v154, v154
	v_exp_f32_e32 v155, v155
	v_cvt_pk_fp8_f32 v145, v156, v157
	s_add_u32 s8, s8, s4
	v_exp_f32_e32 v158, v158
	v_exp_f32_e32 v159, v159
	v_cvt_pk_fp8_f32 v144, v160, v161
	s_addc_u32 s9, s9, s5
	s_add_u32 s4, s29, s4
	s_addc_u32 s5, s34, s5
	v_cvt_pk_fp8_f32 v145, v154, v155 op_sel:[0,0,1]
	v_lshl_add_u64 v[154:155], s[4:5], 0, v[168:169]
	v_cvt_pk_fp8_f32 v144, v158, v159 op_sel:[0,0,1]
	global_load_dwordx4 v[158:161], v[154:155], off
	v_lshl_add_u64 v[154:155], s[8:9], 0, v[170:171]
	global_load_dwordx4 v[154:157], v[154:155], off
	v_exp_f32_e32 v178, v178
	v_exp_f32_e32 v179, v179
	v_exp_f32_e32 v174, v174
	v_exp_f32_e32 v175, v175
	v_cvt_pk_fp8_f32 v138, v228, v229
	v_exp_f32_e32 v176, v176
	v_exp_f32_e32 v177, v177
	v_exp_f32_e32 v172, v172
	v_exp_f32_e32 v173, v173
	v_cvt_pk_fp8_f32 v138, v221, v223 op_sel:[0,0,1]
	v_cvt_pk_fp8_f32 v142, v178, v179
	v_cvt_pk_fp8_f32 v139, v226, v227
	v_cvt_pk_fp8_f32 v143, v174, v175
	v_cvt_pk_fp8_f32 v140, v220, v222
	v_cvt_pk_fp8_f32 v141, v185, v219
	v_cvt_pk_fp8_f32 v142, v176, v177 op_sel:[0,0,1]
	v_cvt_pk_fp8_f32 v139, v224, v225 op_sel:[0,0,1]
	v_cvt_pk_fp8_f32 v143, v172, v173 op_sel:[0,0,1]
	v_cvt_pk_fp8_f32 v140, v181, v182 op_sel:[0,0,1]
	v_cvt_pk_fp8_f32 v141, v183, v184 op_sel:[0,0,1]
	ds_read_b128 v[172:175], v215
	ds_read_b128 v[220:223], v215 offset:2048
	ds_read_b128 v[176:179], v216
	ds_read_b128 v[224:227], v216 offset:2048
	ds_read_b128 v[228:231], v215 offset:4096
	ds_read_b128 v[236:239], v215 offset:6144
	ds_read_b128 v[232:235], v216 offset:4096
	ds_read_b128 v[240:243], v216 offset:6144
	s_waitcnt lgkmcnt(5)
	s_nop 3
	v_mfma_f32_32x32x64_f8f6f4 v[48:63], v[138:145], v[172:179], v[48:63]
	s_waitcnt lgkmcnt(4)
	v_mfma_f32_32x32x64_f8f6f4 v[32:47], v[138:145], v[220:227], v[32:47]
	s_waitcnt lgkmcnt(1)
	v_mfma_f32_32x32x64_f8f6f4 v[16:31], v[138:145], v[228:235], v[16:31]
	s_waitcnt lgkmcnt(0)
	v_mfma_f32_32x32x64_f8f6f4 v[0:15], v[138:145], v[236:243], v[0:15]
	v_mfma_f32_32x32x64_f8f6f4 v[64:79], v[138:145], v[114:121], v[64:79]
	v_max_f32_e32 v138, v97, v97
	v_max_f32_e32 v139, v96, v96
	v_max_f32_e32 v138, v139, v138
	v_max3_f32 v138, v138, v98, v99
	v_max3_f32 v138, v138, v100, v101
	v_max3_f32 v138, v138, v102, v103
	v_max3_f32 v138, v138, v104, v105
	v_max3_f32 v138, v138, v106, v107
	v_max3_f32 v138, v138, v108, v109
	v_max3_f32 v138, v138, v110, v111
	v_max3_f32 v138, v138, v80, v81
	v_max3_f32 v138, v138, v82, v83
	v_max3_f32 v138, v138, v84, v85
	v_max3_f32 v138, v138, v86, v87
	v_max3_f32 v138, v138, v88, v89
	v_max3_f32 v138, v138, v90, v91
	v_max3_f32 v138, v138, v92, v93
	v_max3_f32 v138, v138, v94, v95
	v_mov_b32_e32 v139, v138
	s_nop 1
	v_permlane32_swap_b32_e32 v138, v139
	v_max_f32_e32 v139, v139, v139
	v_max_f32_e32 v138, v138, v138
	v_max_f32_e32 v138, v138, v139
	v_sub_f32_e32 v139, v138, v180
	v_cmp_ge_f32_e32 vcc, s63, v139
	s_cmp_lg_u64 vcc, exec
	s_cselect_b64 s[8:9], -1, 0
	s_mov_b64 vcc, s[8:9]
	s_cbranch_vccnz .LBB0_214
	v_mov_b32_e32 v138, v166

.LBB0_200:
	v_pk_fma_f32 v[96:97], v[96:97], s[62:63], v[138:139] op_sel_hi:[1,0,0]
	v_pk_fma_f32 v[166:167], v[80:81], s[62:63], v[138:139] op_sel_hi:[1,0,0]
	v_pk_fma_f32 v[80:81], v[98:99], s[62:63], v[138:139] op_sel_hi:[1,0,0]
	v_pk_fma_f32 v[172:173], v[82:83], s[62:63], v[138:139] op_sel_hi:[1,0,0]
	v_pk_fma_f32 v[82:83], v[100:101], s[62:63], v[138:139] op_sel_hi:[1,0,0]
	v_pk_fma_f32 v[174:175], v[84:85], s[62:63], v[138:139] op_sel_hi:[1,0,0]
	v_pk_fma_f32 v[84:85], v[102:103], s[62:63], v[138:139] op_sel_hi:[1,0,0]
	v_pk_fma_f32 v[176:177], v[86:87], s[62:63], v[138:139] op_sel_hi:[1,0,0]
	v_pk_fma_f32 v[86:87], v[104:105], s[62:63], v[138:139] op_sel_hi:[1,0,0]
	v_pk_fma_f32 v[178:179], v[88:89], s[62:63], v[138:139] op_sel_hi:[1,0,0]
	v_pk_fma_f32 v[88:89], v[106:107], s[62:63], v[138:139] op_sel_hi:[1,0,0]
	v_pk_fma_f32 v[98:99], v[108:109], s[62:63], v[138:139] op_sel_hi:[1,0,0]
	v_pk_fma_f32 v[100:101], v[110:111], s[62:63], v[138:139] op_sel_hi:[1,0,0]
	v_exp_f32_e32 v235, v96
	v_exp_f32_e32 v236, v97
	v_exp_f32_e32 v227, v80
	v_exp_f32_e32 v229, v81
	v_exp_f32_e32 v233, v82
	v_exp_f32_e32 v234, v83
	v_exp_f32_e32 v231, v84
	v_exp_f32_e32 v232, v85
	v_exp_f32_e32 v228, v86
	v_exp_f32_e32 v230, v87
	v_exp_f32_e32 v221, v88
	v_exp_f32_e32 v222, v89
	v_exp_f32_e32 v225, v98
	v_exp_f32_e32 v226, v99
	v_exp_f32_e32 v223, v100
	v_exp_f32_e32 v224, v101
	v_pk_fma_f32 v[184:185], v[90:91], s[62:63], v[138:139] op_sel_hi:[1,0,0]
	v_pk_fma_f32 v[182:183], v[92:93], s[62:63], v[138:139] op_sel_hi:[1,0,0]
	v_pk_fma_f32 v[180:181], v[94:95], s[62:63], v[138:139] op_sel_hi:[1,0,0]
	s_add_i32 s4, s33, -2
	s_waitcnt lgkmcnt(0)
	s_barrier
	ds_read_b128 v[80:83], v211 offset:32768
	ds_read_b128 v[84:87], v212 offset:32768
	ds_read_b128 v[138:141], v203 offset:36864
	ds_read_b128 v[142:145], v204 offset:36864
	ds_read_b128 v[238:241], v213 offset:32768
	ds_read_b128 v[242:245], v214 offset:32768
	ds_read_b128 v[246:249], v205 offset:36864
	ds_read_b128 v[250:253], v206 offset:36864
	s_waitcnt lgkmcnt(6)
	v_mfma_f32_32x32x64_f8f6f4 v[96:111], v[80:87], v[122:129], 0
	s_waitcnt lgkmcnt(4)
	v_mfma_f32_32x32x64_f8f6f4 v[80:95], v[138:145], v[122:129], 0
	s_waitcnt lgkmcnt(2)
	v_mfma_f32_32x32x64_f8f6f4 v[96:111], v[238:245], v[130:137], v[96:111]
	s_waitcnt lgkmcnt(0)
	v_mfma_f32_32x32x64_f8f6f4 v[80:95], v[246:253], v[130:137], v[80:95]
	s_cmp_lt_i32 s4, s11
	s_cselect_b64 s[4:5], -1, 0
	s_or_b64 s[4:5], s[98:99], s[4:5]
	s_and_b64 vcc, exec, s[4:5]
	s_cbranch_vccnz .LBB0_203
	s_add_i32 s4, s12, s13
	s_add_i32 s4, s4, 62
	s_cmp_gt_u32 s4, 0xffffff5c
	s_cbranch_scc1 .LBB0_203
	v_add_u32_e32 v187, s12, v209
	v_add_u32_e32 v237, -1, v187
	v_cmp_lt_u32_e32 vcc, s67, v237
	v_add_u32_e32 v237, 31, v187
	s_nop 0
	v_cndmask_b32_e32 v96, v191, v96, vcc
	v_cmp_lt_u32_e32 vcc, s67, v237
	v_add_u32_e32 v237, 32, v187
	s_nop 0
	v_cndmask_b32_e32 v80, v191, v80, vcc
	v_cmp_lt_u32_e32 vcc, s67, v187
	s_nop 1
	v_cndmask_b32_e32 v97, v191, v97, vcc
	v_cmp_lt_u32_e32 vcc, s67, v237
	v_add_u32_e32 v237, 1, v187
	s_nop 0
	v_cndmask_b32_e32 v81, v191, v81, vcc
	v_cmp_lt_u32_e32 vcc, s67, v237
	v_add_u32_e32 v237, 33, v187
	s_nop 0
	v_cndmask_b32_e32 v98, v191, v98, vcc
	v_cmp_lt_u32_e32 vcc, s67, v237
	v_add_u32_e32 v237, 2, v187
	s_nop 0
	v_cndmask_b32_e32 v82, v191, v82, vcc
	v_cmp_lt_u32_e32 vcc, s67, v237
	v_add_u32_e32 v237, 34, v187
	s_nop 0
	v_cndmask_b32_e32 v99, v191, v99, vcc
	v_cmp_lt_u32_e32 vcc, s67, v237
	v_add_u32_e32 v237, 7, v187
	s_nop 0
	v_cndmask_b32_e32 v83, v191, v83, vcc
	v_cmp_lt_u32_e32 vcc, s67, v237
	v_add_u32_e32 v237, 39, v187
	s_nop 0
	v_cndmask_b32_e32 v100, v191, v100, vcc
	v_cmp_lt_u32_e32 vcc, s67, v237
	v_add_u32_e32 v237, 8, v187
	s_nop 0
	v_cndmask_b32_e32 v84, v191, v84, vcc
	v_cmp_lt_u32_e32 vcc, s67, v237
	v_add_u32_e32 v237, 40, v187
	s_nop 0
	v_cndmask_b32_e32 v101, v191, v101, vcc
	v_cmp_lt_u32_e32 vcc, s67, v237
	v_add_u32_e32 v237, 9, v187
	s_nop 0
	v_cndmask_b32_e32 v85, v191, v85, vcc
	v_cmp_lt_u32_e32 vcc, s67, v237
	v_add_u32_e32 v237, 41, v187
	s_nop 0
	v_cndmask_b32_e32 v102, v191, v102, vcc
	v_cmp_lt_u32_e32 vcc, s67, v237
	v_add_u32_e32 v237, 10, v187
	s_nop 0
	v_cndmask_b32_e32 v86, v191, v86, vcc
	v_cmp_lt_u32_e32 vcc, s67, v237
	v_add_u32_e32 v237, 42, v187
	s_nop 0
	v_cndmask_b32_e32 v103, v191, v103, vcc
	v_cmp_lt_u32_e32 vcc, s67, v237
	v_add_u32_e32 v237, 15, v187
	s_nop 0
	v_cndmask_b32_e32 v87, v191, v87, vcc
	v_cmp_lt_u32_e32 vcc, s67, v237
	v_add_u32_e32 v237, 47, v187
	s_nop 0
	v_cndmask_b32_e32 v104, v191, v104, vcc
	v_cmp_lt_u32_e32 vcc, s67, v237
	v_add_u32_e32 v237, 16, v187
	s_nop 0
	v_cndmask_b32_e32 v88, v191, v88, vcc
	v_cmp_lt_u32_e32 vcc, s67, v237
	v_add_u32_e32 v237, 48, v187
	s_nop 0
	v_cndmask_b32_e32 v105, v191, v105, vcc
	v_cmp_lt_u32_e32 vcc, s67, v237
	v_add_u32_e32 v237, 17, v187
	s_nop 0
	v_cndmask_b32_e32 v89, v191, v89, vcc
	v_cmp_lt_u32_e32 vcc, s67, v237
	v_add_u32_e32 v237, 49, v187
	s_nop 0
	v_cndmask_b32_e32 v106, v191, v106, vcc
	v_cmp_lt_u32_e32 vcc, s67, v237
	v_add_u32_e32 v237, 18, v187
	s_nop 0
	v_cndmask_b32_e32 v90, v191, v90, vcc
	v_cmp_lt_u32_e32 vcc, s67, v237
	v_add_u32_e32 v237, 50, v187
	s_nop 0
	v_cndmask_b32_e32 v107, v191, v107, vcc
	v_cmp_lt_u32_e32 vcc, s67, v237
	v_add_u32_e32 v237, 23, v187
	s_nop 0
	v_cndmask_b32_e32 v91, v191, v91, vcc
	v_cmp_lt_u32_e32 vcc, s67, v237
	v_add_u32_e32 v237, 55, v187
	s_nop 0
	v_cndmask_b32_e32 v108, v191, v108, vcc
	v_cmp_lt_u32_e32 vcc, s67, v237
	v_add_u32_e32 v237, 24, v187
	s_nop 0
	v_cndmask_b32_e32 v92, v191, v92, vcc
	v_cmp_lt_u32_e32 vcc, s67, v237
	v_add_u32_e32 v237, 56, v187
	s_nop 0
	v_cndmask_b32_e32 v109, v191, v109, vcc
	v_cmp_lt_u32_e32 vcc, s67, v237
	v_add_u32_e32 v237, 25, v187
	s_nop 0
	v_cndmask_b32_e32 v93, v191, v93, vcc
	v_cmp_lt_u32_e32 vcc, s67, v237
	v_add_u32_e32 v237, 57, v187
	s_nop 0
	v_cndmask_b32_e32 v110, v191, v110, vcc
	v_cmp_lt_u32_e32 vcc, s67, v237
	v_add_u32_e32 v237, 26, v187
	v_add_u32_e32 v187, 58, v187
	v_cndmask_b32_e32 v94, v191, v94, vcc
	v_cmp_lt_u32_e32 vcc, s67, v237
	s_nop 1
	v_cndmask_b32_e32 v111, v191, v111, vcc
	v_cmp_lt_u32_e32 vcc, s67, v187
	s_nop 1
	v_cndmask_b32_e32 v95, v191, v95, vcc

.LBB0_205:
	v_exp_f32_e32 v166, v166
	v_exp_f32_e32 v167, v167
	v_exp_f32_e32 v174, v174
	v_exp_f32_e32 v175, v175
	v_exp_f32_e32 v178, v178
	v_exp_f32_e32 v179, v179
	v_exp_f32_e32 v182, v182
	v_exp_f32_e32 v183, v183
	v_cvt_pk_fp8_f32 v138, v235, v236
	v_exp_f32_e32 v172, v172
	v_exp_f32_e32 v173, v173
	v_exp_f32_e32 v176, v176
	v_exp_f32_e32 v177, v177
	v_exp_f32_e32 v184, v184
	v_exp_f32_e32 v185, v185
	v_exp_f32_e32 v180, v180
	v_exp_f32_e32 v181, v181
	v_cvt_pk_fp8_f32 v142, v166, v167
	v_cvt_pk_fp8_f32 v139, v233, v234
	v_cvt_pk_fp8_f32 v143, v174, v175
	v_cvt_pk_fp8_f32 v138, v227, v229 op_sel:[0,0,1]
	v_cvt_pk_fp8_f32 v140, v228, v230
	v_cvt_pk_fp8_f32 v144, v178, v179
	v_cvt_pk_fp8_f32 v141, v225, v226
	v_cvt_pk_fp8_f32 v145, v182, v183
	v_cvt_pk_fp8_f32 v142, v172, v173 op_sel:[0,0,1]
	v_cvt_pk_fp8_f32 v139, v231, v232 op_sel:[0,0,1]
	v_cvt_pk_fp8_f32 v143, v176, v177 op_sel:[0,0,1]
	v_cvt_pk_fp8_f32 v140, v221, v222 op_sel:[0,0,1]
	v_cvt_pk_fp8_f32 v144, v184, v185 op_sel:[0,0,1]
	v_cvt_pk_fp8_f32 v141, v223, v224 op_sel:[0,0,1]
	v_cvt_pk_fp8_f32 v145, v180, v181 op_sel:[0,0,1]
	ds_read_b128 v[172:175], v215 offset:16384
	ds_read_b128 v[222:225], v215 offset:18432
	ds_read_b128 v[176:179], v216 offset:16384
	ds_read_b128 v[226:229], v216 offset:18432
	ds_read_b128 v[230:233], v215 offset:20480
	ds_read_b128 v[238:241], v215 offset:22528
	ds_read_b128 v[234:237], v216 offset:20480
	ds_read_b128 v[242:245], v216 offset:22528
	s_waitcnt lgkmcnt(5)
	s_nop 3
	v_mfma_f32_32x32x64_f8f6f4 v[48:63], v[138:145], v[172:179], v[48:63]
	s_waitcnt lgkmcnt(4)
	v_mfma_f32_32x32x64_f8f6f4 v[32:47], v[138:145], v[222:229], v[32:47]
	s_waitcnt lgkmcnt(1)
	v_mfma_f32_32x32x64_f8f6f4 v[16:31], v[138:145], v[230:237], v[16:31]
	s_waitcnt lgkmcnt(0)
	v_mfma_f32_32x32x64_f8f6f4 v[0:15], v[138:145], v[238:245], v[0:15]
	v_mfma_f32_32x32x64_f8f6f4 v[64:79], v[138:145], v[114:121], v[64:79]
	v_max_f32_e32 v138, v97, v97
	v_max_f32_e32 v139, v96, v96
	v_max_f32_e32 v138, v139, v138
	v_max3_f32 v138, v138, v98, v99
	v_max3_f32 v138, v138, v100, v101
	v_max3_f32 v138, v138, v102, v103
	v_max3_f32 v138, v138, v104, v105
	v_max3_f32 v138, v138, v106, v107
	v_max3_f32 v138, v138, v108, v109
	v_max3_f32 v138, v138, v110, v111
	v_max3_f32 v138, v138, v80, v81
	v_max3_f32 v138, v138, v82, v83
	v_max3_f32 v138, v138, v84, v85
	v_max3_f32 v138, v138, v86, v87
	v_max3_f32 v138, v138, v88, v89
	v_max3_f32 v138, v138, v90, v91
	v_max3_f32 v138, v138, v92, v93
	v_max3_f32 v138, v138, v94, v95
	v_mov_b32_e32 v139, v138
	s_nop 1
	v_permlane32_swap_b32_e32 v138, v139
	v_max_f32_e32 v139, v139, v139
	v_max_f32_e32 v138, v138, v138
	v_max_f32_e32 v138, v138, v139
	v_sub_f32_e32 v139, v138, v219
	v_cmp_ge_f32_e32 vcc, s63, v139
	s_cmp_lg_u64 vcc, exec
	s_cselect_b64 s[8:9], -1, 0
	s_mov_b64 vcc, s[8:9]
	s_cbranch_vccnz .LBB0_215
	v_mov_b32_e32 v138, v220

.LBB0_218:
	v_add_u32_e32 v81, 0, v198
	v_add_u32_e32 v90, 0, v197
	v_add_u32_e32 v82, v81, v192
	v_add_u32_e32 v86, v90, v192
	v_add_u32_e32 v81, v81, v80
	ds_read_b128 v[82:85], v82 offset:49152
	ds_read_b128 v[86:89], v86 offset:49152
	v_add_u32_e32 v90, v90, v80
	ds_read_b128 v[138:141], v81 offset:49152
	ds_read_b128 v[142:145], v90 offset:49152
	v_add_u32_e32 v81, 0, v196
	v_add_u32_e32 v90, v81, v192
	v_add_u32_e32 v91, 0, v195
	v_add_u32_e32 v81, v81, v80
	v_add_u32_e32 v92, v91, v192
	ds_read_b128 v[146:149], v90 offset:49152
	ds_read_b128 v[150:153], v92 offset:49152
	v_add_u32_e32 v80, v91, v80
	ds_read_b128 v[202:205], v81 offset:49152
	ds_read_b128 v[206:209], v80 offset:49152
	s_waitcnt lgkmcnt(6)
	v_mfma_f32_32x32x64_f8f6f4 v[96:111], v[82:89], v[122:129], 0
	s_waitcnt lgkmcnt(4)
	v_mfma_f32_32x32x64_f8f6f4 v[80:95], v[138:145], v[122:129], 0
	s_waitcnt lgkmcnt(2)
	v_mfma_f32_32x32x64_f8f6f4 v[96:111], v[146:153], v[130:137], v[96:111]
	s_waitcnt lgkmcnt(0)
	v_mfma_f32_32x32x64_f8f6f4 v[80:95], v[202:209], v[130:137], v[80:95]
	s_cmp_gt_i32 s61, 0
	s_cselect_b64 s[4:5], -1, 0
	s_and_b64 s[4:5], s[4:5], s[22:23]
	s_and_b64 vcc, exec, s[4:5]
	s_cbranch_vccz .LBB0_221
	s_lshl_b32 s4, s61, 6
	s_add_i32 s5, s4, s52
	s_add_i32 s5, s5, s18
	s_addk_i32 s5, 0xff7e
	s_cmp_gt_u32 s5, 0xffffff5c
	s_cbranch_scc1 .LBB0_221
	s_sub_i32 s4, s4, 64
	v_lshl_or_b32 v130, v194, 2, s4
	v_add_u32_e32 v130, v130, v165
	v_add_u32_e32 v131, 0xffffff7f, v130
	v_cmp_lt_u32_e32 vcc, s67, v131
	v_add_u32_e32 v131, 0xffffff9f, v130
	s_nop 0
	v_cndmask_b32_e32 v96, v191, v96, vcc
	v_cmp_lt_u32_e32 vcc, s67, v131
	v_add_u32_e32 v131, 0xffffff80, v130
	s_nop 0
	v_cndmask_b32_e32 v80, v191, v80, vcc
	v_cmp_lt_u32_e32 vcc, s67, v131
	v_add_u32_e32 v131, 0xffffffa0, v130
	s_nop 0
	v_cndmask_b32_e32 v97, v191, v97, vcc
	v_cmp_lt_u32_e32 vcc, s67, v131
	v_add_u32_e32 v131, 0xffffff81, v130
	s_nop 0
	v_cndmask_b32_e32 v81, v191, v81, vcc
	v_cmp_lt_u32_e32 vcc, s67, v131
	v_add_u32_e32 v131, 0xffffffa1, v130
	s_nop 0
	v_cndmask_b32_e32 v98, v191, v98, vcc
	v_cmp_lt_u32_e32 vcc, s67, v131
	v_add_u32_e32 v131, 0xffffff82, v130
	s_nop 0
	v_cndmask_b32_e32 v82, v191, v82, vcc
	v_cmp_lt_u32_e32 vcc, s67, v131
	v_add_u32_e32 v131, 0xffffffa2, v130
	s_nop 0
	v_cndmask_b32_e32 v99, v191, v99, vcc
	v_cmp_lt_u32_e32 vcc, s67, v131
	v_add_u32_e32 v131, 0xffffff87, v130
	s_nop 0
	v_cndmask_b32_e32 v83, v191, v83, vcc
	v_cmp_lt_u32_e32 vcc, s67, v131
	v_add_u32_e32 v131, 0xffffffa7, v130
	s_nop 0
	v_cndmask_b32_e32 v100, v191, v100, vcc
	v_cmp_lt_u32_e32 vcc, s67, v131
	v_add_u32_e32 v131, 0xffffff88, v130
	s_nop 0
	v_cndmask_b32_e32 v84, v191, v84, vcc
	v_cmp_lt_u32_e32 vcc, s67, v131
	v_add_u32_e32 v131, 0xffffffa8, v130
	s_nop 0
	v_cndmask_b32_e32 v101, v191, v101, vcc
	v_cmp_lt_u32_e32 vcc, s67, v131
	v_add_u32_e32 v131, 0xffffff89, v130
	s_nop 0
	v_cndmask_b32_e32 v85, v191, v85, vcc
	v_cmp_lt_u32_e32 vcc, s67, v131
	v_add_u32_e32 v131, 0xffffffa9, v130
	s_nop 0
	v_cndmask_b32_e32 v102, v191, v102, vcc
	v_cmp_lt_u32_e32 vcc, s67, v131
	v_add_u32_e32 v131, 0xffffff8a, v130
	s_nop 0
	v_cndmask_b32_e32 v86, v191, v86, vcc
	v_cmp_lt_u32_e32 vcc, s67, v131
	v_add_u32_e32 v131, 0xffffffaa, v130
	s_nop 0
	v_cndmask_b32_e32 v103, v191, v103, vcc
	v_cmp_lt_u32_e32 vcc, s67, v131
	v_add_u32_e32 v131, 0xffffff8f, v130
	s_nop 0
	v_cndmask_b32_e32 v87, v191, v87, vcc
	v_cmp_lt_u32_e32 vcc, s67, v131
	v_add_u32_e32 v131, 0xffffffaf, v130
	s_nop 0
	v_cndmask_b32_e32 v104, v191, v104, vcc
	v_cmp_lt_u32_e32 vcc, s67, v131
	v_add_u32_e32 v131, 0xffffff90, v130
	s_nop 0
	v_cndmask_b32_e32 v88, v191, v88, vcc
	v_cmp_lt_u32_e32 vcc, s67, v131
	v_add_u32_e32 v131, 0xffffffb0, v130
	s_nop 0
	v_cndmask_b32_e32 v105, v191, v105, vcc
	v_cmp_lt_u32_e32 vcc, s67, v131
	v_add_u32_e32 v131, 0xffffff91, v130
	s_nop 0
	v_cndmask_b32_e32 v89, v191, v89, vcc
	v_cmp_lt_u32_e32 vcc, s67, v131
	v_add_u32_e32 v131, 0xffffffb1, v130
	s_nop 0
	v_cndmask_b32_e32 v106, v191, v106, vcc
	v_cmp_lt_u32_e32 vcc, s67, v131
	v_add_u32_e32 v131, 0xffffff92, v130
	s_nop 0
	v_cndmask_b32_e32 v90, v191, v90, vcc
	v_cmp_lt_u32_e32 vcc, s67, v131
	v_add_u32_e32 v131, 0xffffffb2, v130
	s_nop 0
	v_cndmask_b32_e32 v107, v191, v107, vcc
	v_cmp_lt_u32_e32 vcc, s67, v131
	v_add_u32_e32 v131, 0xffffff97, v130
	s_nop 0
	v_cndmask_b32_e32 v91, v191, v91, vcc
	v_cmp_lt_u32_e32 vcc, s67, v131
	v_add_u32_e32 v131, 0xffffffb7, v130
	s_nop 0
	v_cndmask_b32_e32 v108, v191, v108, vcc
	v_cmp_lt_u32_e32 vcc, s67, v131
	v_add_u32_e32 v131, 0xffffff98, v130
	s_nop 0
	v_cndmask_b32_e32 v92, v191, v92, vcc
	v_cmp_lt_u32_e32 vcc, s67, v131
	v_add_u32_e32 v131, 0xffffffb8, v130
	s_nop 0
	v_cndmask_b32_e32 v109, v191, v109, vcc
	v_cmp_lt_u32_e32 vcc, s67, v131
	v_add_u32_e32 v131, 0xffffff99, v130
	s_nop 0
	v_cndmask_b32_e32 v93, v191, v93, vcc
	v_cmp_lt_u32_e32 vcc, s67, v131
	v_add_u32_e32 v131, 0xffffffb9, v130
	s_nop 0
	v_cndmask_b32_e32 v110, v191, v110, vcc
	v_cmp_lt_u32_e32 vcc, s67, v131
	v_add_u32_e32 v131, 0xffffff9a, v130
	v_add_u32_e32 v130, 0xffffffba, v130
	v_cndmask_b32_e32 v94, v191, v94, vcc
	v_cmp_lt_u32_e32 vcc, s67, v131
	s_nop 1
	v_cndmask_b32_e32 v111, v191, v111, vcc
	v_cmp_lt_u32_e32 vcc, s67, v130
	s_nop 1
	v_cndmask_b32_e32 v95, v191, v95, vcc
.LBB0_221:
	v_exp_f32_e32 v130, v178
	v_exp_f32_e32 v131, v179
	v_exp_f32_e32 v134, v174
	v_exp_f32_e32 v135, v175
	v_exp_f32_e32 v138, v160
	v_exp_f32_e32 v139, v161
	v_exp_f32_e32 v142, v156
	v_exp_f32_e32 v143, v157
	v_exp_f32_e32 v132, v176
	v_exp_f32_e32 v133, v177
	v_exp_f32_e32 v136, v172
	v_exp_f32_e32 v137, v173
	v_exp_f32_e32 v140, v158
	v_exp_f32_e32 v141, v159
	v_exp_f32_e32 v144, v154
	v_exp_f32_e32 v145, v155
	v_cvt_pk_fp8_f32 v126, v130, v131
	v_cvt_pk_fp8_f32 v127, v134, v135
	v_cvt_pk_fp8_f32 v128, v138, v139
	v_cvt_pk_fp8_f32 v129, v142, v143
	v_lshlrev_b32_e32 v130, 4, v200
	v_lshlrev_b32_e32 v131, 4, v201
	v_add_u32_e32 v130, v199, v130
	v_cvt_pk_fp8_f32 v122, v228, v229
	v_cvt_pk_fp8_f32 v123, v226, v227
	v_cvt_pk_fp8_f32 v126, v132, v133 op_sel:[0,0,1]
	v_cvt_pk_fp8_f32 v127, v136, v137 op_sel:[0,0,1]
	v_cvt_pk_fp8_f32 v128, v140, v141 op_sel:[0,0,1]
	v_cvt_pk_fp8_f32 v129, v144, v145 op_sel:[0,0,1]
	v_add_u32_e32 v131, v199, v131
	ds_read_b128 v[132:135], v130
	ds_read_b128 v[140:143], v130 offset:2048
	ds_read_b128 v[136:139], v131
	ds_read_b128 v[144:147], v131 offset:2048
	ds_read_b128 v[148:151], v130 offset:4096
	ds_read_b128 v[168:171], v130 offset:6144
	ds_read_b128 v[152:155], v131 offset:4096
	ds_read_b128 v[172:175], v131 offset:6144
	v_cvt_pk_fp8_f32 v124, v220, v222
	v_cvt_pk_fp8_f32 v125, v185, v219
	v_cvt_pk_fp8_f32 v122, v221, v223 op_sel:[0,0,1]
	v_cvt_pk_fp8_f32 v123, v224, v225 op_sel:[0,0,1]
	v_cvt_pk_fp8_f32 v124, v181, v182 op_sel:[0,0,1]
	v_cvt_pk_fp8_f32 v125, v183, v184 op_sel:[0,0,1]
	s_mov_b64 s[4:5], -1
	s_waitcnt lgkmcnt(5)
	s_nop 3
	v_mfma_f32_32x32x64_f8f6f4 v[48:63], v[122:129], v[132:139], v[48:63]
	s_waitcnt lgkmcnt(4)
	v_mfma_f32_32x32x64_f8f6f4 v[32:47], v[122:129], v[140:147], v[32:47]
	s_waitcnt lgkmcnt(1)
	v_mfma_f32_32x32x64_f8f6f4 v[16:31], v[122:129], v[148:155], v[16:31]
	s_waitcnt lgkmcnt(0)
	v_mfma_f32_32x32x64_f8f6f4 v[0:15], v[122:129], v[168:175], v[0:15]
	v_mfma_f32_32x32x64_f8f6f4 v[64:79], v[122:129], v[114:121], v[64:79]
	s_nop 15
	s_nop 7
	v_max_f32_e32 v122, v97, v97
	v_max_f32_e32 v123, v96, v96
	v_max_f32_e32 v122, v123, v122
	v_max3_f32 v122, v122, v98, v99
	v_max3_f32 v122, v122, v100, v101
	v_max3_f32 v122, v122, v102, v103
	v_max3_f32 v122, v122, v104, v105
	v_max3_f32 v122, v122, v106, v107
	v_max3_f32 v122, v122, v108, v109
	v_max3_f32 v122, v122, v110, v111
	v_max3_f32 v122, v122, v80, v81
	v_max3_f32 v122, v122, v82, v83
	v_max3_f32 v122, v122, v84, v85
	v_max3_f32 v122, v122, v86, v87
	v_max3_f32 v122, v122, v88, v89
	v_max3_f32 v122, v122, v90, v91
	v_max3_f32 v122, v122, v92, v93
	v_max3_f32 v122, v122, v94, v95
	v_mov_b32_e32 v123, v122
	s_nop 1
	v_permlane32_swap_b32_e32 v122, v123
	v_max_f32_e32 v123, v123, v123
	v_max_f32_e32 v122, v122, v122
	v_max_f32_e32 v124, v122, v123
	v_sub_f32_e32 v122, v124, v180
	v_cmp_ge_f32_e32 vcc, s63, v122
	s_cmp_lg_u64 vcc, exec
	s_cselect_b64 s[6:7], -1, 0
	s_mov_b64 vcc, s[6:7]
	s_cbranch_vccnz .LBB0_237
	s_andn2_b64 vcc, exec, s[4:5]
	s_cbranch_vccnz .LBB0_224

.LBB0_228:
	v_pk_fma_f32 v[96:97], v[96:97], s[62:63], v[166:167] op_sel_hi:[1,0,0]
	v_pk_fma_f32 v[80:81], v[80:81], s[62:63], v[166:167] op_sel_hi:[1,0,0]
	v_pk_fma_f32 v[98:99], v[98:99], s[62:63], v[166:167] op_sel_hi:[1,0,0]
	v_pk_fma_f32 v[100:101], v[100:101], s[62:63], v[166:167] op_sel_hi:[1,0,0]
	v_pk_fma_f32 v[84:85], v[84:85], s[62:63], v[166:167] op_sel_hi:[1,0,0]
	v_pk_fma_f32 v[102:103], v[102:103], s[62:63], v[166:167] op_sel_hi:[1,0,0]
	v_pk_fma_f32 v[126:127], v[104:105], s[62:63], v[166:167] op_sel_hi:[1,0,0]
	v_pk_fma_f32 v[88:89], v[88:89], s[62:63], v[166:167] op_sel_hi:[1,0,0]
	v_pk_fma_f32 v[128:129], v[106:107], s[62:63], v[166:167] op_sel_hi:[1,0,0]
	v_pk_fma_f32 v[132:133], v[108:109], s[62:63], v[166:167] op_sel_hi:[1,0,0]
	v_pk_fma_f32 v[92:93], v[92:93], s[62:63], v[166:167] op_sel_hi:[1,0,0]
	v_pk_fma_f32 v[134:135], v[110:111], s[62:63], v[166:167] op_sel_hi:[1,0,0]
	v_exp_f32_e32 v122, v96
	v_exp_f32_e32 v124, v97
	v_exp_f32_e32 v104, v98
	v_exp_f32_e32 v110, v100
	v_exp_f32_e32 v111, v101
	v_exp_f32_e32 v108, v102
	v_exp_f32_e32 v109, v103
	v_exp_f32_e32 v105, v126
	v_exp_f32_e32 v107, v127
	v_exp_f32_e32 v98, v128
	v_exp_f32_e32 v102, v132
	v_exp_f32_e32 v103, v133
	v_pk_fma_f32 v[96:97], v[90:91], s[62:63], v[166:167] op_sel_hi:[1,0,0]
	v_pk_fma_f32 v[90:91], v[94:95], s[62:63], v[166:167] op_sel_hi:[1,0,0]
	v_exp_f32_e32 v94, v80
	v_exp_f32_e32 v95, v81
	v_exp_f32_e32 v127, v84
	v_exp_f32_e32 v128, v85
	v_exp_f32_e32 v88, v88
	v_exp_f32_e32 v89, v89
	v_exp_f32_e32 v92, v92
	v_exp_f32_e32 v93, v93
	v_pk_fma_f32 v[82:83], v[82:83], s[62:63], v[166:167] op_sel_hi:[1,0,0]
	v_pk_fma_f32 v[86:87], v[86:87], s[62:63], v[166:167] op_sel_hi:[1,0,0]
	v_exp_f32_e32 v106, v99
	v_exp_f32_e32 v99, v129
	v_exp_f32_e32 v125, v82
	v_exp_f32_e32 v126, v83
	v_exp_f32_e32 v129, v86
	v_exp_f32_e32 v132, v87
	v_exp_f32_e32 v100, v134
	v_exp_f32_e32 v101, v135
	v_exp_f32_e32 v96, v96
	v_exp_f32_e32 v97, v97
	v_exp_f32_e32 v90, v90
	v_exp_f32_e32 v91, v91
	v_cvt_pk_fp8_f32 v80, v122, v124
	v_cvt_pk_fp8_f32 v84, v94, v95
	v_cvt_pk_fp8_f32 v81, v110, v111
	v_cvt_pk_fp8_f32 v85, v127, v128
	v_cvt_pk_fp8_f32 v82, v105, v107
	v_cvt_pk_fp8_f32 v86, v88, v89
	v_cvt_pk_fp8_f32 v83, v102, v103
	v_cvt_pk_fp8_f32 v87, v92, v93
	v_cvt_pk_fp8_f32 v80, v104, v106 op_sel:[0,0,1]
	v_cvt_pk_fp8_f32 v84, v125, v126 op_sel:[0,0,1]
	v_cvt_pk_fp8_f32 v81, v108, v109 op_sel:[0,0,1]
	v_cvt_pk_fp8_f32 v85, v129, v132 op_sel:[0,0,1]
	v_cvt_pk_fp8_f32 v82, v98, v99 op_sel:[0,0,1]
	v_cvt_pk_fp8_f32 v86, v96, v97 op_sel:[0,0,1]
	v_cvt_pk_fp8_f32 v83, v100, v101 op_sel:[0,0,1]
	v_cvt_pk_fp8_f32 v87, v90, v91 op_sel:[0,0,1]
	ds_read_b128 v[88:91], v130 offset:16384
	ds_read_b128 v[96:99], v130 offset:18432
	ds_read_b128 v[92:95], v131 offset:16384
	ds_read_b128 v[100:103], v131 offset:18432
	ds_read_b128 v[104:107], v130 offset:20480
	ds_read_b128 v[124:127], v130 offset:22528
	ds_read_b128 v[108:111], v131 offset:20480
	ds_read_b128 v[128:131], v131 offset:22528
	v_cmp_eq_u32_e32 vcc, 0, v194
	s_waitcnt lgkmcnt(5)
	s_nop 3
	v_mfma_f32_32x32x64_f8f6f4 v[48:63], v[80:87], v[88:95], v[48:63]
	s_waitcnt lgkmcnt(4)
	v_mfma_f32_32x32x64_f8f6f4 v[32:47], v[80:87], v[96:103], v[32:47]
	s_waitcnt lgkmcnt(1)
	v_mfma_f32_32x32x64_f8f6f4 v[16:31], v[80:87], v[104:111], v[16:31]
	s_waitcnt lgkmcnt(0)
	v_mfma_f32_32x32x64_f8f6f4 v[0:15], v[80:87], v[124:131], v[0:15]
	v_mfma_f32_32x32x64_f8f6f4 v[64:79], v[80:87], v[114:121], v[64:79]
	s_nop 15
	s_nop 7
	s_and_saveexec_b64 s[4:5], vcc
	s_cbranch_execz .LBB0_230
	v_readlane_b32 s6, v255, 25
	v_mov_b32_e32 v122, s35
	s_mov_b32 s8, s6
	s_mov_b32 s9, s62
	v_pk_mul_f32 v[80:81], v[122:123], s[8:9]
	v_readlane_b32 s7, v255, 26
	v_sub_f32_e32 v80, v80, v81
	v_add_f32_e32 v80, 0x40400000, v80
	v_exp_f32_e32 v80, v80
	v_writelane_b32 v255, s6, 25
	ds_write_b32 v162, v80
	s_nop 0
	v_writelane_b32 v255, s7, 26

.LBB0_300:
	ds_read_b128 v[170:173], v166
	ds_read_b128 v[174:177], v166 offset:1024
	ds_read_b128 v[178:181], v166 offset:2048
	ds_read_b128 v[182:185], v166 offset:3072
	v_add_u32_e32 v167, 0xc000, v152
	v_lshl_add_u64 v[240:241], v[138:139], 0, s[6:7]
	v_readfirstlane_b32 s5, v167
	v_lshl_add_u64 v[168:169], v[240:241], 0, s[42:43]
	s_mov_b32 m0, s5
	ds_read_b128 v[192:195], v150
	ds_read_b128 v[196:199], v150 offset:1024
	ds_read_b128 v[200:203], v149
	ds_read_b128 v[204:207], v149 offset:1024
	ds_read_b128 v[208:211], v148
	ds_read_b128 v[212:215], v148 offset:1024
	ds_read_b128 v[216:219], v147
	ds_read_b128 v[220:223], v147 offset:1024
	global_load_lds_dwordx4 v[168:169], off
	v_add_u32_e32 v168, 0xe000, v152
	v_lshl_add_u64 v[242:243], v[140:141], 0, s[6:7]
	v_readfirstlane_b32 s5, v168
	v_lshl_add_u64 v[224:225], v[242:243], 0, s[42:43]
	s_mov_b32 m0, s5
	s_nop 0
	global_load_lds_dwordx4 v[224:225], off
	s_waitcnt lgkmcnt(8)
	s_barrier
	s_waitcnt lgkmcnt(0)
	s_setprio 1
	v_mfma_f32_16x16x32_bf16 v[0:3], v[192:195], v[170:173], v[0:3]
	v_mfma_f32_16x16x32_bf16 v[4:7], v[192:195], v[178:181], v[4:7]
	v_mfma_f32_16x16x32_bf16 v[8:11], v[200:203], v[170:173], v[8:11]
	v_mfma_f32_16x16x32_bf16 v[16:19], v[200:203], v[178:181], v[16:19]
	v_mfma_f32_16x16x32_bf16 v[28:31], v[208:211], v[170:173], v[28:31]
	v_mfma_f32_16x16x32_bf16 v[40:43], v[208:211], v[178:181], v[40:43]
	v_mfma_f32_16x16x32_bf16 v[52:55], v[216:219], v[170:173], v[52:55]
	v_mfma_f32_16x16x32_bf16 v[64:67], v[216:219], v[178:181], v[64:67]
	v_mfma_f32_16x16x32_bf16 v[0:3], v[196:199], v[174:177], v[0:3]
	v_mfma_f32_16x16x32_bf16 v[4:7], v[196:199], v[182:185], v[4:7]
	v_mfma_f32_16x16x32_bf16 v[8:11], v[204:207], v[174:177], v[8:11]
	v_mfma_f32_16x16x32_bf16 v[16:19], v[204:207], v[182:185], v[16:19]
	v_mfma_f32_16x16x32_bf16 v[28:31], v[212:215], v[174:177], v[28:31]
	v_mfma_f32_16x16x32_bf16 v[40:43], v[212:215], v[182:185], v[40:43]
	v_mfma_f32_16x16x32_bf16 v[52:55], v[220:223], v[174:177], v[52:55]
	v_mfma_f32_16x16x32_bf16 v[64:67], v[220:223], v[182:185], v[64:67]
	s_setprio 0
	s_barrier
	v_lshl_add_u64 v[244:245], v[134:135], 0, s[6:7]
	v_readfirstlane_b32 s5, v146
	v_lshl_add_u64 v[246:247], v[244:245], 0, s[44:45]
	s_mov_b32 m0, s5
	v_add_u32_e32 v169, 0x2000, v146
	ds_read_b128 v[224:227], v165
	ds_read_b128 v[228:231], v165 offset:1024
	ds_read_b128 v[232:235], v165 offset:2048
	ds_read_b128 v[236:239], v165 offset:3072
	global_load_lds_dwordx4 v[246:247], off
	v_lshl_add_u64 v[246:247], v[136:137], 0, s[6:7]
	v_readfirstlane_b32 s5, v169
	v_lshl_add_u64 v[248:249], v[246:247], 0, s[44:45]
	s_mov_b32 m0, s5
	s_nop 0
	global_load_lds_dwordx4 v[248:249], off
	s_barrier
	s_waitcnt lgkmcnt(0)
	s_setprio 1
	v_mfma_f32_16x16x32_bf16 v[12:15], v[192:195], v[224:227], v[12:15]
	v_mfma_f32_16x16x32_bf16 v[20:23], v[192:195], v[232:235], v[20:23]
	v_mfma_f32_16x16x32_bf16 v[32:35], v[200:203], v[224:227], v[32:35]
	v_mfma_f32_16x16x32_bf16 v[44:47], v[200:203], v[232:235], v[44:47]
	v_mfma_f32_16x16x32_bf16 v[56:59], v[208:211], v[224:227], v[56:59]
	v_mfma_f32_16x16x32_bf16 v[68:71], v[208:211], v[232:235], v[68:71]
	v_mfma_f32_16x16x32_bf16 v[76:79], v[216:219], v[224:227], v[76:79]
	v_mfma_f32_16x16x32_bf16 v[84:87], v[216:219], v[232:235], v[84:87]
	v_mfma_f32_16x16x32_bf16 v[12:15], v[196:199], v[228:231], v[12:15]
	v_mfma_f32_16x16x32_bf16 v[20:23], v[196:199], v[236:239], v[20:23]
	v_mfma_f32_16x16x32_bf16 v[32:35], v[204:207], v[228:231], v[32:35]
	v_mfma_f32_16x16x32_bf16 v[44:47], v[204:207], v[236:239], v[44:47]
	v_mfma_f32_16x16x32_bf16 v[56:59], v[212:215], v[228:231], v[56:59]
	v_mfma_f32_16x16x32_bf16 v[68:71], v[212:215], v[236:239], v[68:71]
	v_mfma_f32_16x16x32_bf16 v[76:79], v[220:223], v[228:231], v[76:79]
	v_mfma_f32_16x16x32_bf16 v[84:87], v[220:223], v[236:239], v[84:87]
	s_setprio 0
	v_readfirstlane_b32 s5, v152
	v_lshl_add_u64 v[248:249], v[240:241], 0, s[44:45]
	s_mov_b32 m0, s5
	v_readfirstlane_b32 s5, v153
	s_barrier
	ds_read_b128 v[192:195], v150 offset:16384
	ds_read_b128 v[196:199], v150 offset:17408
	ds_read_b128 v[200:203], v149 offset:16384
	ds_read_b128 v[204:207], v149 offset:17408
	ds_read_b128 v[208:211], v148 offset:16384
	ds_read_b128 v[212:215], v148 offset:17408
	ds_read_b128 v[216:219], v147 offset:16384
	ds_read_b128 v[220:223], v147 offset:17408
	global_load_lds_dwordx4 v[248:249], off
	v_lshl_add_u64 v[248:249], v[242:243], 0, s[44:45]
	s_mov_b32 m0, s5
	s_nop 0
	global_load_lds_dwordx4 v[248:249], off
	s_barrier
	s_waitcnt lgkmcnt(0)
	s_setprio 1
	v_mfma_f32_16x16x32_bf16 v[24:27], v[192:195], v[170:173], v[24:27]
	v_mfma_f32_16x16x32_bf16 v[36:39], v[192:195], v[178:181], v[36:39]
	v_mfma_f32_16x16x32_bf16 v[48:51], v[200:203], v[170:173], v[48:51]
	v_mfma_f32_16x16x32_bf16 v[60:63], v[200:203], v[178:181], v[60:63]
	v_mfma_f32_16x16x32_bf16 v[72:75], v[208:211], v[170:173], v[72:75]
	v_mfma_f32_16x16x32_bf16 v[80:83], v[208:211], v[178:181], v[80:83]
	v_mfma_f32_16x16x32_bf16 v[88:91], v[216:219], v[170:173], v[88:91]
	v_mfma_f32_16x16x32_bf16 v[96:99], v[216:219], v[178:181], v[96:99]
	v_mfma_f32_16x16x32_bf16 v[24:27], v[196:199], v[174:177], v[24:27]
	v_mfma_f32_16x16x32_bf16 v[36:39], v[196:199], v[182:185], v[36:39]
	v_mfma_f32_16x16x32_bf16 v[48:51], v[204:207], v[174:177], v[48:51]
	v_mfma_f32_16x16x32_bf16 v[60:63], v[204:207], v[182:185], v[60:63]
	v_mfma_f32_16x16x32_bf16 v[72:75], v[212:215], v[174:177], v[72:75]
	v_mfma_f32_16x16x32_bf16 v[80:83], v[212:215], v[182:185], v[80:83]
	v_mfma_f32_16x16x32_bf16 v[88:91], v[220:223], v[174:177], v[88:91]
	v_mfma_f32_16x16x32_bf16 v[96:99], v[220:223], v[182:185], v[96:99]
	s_setprio 0
	s_barrier
	v_readfirstlane_b32 s5, v154
	v_add_u32_e32 v169, 0x2000, v154
	v_lshl_add_u64 v[170:171], v[244:245], 0, s[46:47]
	s_mov_b32 m0, s5
	v_readfirstlane_b32 s5, v169
	global_load_lds_dwordx4 v[170:171], off
	v_lshl_add_u64 v[170:171], v[246:247], 0, s[46:47]
	s_mov_b32 m0, s5
	s_nop 0
	global_load_lds_dwordx4 v[170:171], off
	s_waitcnt vmcnt(6)
	s_barrier
	s_setprio 1
	v_mfma_f32_16x16x32_bf16 v[92:95], v[192:195], v[224:227], v[92:95]
	v_mfma_f32_16x16x32_bf16 v[100:103], v[192:195], v[232:235], v[100:103]
	v_mfma_f32_16x16x32_bf16 v[104:107], v[200:203], v[224:227], v[104:107]
	v_mfma_f32_16x16x32_bf16 v[108:111], v[200:203], v[232:235], v[108:111]
	v_mfma_f32_16x16x32_bf16 v[114:117], v[208:211], v[224:227], v[114:117]
	v_mfma_f32_16x16x32_bf16 v[118:121], v[208:211], v[232:235], v[118:121]
	v_mfma_f32_16x16x32_bf16 v[122:125], v[216:219], v[224:227], v[122:125]
	v_mfma_f32_16x16x32_bf16 v[126:129], v[216:219], v[232:235], v[126:129]
	v_mfma_f32_16x16x32_bf16 v[92:95], v[196:199], v[228:231], v[92:95]
	v_mfma_f32_16x16x32_bf16 v[100:103], v[196:199], v[236:239], v[100:103]
	v_mfma_f32_16x16x32_bf16 v[104:107], v[204:207], v[228:231], v[104:107]
	v_mfma_f32_16x16x32_bf16 v[108:111], v[204:207], v[236:239], v[108:111]
	v_mfma_f32_16x16x32_bf16 v[114:117], v[212:215], v[228:231], v[114:117]
	v_mfma_f32_16x16x32_bf16 v[118:121], v[212:215], v[236:239], v[118:121]
	v_mfma_f32_16x16x32_bf16 v[122:125], v[220:223], v[228:231], v[122:125]
	v_mfma_f32_16x16x32_bf16 v[126:129], v[220:223], v[236:239], v[126:129]
	s_setprio 0
	s_barrier
	ds_read_b128 v[170:173], v155
	ds_read_b128 v[174:177], v155 offset:1024
	ds_read_b128 v[178:181], v155 offset:2048
	ds_read_b128 v[182:185], v155 offset:3072
	v_readfirstlane_b32 s5, v156
	v_lshl_add_u64 v[224:225], v[240:241], 0, s[46:47]
	s_mov_b32 m0, s5
	v_readfirstlane_b32 s5, v157
	ds_read_b128 v[192:195], v150 offset:32768
	ds_read_b128 v[196:199], v150 offset:33792
	ds_read_b128 v[200:203], v149 offset:32768
	ds_read_b128 v[204:207], v149 offset:33792
	ds_read_b128 v[208:211], v148 offset:32768
	ds_read_b128 v[212:215], v148 offset:33792
	ds_read_b128 v[216:219], v147 offset:32768
	ds_read_b128 v[220:223], v147 offset:33792
	global_load_lds_dwordx4 v[224:225], off
	v_lshl_add_u64 v[224:225], v[242:243], 0, s[46:47]
	s_mov_b32 m0, s5
	s_nop 0
	global_load_lds_dwordx4 v[224:225], off
	s_waitcnt lgkmcnt(8)
	s_barrier
	s_waitcnt lgkmcnt(0)
	s_setprio 1
	v_mfma_f32_16x16x32_bf16 v[0:3], v[192:195], v[170:173], v[0:3]
	v_mfma_f32_16x16x32_bf16 v[4:7], v[192:195], v[178:181], v[4:7]
	v_mfma_f32_16x16x32_bf16 v[8:11], v[200:203], v[170:173], v[8:11]
	v_mfma_f32_16x16x32_bf16 v[16:19], v[200:203], v[178:181], v[16:19]
	v_mfma_f32_16x16x32_bf16 v[28:31], v[208:211], v[170:173], v[28:31]
	v_mfma_f32_16x16x32_bf16 v[40:43], v[208:211], v[178:181], v[40:43]
	v_mfma_f32_16x16x32_bf16 v[52:55], v[216:219], v[170:173], v[52:55]
	v_mfma_f32_16x16x32_bf16 v[64:67], v[216:219], v[178:181], v[64:67]
	v_mfma_f32_16x16x32_bf16 v[0:3], v[196:199], v[174:177], v[0:3]
	v_mfma_f32_16x16x32_bf16 v[4:7], v[196:199], v[182:185], v[4:7]
	v_mfma_f32_16x16x32_bf16 v[8:11], v[204:207], v[174:177], v[8:11]
	v_mfma_f32_16x16x32_bf16 v[16:19], v[204:207], v[182:185], v[16:19]
	v_mfma_f32_16x16x32_bf16 v[28:31], v[212:215], v[174:177], v[28:31]
	v_mfma_f32_16x16x32_bf16 v[40:43], v[212:215], v[182:185], v[40:43]
	v_mfma_f32_16x16x32_bf16 v[52:55], v[220:223], v[174:177], v[52:55]
	v_mfma_f32_16x16x32_bf16 v[64:67], v[220:223], v[182:185], v[64:67]
	s_setprio 0
	s_barrier
	v_readfirstlane_b32 s5, v158
	v_lshl_add_u64 v[248:249], v[244:245], 0, s[48:49]
	s_mov_b32 m0, s5
	v_readfirstlane_b32 s5, v159
	ds_read_b128 v[224:227], v151
	ds_read_b128 v[228:231], v151 offset:1024
	ds_read_b128 v[232:235], v151 offset:2048
	ds_read_b128 v[236:239], v151 offset:3072
	global_load_lds_dwordx4 v[248:249], off
	v_lshl_add_u64 v[248:249], v[246:247], 0, s[48:49]
	s_mov_b32 m0, s5
	s_nop 0
	global_load_lds_dwordx4 v[248:249], off
	s_barrier
	s_waitcnt lgkmcnt(0)
	s_setprio 1
	v_mfma_f32_16x16x32_bf16 v[12:15], v[192:195], v[224:227], v[12:15]
	v_mfma_f32_16x16x32_bf16 v[20:23], v[192:195], v[232:235], v[20:23]
	v_mfma_f32_16x16x32_bf16 v[32:35], v[200:203], v[224:227], v[32:35]
	v_mfma_f32_16x16x32_bf16 v[44:47], v[200:203], v[232:235], v[44:47]
	v_mfma_f32_16x16x32_bf16 v[56:59], v[208:211], v[224:227], v[56:59]
	v_mfma_f32_16x16x32_bf16 v[68:71], v[208:211], v[232:235], v[68:71]
	v_mfma_f32_16x16x32_bf16 v[76:79], v[216:219], v[224:227], v[76:79]
	v_mfma_f32_16x16x32_bf16 v[84:87], v[216:219], v[232:235], v[84:87]
	v_mfma_f32_16x16x32_bf16 v[12:15], v[196:199], v[228:231], v[12:15]
	v_mfma_f32_16x16x32_bf16 v[20:23], v[196:199], v[236:239], v[20:23]
	v_mfma_f32_16x16x32_bf16 v[32:35], v[204:207], v[228:231], v[32:35]
	v_mfma_f32_16x16x32_bf16 v[44:47], v[204:207], v[236:239], v[44:47]
	v_mfma_f32_16x16x32_bf16 v[56:59], v[212:215], v[228:231], v[56:59]
	v_mfma_f32_16x16x32_bf16 v[68:71], v[212:215], v[236:239], v[68:71]
	v_mfma_f32_16x16x32_bf16 v[76:79], v[220:223], v[228:231], v[76:79]
	v_mfma_f32_16x16x32_bf16 v[84:87], v[220:223], v[236:239], v[84:87]
	s_setprio 0
	v_readfirstlane_b32 s5, v160
	v_lshl_add_u64 v[240:241], v[240:241], 0, s[48:49]
	s_mov_b32 m0, s5
	v_readfirstlane_b32 s5, v161
	s_barrier
	ds_read_b128 v[192:195], v150 offset:49152
	ds_read_b128 v[196:199], v150 offset:50176
	ds_read_b128 v[200:203], v149 offset:49152
	ds_read_b128 v[204:207], v149 offset:50176
	ds_read_b128 v[208:211], v148 offset:49152
	ds_read_b128 v[212:215], v148 offset:50176
	ds_read_b128 v[216:219], v147 offset:49152
	ds_read_b128 v[220:223], v147 offset:50176
	global_load_lds_dwordx4 v[240:241], off
	v_lshl_add_u64 v[240:241], v[242:243], 0, s[48:49]
	s_mov_b32 m0, s5
	s_nop 0
	global_load_lds_dwordx4 v[240:241], off
	s_barrier
	s_waitcnt lgkmcnt(0)
	s_setprio 1
	v_mfma_f32_16x16x32_bf16 v[24:27], v[192:195], v[170:173], v[24:27]
	v_mfma_f32_16x16x32_bf16 v[36:39], v[192:195], v[178:181], v[36:39]
	v_mfma_f32_16x16x32_bf16 v[48:51], v[200:203], v[170:173], v[48:51]
	v_mfma_f32_16x16x32_bf16 v[60:63], v[200:203], v[178:181], v[60:63]
	v_mfma_f32_16x16x32_bf16 v[72:75], v[208:211], v[170:173], v[72:75]
	v_mfma_f32_16x16x32_bf16 v[80:83], v[208:211], v[178:181], v[80:83]
	v_mfma_f32_16x16x32_bf16 v[88:91], v[216:219], v[170:173], v[88:91]
	v_mfma_f32_16x16x32_bf16 v[96:99], v[216:219], v[178:181], v[96:99]
	v_mfma_f32_16x16x32_bf16 v[24:27], v[196:199], v[174:177], v[24:27]
	v_mfma_f32_16x16x32_bf16 v[36:39], v[196:199], v[182:185], v[36:39]
	v_mfma_f32_16x16x32_bf16 v[48:51], v[204:207], v[174:177], v[48:51]
	v_mfma_f32_16x16x32_bf16 v[60:63], v[204:207], v[182:185], v[60:63]
	v_mfma_f32_16x16x32_bf16 v[72:75], v[212:215], v[174:177], v[72:75]
	v_mfma_f32_16x16x32_bf16 v[80:83], v[212:215], v[182:185], v[80:83]
	v_mfma_f32_16x16x32_bf16 v[88:91], v[220:223], v[174:177], v[88:91]
	v_mfma_f32_16x16x32_bf16 v[96:99], v[220:223], v[182:185], v[96:99]
	s_setprio 0
	s_barrier
	v_readfirstlane_b32 s5, v162
	v_lshl_add_u64 v[170:171], v[244:245], 0, s[50:51]
	s_mov_b32 m0, s5
	v_readfirstlane_b32 s5, v164
	global_load_lds_dwordx4 v[170:171], off
	v_lshl_add_u64 v[170:171], v[246:247], 0, s[50:51]
	s_mov_b32 m0, s5
	s_nop 0
	global_load_lds_dwordx4 v[170:171], off
	s_waitcnt vmcnt(6)
	s_barrier
	s_setprio 1
	v_mfma_f32_16x16x32_bf16 v[92:95], v[192:195], v[224:227], v[92:95]
	v_mfma_f32_16x16x32_bf16 v[100:103], v[192:195], v[232:235], v[100:103]
	v_mfma_f32_16x16x32_bf16 v[104:107], v[200:203], v[224:227], v[104:107]
	v_mfma_f32_16x16x32_bf16 v[108:111], v[200:203], v[232:235], v[108:111]
	v_mfma_f32_16x16x32_bf16 v[114:117], v[208:211], v[224:227], v[114:117]
	v_mfma_f32_16x16x32_bf16 v[118:121], v[208:211], v[232:235], v[118:121]
	v_mfma_f32_16x16x32_bf16 v[122:125], v[216:219], v[224:227], v[122:125]
	v_mfma_f32_16x16x32_bf16 v[126:129], v[216:219], v[232:235], v[126:129]
	v_mfma_f32_16x16x32_bf16 v[92:95], v[196:199], v[228:231], v[92:95]
	v_mfma_f32_16x16x32_bf16 v[100:103], v[196:199], v[236:239], v[100:103]
	v_mfma_f32_16x16x32_bf16 v[104:107], v[204:207], v[228:231], v[104:107]
	v_mfma_f32_16x16x32_bf16 v[108:111], v[204:207], v[236:239], v[108:111]
	v_mfma_f32_16x16x32_bf16 v[114:117], v[212:215], v[228:231], v[114:117]
	v_mfma_f32_16x16x32_bf16 v[118:121], v[212:215], v[236:239], v[118:121]
	v_mfma_f32_16x16x32_bf16 v[122:125], v[220:223], v[228:231], v[122:125]
	v_mfma_f32_16x16x32_bf16 v[126:129], v[220:223], v[236:239], v[126:129]
	s_setprio 0
	s_add_i32 s4, s4, 2
	s_add_u32 s6, s6, 0x100
	s_addc_u32 s7, s7, 0
	s_cmp_gt_u32 s4, 27
	s_barrier
	s_cbranch_scc0 .LBB0_300
	s_mov_b64 s[6:7], 0xf80
	v_readfirstlane_b32 s4, v167
	v_lshl_add_u64 v[130:131], v[130:131], 0, s[6:7]
	s_mov_b32 m0, s4
	v_readfirstlane_b32 s4, v168
	ds_read_b128 v[134:137], v166
	ds_read_b128 v[138:141], v166 offset:1024
	ds_read_b128 v[156:159], v166 offset:2048
	ds_read_b128 v[170:173], v166 offset:3072
	ds_read_b128 v[174:177], v150
	ds_read_b128 v[178:181], v150 offset:1024
	ds_read_b128 v[182:185], v149
	ds_read_b128 v[192:195], v149 offset:1024
	ds_read_b128 v[196:199], v148
	ds_read_b128 v[200:203], v148 offset:1024
	ds_read_b128 v[204:207], v147
	ds_read_b128 v[208:211], v147 offset:1024
	global_load_lds_dwordx4 v[130:131], off
	v_lshl_add_u64 v[130:131], v[132:133], 0, s[6:7]
	s_mov_b32 m0, s4
	s_nop 0
	global_load_lds_dwordx4 v[130:131], off
	s_barrier
	s_waitcnt lgkmcnt(0)
	s_setprio 1
	v_mfma_f32_16x16x32_bf16 v[0:3], v[174:177], v[134:137], v[0:3]
	v_mfma_f32_16x16x32_bf16 v[4:7], v[174:177], v[156:159], v[4:7]
	v_mfma_f32_16x16x32_bf16 v[8:11], v[182:185], v[134:137], v[8:11]
	v_mfma_f32_16x16x32_bf16 v[16:19], v[182:185], v[156:159], v[16:19]
	v_mfma_f32_16x16x32_bf16 v[28:31], v[196:199], v[134:137], v[28:31]
	v_mfma_f32_16x16x32_bf16 v[40:43], v[196:199], v[156:159], v[40:43]
	v_mfma_f32_16x16x32_bf16 v[52:55], v[204:207], v[134:137], v[52:55]
	v_mfma_f32_16x16x32_bf16 v[64:67], v[204:207], v[156:159], v[64:67]
	v_mfma_f32_16x16x32_bf16 v[0:3], v[178:181], v[138:141], v[0:3]
	v_mfma_f32_16x16x32_bf16 v[4:7], v[178:181], v[170:173], v[4:7]
	v_mfma_f32_16x16x32_bf16 v[8:11], v[192:195], v[138:141], v[8:11]
	v_mfma_f32_16x16x32_bf16 v[16:19], v[192:195], v[170:173], v[16:19]
	v_mfma_f32_16x16x32_bf16 v[28:31], v[200:203], v[138:141], v[28:31]
	v_mfma_f32_16x16x32_bf16 v[40:43], v[200:203], v[170:173], v[40:43]
	v_mfma_f32_16x16x32_bf16 v[52:55], v[208:211], v[138:141], v[52:55]
	v_mfma_f32_16x16x32_bf16 v[64:67], v[208:211], v[170:173], v[64:67]
	s_setprio 0
	s_barrier
	ds_read_b128 v[130:133], v165
	ds_read_b128 v[166:169], v165 offset:1024
	ds_read_b128 v[212:215], v165 offset:2048
	ds_read_b128 v[216:219], v165 offset:3072
	s_barrier
	s_waitcnt lgkmcnt(0)
	s_setprio 1
	v_mfma_f32_16x16x32_bf16 v[12:15], v[174:177], v[130:133], v[12:15]
	v_mfma_f32_16x16x32_bf16 v[220:223], v[178:181], v[166:169], v[12:15]
	v_mfma_f32_16x16x32_bf16 v[12:15], v[174:177], v[212:215], v[20:23]
	v_mfma_f32_16x16x32_bf16 v[174:177], v[178:181], v[216:219], v[12:15]
	v_mfma_f32_16x16x32_bf16 v[12:15], v[182:185], v[130:133], v[32:35]
	v_mfma_f32_16x16x32_bf16 v[178:181], v[192:195], v[166:169], v[12:15]
	v_mfma_f32_16x16x32_bf16 v[12:15], v[182:185], v[212:215], v[44:47]
	v_mfma_f32_16x16x32_bf16 v[44:47], v[192:195], v[216:219], v[12:15]
	v_mfma_f32_16x16x32_bf16 v[12:15], v[196:199], v[130:133], v[56:59]
	v_mfma_f32_16x16x32_bf16 v[56:59], v[200:203], v[166:169], v[12:15]
	v_mfma_f32_16x16x32_bf16 v[12:15], v[196:199], v[212:215], v[68:71]
	v_mfma_f32_16x16x32_bf16 v[68:71], v[200:203], v[216:219], v[12:15]
	v_mfma_f32_16x16x32_bf16 v[12:15], v[204:207], v[130:133], v[76:79]
	v_mfma_f32_16x16x32_bf16 v[76:79], v[208:211], v[166:169], v[12:15]
	v_mfma_f32_16x16x32_bf16 v[12:15], v[204:207], v[212:215], v[84:87]
	v_mfma_f32_16x16x32_bf16 v[84:87], v[208:211], v[216:219], v[12:15]
	s_setprio 0
	s_barrier
	s_nop 4
	ds_read_b128 v[12:15], v150 offset:16384
	ds_read_b128 v[20:23], v150 offset:17408
	ds_read_b128 v[32:35], v149 offset:16384
	ds_read_b128 v[182:185], v149 offset:17408
	ds_read_b128 v[192:195], v148 offset:16384
	ds_read_b128 v[196:199], v148 offset:17408
	ds_read_b128 v[200:203], v147 offset:16384
	ds_read_b128 v[204:207], v147 offset:17408
	s_waitcnt vmcnt(4)
	s_barrier
	s_waitcnt lgkmcnt(0)
	s_setprio 1
	v_mfma_f32_16x16x32_bf16 v[24:27], v[12:15], v[134:137], v[24:27]
	v_mfma_f32_16x16x32_bf16 v[208:211], v[20:23], v[138:141], v[24:27]
	v_mfma_f32_16x16x32_bf16 v[24:27], v[12:15], v[156:159], v[36:39]
	v_mfma_f32_16x16x32_bf16 v[224:227], v[20:23], v[170:173], v[24:27]
	v_mfma_f32_16x16x32_bf16 v[24:27], v[32:35], v[134:137], v[48:51]
	v_mfma_f32_16x16x32_bf16 v[228:231], v[182:185], v[138:141], v[24:27]
	v_mfma_f32_16x16x32_bf16 v[24:27], v[32:35], v[156:159], v[60:63]
	v_mfma_f32_16x16x32_bf16 v[232:235], v[182:185], v[170:173], v[24:27]
	v_mfma_f32_16x16x32_bf16 v[24:27], v[192:195], v[134:137], v[72:75]
	v_mfma_f32_16x16x32_bf16 v[236:239], v[196:199], v[138:141], v[24:27]
	v_mfma_f32_16x16x32_bf16 v[24:27], v[192:195], v[156:159], v[80:83]
	v_mfma_f32_16x16x32_bf16 v[240:243], v[196:199], v[170:173], v[24:27]
	v_mfma_f32_16x16x32_bf16 v[24:27], v[200:203], v[134:137], v[88:91]
	v_mfma_f32_16x16x32_bf16 v[88:91], v[204:207], v[138:141], v[24:27]
	v_mfma_f32_16x16x32_bf16 v[24:27], v[200:203], v[156:159], v[96:99]
	v_mfma_f32_16x16x32_bf16 v[96:99], v[204:207], v[170:173], v[24:27]
	s_setprio 0
	s_setprio 1
	v_mfma_f32_16x16x32_bf16 v[24:27], v[12:15], v[130:133], v[92:95]
	v_mfma_f32_16x16x32_bf16 v[12:15], v[12:15], v[212:215], v[100:103]
	v_mfma_f32_16x16x32_bf16 v[100:103], v[20:23], v[216:219], v[12:15]
	v_mfma_f32_16x16x32_bf16 v[12:15], v[32:35], v[130:133], v[104:107]
	v_mfma_f32_16x16x32_bf16 v[104:107], v[182:185], v[166:169], v[12:15]
	v_mfma_f32_16x16x32_bf16 v[12:15], v[32:35], v[212:215], v[108:111]
	v_mfma_f32_16x16x32_bf16 v[108:111], v[182:185], v[216:219], v[12:15]
	v_mfma_f32_16x16x32_bf16 v[12:15], v[192:195], v[130:133], v[114:117]
	v_mfma_f32_16x16x32_bf16 v[114:117], v[196:199], v[166:169], v[12:15]
	v_mfma_f32_16x16x32_bf16 v[12:15], v[192:195], v[212:215], v[118:121]
	v_mfma_f32_16x16x32_bf16 v[118:121], v[196:199], v[216:219], v[12:15]
	v_mfma_f32_16x16x32_bf16 v[12:15], v[200:203], v[130:133], v[122:125]
	v_mfma_f32_16x16x32_bf16 v[122:125], v[204:207], v[166:169], v[12:15]
	v_mfma_f32_16x16x32_bf16 v[12:15], v[200:203], v[212:215], v[126:129]
	v_mfma_f32_16x16x32_bf16 v[126:129], v[204:207], v[216:219], v[12:15]
	v_mfma_f32_16x16x32_bf16 v[134:137], v[20:23], v[166:169], v[24:27]
	s_setprio 0
	s_barrier
	ds_read_b128 v[92:95], v155
	ds_read_b128 v[130:133], v155 offset:1024
	ds_read_b128 v[138:141], v155 offset:2048
	ds_read_b128 v[152:155], v155 offset:3072
	ds_read_b128 v[36:39], v150 offset:32768
	ds_read_b128 v[48:51], v150 offset:33792
	ds_read_b128 v[60:63], v149 offset:32768
	ds_read_b128 v[72:75], v149 offset:33792
	ds_read_b128 v[80:83], v148 offset:32768
	ds_read_b128 v[156:159], v148 offset:33792
	ds_read_b128 v[164:167], v147 offset:32768
	ds_read_b128 v[168:171], v147 offset:33792
	s_waitcnt vmcnt(2)
	s_barrier
	s_waitcnt lgkmcnt(0)
	s_setprio 1
	v_mfma_f32_16x16x32_bf16 v[0:3], v[36:39], v[92:95], v[0:3]
	v_mfma_f32_16x16x32_bf16 v[4:7], v[36:39], v[138:141], v[4:7]
	v_mfma_f32_16x16x32_bf16 v[8:11], v[60:63], v[92:95], v[8:11]
	v_mfma_f32_16x16x32_bf16 v[12:15], v[60:63], v[138:141], v[16:19]
	v_mfma_f32_16x16x32_bf16 v[16:19], v[80:83], v[92:95], v[28:31]
	v_mfma_f32_16x16x32_bf16 v[20:23], v[80:83], v[138:141], v[40:43]
	v_mfma_f32_16x16x32_bf16 v[24:27], v[164:167], v[92:95], v[52:55]
	v_mfma_f32_16x16x32_bf16 v[28:31], v[164:167], v[138:141], v[64:67]
	v_mfma_f32_16x16x32_bf16 v[0:3], v[48:51], v[130:133], v[0:3]
	v_mfma_f32_16x16x32_bf16 v[4:7], v[48:51], v[152:155], v[4:7]
	v_mfma_f32_16x16x32_bf16 v[8:11], v[72:75], v[130:133], v[8:11]
	v_mfma_f32_16x16x32_bf16 v[12:15], v[72:75], v[152:155], v[12:15]
	v_mfma_f32_16x16x32_bf16 v[16:19], v[156:159], v[130:133], v[16:19]
	v_mfma_f32_16x16x32_bf16 v[20:23], v[156:159], v[152:155], v[20:23]
	v_mfma_f32_16x16x32_bf16 v[24:27], v[168:171], v[130:133], v[24:27]
	v_mfma_f32_16x16x32_bf16 v[28:31], v[168:171], v[152:155], v[28:31]
	s_setprio 0
	s_barrier
	ds_read_b128 v[182:185], v151
	ds_read_b128 v[192:195], v151 offset:1024
	ds_read_b128 v[196:199], v151 offset:2048
	ds_read_b128 v[200:203], v151 offset:3072
	s_waitcnt vmcnt(0)
	s_barrier
	s_waitcnt lgkmcnt(0)
	s_setprio 1
	v_mfma_f32_16x16x32_bf16 v[32:35], v[36:39], v[182:185], v[220:223]
	v_mfma_f32_16x16x32_bf16 v[36:39], v[36:39], v[196:199], v[174:177]
	v_mfma_f32_16x16x32_bf16 v[32:35], v[48:51], v[192:195], v[32:35]
	v_mfma_f32_16x16x32_bf16 v[36:39], v[48:51], v[200:203], v[36:39]
	v_mfma_f32_16x16x32_bf16 v[40:43], v[60:63], v[182:185], v[178:181]
	v_mfma_f32_16x16x32_bf16 v[44:47], v[60:63], v[196:199], v[44:47]
	v_mfma_f32_16x16x32_bf16 v[48:51], v[80:83], v[182:185], v[56:59]
	v_mfma_f32_16x16x32_bf16 v[52:55], v[80:83], v[196:199], v[68:71]
	v_mfma_f32_16x16x32_bf16 v[56:59], v[164:167], v[182:185], v[76:79]
	v_mfma_f32_16x16x32_bf16 v[60:63], v[164:167], v[196:199], v[84:87]
	v_mfma_f32_16x16x32_bf16 v[40:43], v[72:75], v[192:195], v[40:43]
	v_mfma_f32_16x16x32_bf16 v[44:47], v[72:75], v[200:203], v[44:47]
	v_mfma_f32_16x16x32_bf16 v[48:51], v[156:159], v[192:195], v[48:51]
	v_mfma_f32_16x16x32_bf16 v[52:55], v[156:159], v[200:203], v[52:55]
	v_mfma_f32_16x16x32_bf16 v[56:59], v[168:171], v[192:195], v[56:59]
	v_mfma_f32_16x16x32_bf16 v[60:63], v[168:171], v[200:203], v[60:63]
	s_setprio 0
	s_barrier
	ds_read_b128 v[156:159], v150 offset:49152
	ds_read_b128 v[164:167], v150 offset:50176
	ds_read_b128 v[168:171], v149 offset:49152
	ds_read_b128 v[172:175], v149 offset:50176
	ds_read_b128 v[176:179], v148 offset:49152
	ds_read_b128 v[148:151], v148 offset:50176
	ds_read_b128 v[204:207], v147 offset:49152
	ds_read_b128 v[212:215], v147 offset:50176
	s_barrier
	s_waitcnt lgkmcnt(0)
	s_setprio 1
	v_mfma_f32_16x16x32_bf16 v[64:67], v[156:159], v[92:95], v[208:211]
	v_mfma_f32_16x16x32_bf16 v[68:71], v[156:159], v[138:141], v[224:227]
	v_mfma_f32_16x16x32_bf16 v[72:75], v[168:171], v[92:95], v[228:231]
	v_mfma_f32_16x16x32_bf16 v[76:79], v[168:171], v[138:141], v[232:235]
	v_mfma_f32_16x16x32_bf16 v[80:83], v[176:179], v[92:95], v[236:239]
	v_mfma_f32_16x16x32_bf16 v[84:87], v[176:179], v[138:141], v[240:243]
	v_mfma_f32_16x16x32_bf16 v[88:91], v[204:207], v[92:95], v[88:91]
	v_mfma_f32_16x16x32_bf16 v[92:95], v[204:207], v[138:141], v[96:99]
	v_mfma_f32_16x16x32_bf16 v[64:67], v[164:167], v[130:133], v[64:67]
	v_mfma_f32_16x16x32_bf16 v[68:71], v[164:167], v[152:155], v[68:71]
	v_mfma_f32_16x16x32_bf16 v[72:75], v[172:175], v[130:133], v[72:75]
	v_mfma_f32_16x16x32_bf16 v[76:79], v[172:175], v[152:155], v[76:79]
	v_mfma_f32_16x16x32_bf16 v[80:83], v[148:151], v[130:133], v[80:83]
	v_mfma_f32_16x16x32_bf16 v[84:87], v[148:151], v[152:155], v[84:87]
	v_mfma_f32_16x16x32_bf16 v[88:91], v[212:215], v[130:133], v[88:91]
	v_mfma_f32_16x16x32_bf16 v[92:95], v[212:215], v[152:155], v[92:95]
	s_setprio 0
	s_setprio 1
	v_mfma_f32_16x16x32_bf16 v[96:99], v[156:159], v[182:185], v[134:137]
	v_mfma_f32_16x16x32_bf16 v[100:103], v[156:159], v[196:199], v[100:103]
	v_mfma_f32_16x16x32_bf16 v[104:107], v[168:171], v[182:185], v[104:107]
	v_mfma_f32_16x16x32_bf16 v[108:111], v[168:171], v[196:199], v[108:111]
	v_mfma_f32_16x16x32_bf16 v[114:117], v[176:179], v[182:185], v[114:117]
	v_mfma_f32_16x16x32_bf16 v[118:121], v[176:179], v[196:199], v[118:121]
	v_mfma_f32_16x16x32_bf16 v[122:125], v[204:207], v[182:185], v[122:125]
	v_mfma_f32_16x16x32_bf16 v[126:129], v[204:207], v[196:199], v[126:129]
	v_mfma_f32_16x16x32_bf16 v[96:99], v[164:167], v[192:195], v[96:99]
	v_mfma_f32_16x16x32_bf16 v[100:103], v[164:167], v[200:203], v[100:103]
	v_mfma_f32_16x16x32_bf16 v[104:107], v[172:175], v[192:195], v[104:107]
	v_mfma_f32_16x16x32_bf16 v[108:111], v[172:175], v[200:203], v[108:111]
	v_mfma_f32_16x16x32_bf16 v[114:117], v[148:151], v[192:195], v[114:117]
	v_mfma_f32_16x16x32_bf16 v[118:121], v[148:151], v[200:203], v[118:121]
	v_mfma_f32_16x16x32_bf16 v[122:125], v[212:215], v[192:195], v[122:125]
	v_mfma_f32_16x16x32_bf16 v[126:129], v[212:215], v[200:203], v[126:129]
	s_setprio 0
	s_movk_i32 s4, 0x100
	v_cmp_gt_u32_e32 vcc, s4, v113
	s_barrier
	s_and_saveexec_b64 s[4:5], vcc
	s_cbranch_execz .LBB0_303
	s_barrier

.LBB0_341:
	ds_read_b128 v[8:11], v204
	ds_read_b128 v[12:15], v204 offset:1024
	ds_read_b128 v[0:3], v204 offset:2048
	ds_read_b128 v[4:7], v204 offset:3072
	v_add_u32_e32 v205, 0xc000, v192
	v_lshl_add_u64 v[168:169], v[164:165], 0, s[6:7]
	v_readfirstlane_b32 s5, v205
	v_add_u32_e32 v206, 0xe000, v192
	v_lshl_add_u64 v[16:17], v[168:169], 0, s[54:55]
	s_mov_b32 m0, s5
	v_lshl_add_u64 v[170:171], v[166:167], 0, s[6:7]
	v_readfirstlane_b32 s5, v206
	ds_read_b128 v[208:211], v182
	ds_read_b128 v[212:215], v182 offset:1024
	ds_read_b128 v[216:219], v181
	ds_read_b128 v[220:223], v181 offset:1024
	ds_read_b128 v[224:227], v180
	ds_read_b128 v[228:231], v180 offset:1024
	ds_read_b128 v[232:235], v179
	ds_read_b128 v[236:239], v179 offset:1024
	global_load_lds_dwordx4 v[16:17], off
	v_lshl_add_u64 v[16:17], v[170:171], 0, s[54:55]
	s_mov_b32 m0, s5
	s_nop 0
	global_load_lds_dwordx4 v[16:17], off
	s_waitcnt lgkmcnt(8)
	s_barrier
	s_waitcnt lgkmcnt(0)
	s_setprio 1
	v_mfma_f32_16x16x128_f8f6f4 v[24:27], v[208:215], v[8:15], v[24:27]
	v_mfma_f32_16x16x128_f8f6f4 v[28:31], v[208:215], v[0:7], v[28:31]
	v_mfma_f32_16x16x128_f8f6f4 v[32:35], v[216:223], v[8:15], v[32:35]
	v_mfma_f32_16x16x128_f8f6f4 v[36:39], v[216:223], v[0:7], v[36:39]
	v_mfma_f32_16x16x128_f8f6f4 v[40:43], v[224:231], v[8:15], v[40:43]
	v_mfma_f32_16x16x128_f8f6f4 v[44:47], v[224:231], v[0:7], v[44:47]
	v_mfma_f32_16x16x128_f8f6f4 v[48:51], v[232:239], v[8:15], v[48:51]
	v_mfma_f32_16x16x128_f8f6f4 v[52:55], v[232:239], v[0:7], v[52:55]
	s_setprio 0
	s_barrier
	v_lshl_add_u64 v[172:173], v[158:159], 0, s[6:7]
	v_readfirstlane_b32 s5, v185
	v_lshl_add_u64 v[174:175], v[172:173], 0, s[44:45]
	s_mov_b32 m0, s5
	v_add_u32_e32 v187, 0x2000, v185
	ds_read_b128 v[240:243], v197
	ds_read_b128 v[244:247], v197 offset:1024
	ds_read_b128 v[16:19], v197 offset:2048
	ds_read_b128 v[20:23], v197 offset:3072
	global_load_lds_dwordx4 v[174:175], off
	v_lshl_add_u64 v[174:175], v[160:161], 0, s[6:7]
	v_readfirstlane_b32 s5, v187
	v_lshl_add_u64 v[248:249], v[174:175], 0, s[44:45]
	s_mov_b32 m0, s5
	s_nop 0
	global_load_lds_dwordx4 v[248:249], off
	s_barrier
	s_waitcnt lgkmcnt(0)
	s_setprio 1
	v_mfma_f32_16x16x128_f8f6f4 v[56:59], v[208:215], v[240:247], v[56:59]
	v_mfma_f32_16x16x128_f8f6f4 v[60:63], v[208:215], v[16:23], v[60:63]
	v_mfma_f32_16x16x128_f8f6f4 v[64:67], v[216:223], v[240:247], v[64:67]
	v_mfma_f32_16x16x128_f8f6f4 v[68:71], v[216:223], v[16:23], v[68:71]
	v_mfma_f32_16x16x128_f8f6f4 v[72:75], v[224:231], v[240:247], v[72:75]
	v_mfma_f32_16x16x128_f8f6f4 v[76:79], v[224:231], v[16:23], v[76:79]
	v_mfma_f32_16x16x128_f8f6f4 v[80:83], v[232:239], v[240:247], v[80:83]
	v_mfma_f32_16x16x128_f8f6f4 v[84:87], v[232:239], v[16:23], v[84:87]
	s_setprio 0
	v_readfirstlane_b32 s5, v192
	v_lshl_add_u64 v[248:249], v[168:169], 0, s[44:45]
	s_mov_b32 m0, s5
	v_readfirstlane_b32 s5, v193
	s_barrier
	ds_read_b128 v[208:211], v182 offset:16384
	ds_read_b128 v[212:215], v182 offset:17408
	ds_read_b128 v[216:219], v181 offset:16384
	ds_read_b128 v[220:223], v181 offset:17408
	ds_read_b128 v[224:227], v180 offset:16384
	ds_read_b128 v[228:231], v180 offset:17408
	ds_read_b128 v[232:235], v179 offset:16384
	ds_read_b128 v[236:239], v179 offset:17408
	global_load_lds_dwordx4 v[248:249], off
	v_lshl_add_u64 v[248:249], v[170:171], 0, s[44:45]
	s_mov_b32 m0, s5
	s_nop 0
	global_load_lds_dwordx4 v[248:249], off
	s_barrier
	s_waitcnt lgkmcnt(0)
	s_setprio 1
	v_mfma_f32_16x16x128_f8f6f4 v[88:91], v[208:215], v[8:15], v[88:91]
	v_mfma_f32_16x16x128_f8f6f4 v[92:95], v[208:215], v[0:7], v[92:95]
	v_mfma_f32_16x16x128_f8f6f4 v[96:99], v[216:223], v[8:15], v[96:99]
	v_mfma_f32_16x16x128_f8f6f4 v[100:103], v[216:223], v[0:7], v[100:103]
	v_mfma_f32_16x16x128_f8f6f4 v[104:107], v[224:231], v[8:15], v[104:107]
	v_mfma_f32_16x16x128_f8f6f4 v[108:111], v[224:231], v[0:7], v[108:111]
	v_mfma_f32_16x16x128_f8f6f4 v[114:117], v[232:239], v[8:15], v[114:117]
	v_mfma_f32_16x16x128_f8f6f4 v[118:121], v[232:239], v[0:7], v[118:121]
	s_setprio 0
	s_barrier
	v_readfirstlane_b32 s5, v194
	v_add_u32_e32 v2, 0x2000, v194
	v_lshl_add_u64 v[0:1], v[172:173], 0, s[56:57]
	s_mov_b32 m0, s5
	v_readfirstlane_b32 s5, v2
	global_load_lds_dwordx4 v[0:1], off
	v_lshl_add_u64 v[0:1], v[174:175], 0, s[56:57]
	s_mov_b32 m0, s5
	s_nop 0
	global_load_lds_dwordx4 v[0:1], off
	s_waitcnt vmcnt(6)
	s_barrier
	s_setprio 1
	v_mfma_f32_16x16x128_f8f6f4 v[122:125], v[208:215], v[240:247], v[122:125]
	v_mfma_f32_16x16x128_f8f6f4 v[126:129], v[208:215], v[16:23], v[126:129]
	v_mfma_f32_16x16x128_f8f6f4 v[130:133], v[216:223], v[240:247], v[130:133]
	v_mfma_f32_16x16x128_f8f6f4 v[134:137], v[216:223], v[16:23], v[134:137]
	v_mfma_f32_16x16x128_f8f6f4 v[138:141], v[224:231], v[240:247], v[138:141]
	v_mfma_f32_16x16x128_f8f6f4 v[142:145], v[224:231], v[16:23], v[142:145]
	v_mfma_f32_16x16x128_f8f6f4 v[146:149], v[232:239], v[240:247], v[146:149]
	v_mfma_f32_16x16x128_f8f6f4 v[150:153], v[232:239], v[16:23], v[150:153]
	s_setprio 0
	s_barrier
	ds_read_b128 v[0:3], v184
	ds_read_b128 v[4:7], v184 offset:1024
	ds_read_b128 v[8:11], v184 offset:2048
	ds_read_b128 v[12:15], v184 offset:3072
	v_readfirstlane_b32 s5, v195
	v_lshl_add_u64 v[232:233], v[168:169], 0, s[56:57]
	s_mov_b32 m0, s5
	v_readfirstlane_b32 s5, v196
	ds_read_b128 v[16:19], v182 offset:32768
	ds_read_b128 v[20:23], v182 offset:33792
	ds_read_b128 v[208:211], v181 offset:32768
	ds_read_b128 v[212:215], v181 offset:33792
	ds_read_b128 v[216:219], v180 offset:32768
	ds_read_b128 v[220:223], v180 offset:33792
	ds_read_b128 v[224:227], v179 offset:32768
	ds_read_b128 v[228:231], v179 offset:33792
	global_load_lds_dwordx4 v[232:233], off
	v_lshl_add_u64 v[232:233], v[170:171], 0, s[56:57]
	s_mov_b32 m0, s5
	s_nop 0
	global_load_lds_dwordx4 v[232:233], off
	s_waitcnt lgkmcnt(8)
	s_barrier
	s_waitcnt lgkmcnt(0)
	s_setprio 1
	v_mfma_f32_16x16x128_f8f6f4 v[24:27], v[16:23], v[0:7], v[24:27]
	v_mfma_f32_16x16x128_f8f6f4 v[28:31], v[16:23], v[8:15], v[28:31]
	v_mfma_f32_16x16x128_f8f6f4 v[32:35], v[208:215], v[0:7], v[32:35]
	v_mfma_f32_16x16x128_f8f6f4 v[36:39], v[208:215], v[8:15], v[36:39]
	v_mfma_f32_16x16x128_f8f6f4 v[40:43], v[216:223], v[0:7], v[40:43]
	v_mfma_f32_16x16x128_f8f6f4 v[44:47], v[216:223], v[8:15], v[44:47]
	v_mfma_f32_16x16x128_f8f6f4 v[48:51], v[224:231], v[0:7], v[48:51]
	v_mfma_f32_16x16x128_f8f6f4 v[52:55], v[224:231], v[8:15], v[52:55]
	s_setprio 0
	s_barrier
	v_readfirstlane_b32 s5, v198
	v_lshl_add_u64 v[248:249], v[172:173], 0, s[48:49]
	s_mov_b32 m0, s5
	v_readfirstlane_b32 s5, v199
	ds_read_b128 v[232:235], v183
	ds_read_b128 v[236:239], v183 offset:1024
	ds_read_b128 v[240:243], v183 offset:2048
	ds_read_b128 v[244:247], v183 offset:3072
	global_load_lds_dwordx4 v[248:249], off
	v_lshl_add_u64 v[248:249], v[174:175], 0, s[48:49]
	s_mov_b32 m0, s5
	s_nop 0
	global_load_lds_dwordx4 v[248:249], off
	s_barrier
	s_waitcnt lgkmcnt(0)
	s_setprio 1
	v_mfma_f32_16x16x128_f8f6f4 v[56:59], v[16:23], v[232:239], v[56:59]
	v_mfma_f32_16x16x128_f8f6f4 v[60:63], v[16:23], v[240:247], v[60:63]
	v_mfma_f32_16x16x128_f8f6f4 v[64:67], v[208:215], v[232:239], v[64:67]
	v_mfma_f32_16x16x128_f8f6f4 v[68:71], v[208:215], v[240:247], v[68:71]
	v_mfma_f32_16x16x128_f8f6f4 v[72:75], v[216:223], v[232:239], v[72:75]
	v_mfma_f32_16x16x128_f8f6f4 v[76:79], v[216:223], v[240:247], v[76:79]
	v_mfma_f32_16x16x128_f8f6f4 v[80:83], v[224:231], v[232:239], v[80:83]
	v_mfma_f32_16x16x128_f8f6f4 v[84:87], v[224:231], v[240:247], v[84:87]
	s_setprio 0
	v_readfirstlane_b32 s5, v200
	v_lshl_add_u64 v[168:169], v[168:169], 0, s[48:49]
	s_mov_b32 m0, s5
	v_readfirstlane_b32 s5, v201
	s_barrier
	ds_read_b128 v[16:19], v182 offset:49152
	ds_read_b128 v[20:23], v182 offset:50176
	ds_read_b128 v[208:211], v181 offset:49152
	ds_read_b128 v[212:215], v181 offset:50176
	ds_read_b128 v[216:219], v180 offset:49152
	ds_read_b128 v[220:223], v180 offset:50176
	ds_read_b128 v[224:227], v179 offset:49152
	ds_read_b128 v[228:231], v179 offset:50176
	global_load_lds_dwordx4 v[168:169], off
	v_lshl_add_u64 v[168:169], v[170:171], 0, s[48:49]
	s_mov_b32 m0, s5
	s_nop 0
	global_load_lds_dwordx4 v[168:169], off
	s_barrier
	s_waitcnt lgkmcnt(0)
	s_setprio 1
	v_mfma_f32_16x16x128_f8f6f4 v[88:91], v[16:23], v[0:7], v[88:91]
	v_mfma_f32_16x16x128_f8f6f4 v[92:95], v[16:23], v[8:15], v[92:95]
	v_mfma_f32_16x16x128_f8f6f4 v[96:99], v[208:215], v[0:7], v[96:99]
	v_mfma_f32_16x16x128_f8f6f4 v[100:103], v[208:215], v[8:15], v[100:103]
	v_mfma_f32_16x16x128_f8f6f4 v[104:107], v[216:223], v[0:7], v[104:107]
	v_mfma_f32_16x16x128_f8f6f4 v[108:111], v[216:223], v[8:15], v[108:111]
	v_mfma_f32_16x16x128_f8f6f4 v[114:117], v[224:231], v[0:7], v[114:117]
	v_mfma_f32_16x16x128_f8f6f4 v[118:121], v[224:231], v[8:15], v[118:121]
	s_setprio 0
	s_barrier
	v_readfirstlane_b32 s5, v202
	v_lshl_add_u64 v[0:1], v[172:173], 0, s[58:59]
	s_mov_b32 m0, s5
	v_readfirstlane_b32 s5, v203
	global_load_lds_dwordx4 v[0:1], off
	v_lshl_add_u64 v[0:1], v[174:175], 0, s[58:59]
	s_mov_b32 m0, s5
	s_nop 0
	global_load_lds_dwordx4 v[0:1], off
	s_waitcnt vmcnt(6)
	s_barrier
	s_setprio 1
	v_mfma_f32_16x16x128_f8f6f4 v[122:125], v[16:23], v[232:239], v[122:125]
	v_mfma_f32_16x16x128_f8f6f4 v[126:129], v[16:23], v[240:247], v[126:129]
	v_mfma_f32_16x16x128_f8f6f4 v[130:133], v[208:215], v[232:239], v[130:133]
	v_mfma_f32_16x16x128_f8f6f4 v[134:137], v[208:215], v[240:247], v[134:137]
	v_mfma_f32_16x16x128_f8f6f4 v[138:141], v[216:223], v[232:239], v[138:141]
	v_mfma_f32_16x16x128_f8f6f4 v[142:145], v[216:223], v[240:247], v[142:145]
	v_mfma_f32_16x16x128_f8f6f4 v[146:149], v[224:231], v[232:239], v[146:149]
	v_mfma_f32_16x16x128_f8f6f4 v[150:153], v[224:231], v[240:247], v[150:153]
	s_setprio 0
	s_add_i32 s4, s4, 2
	s_add_u32 s6, s6, 0x100
	s_addc_u32 s7, s7, 0
	s_cmp_gt_u32 s4, 11
	s_barrier
	s_cbranch_scc0 .LBB0_341
	s_mov_b64 s[6:7], 0x780
	v_readfirstlane_b32 s4, v205
	v_lshl_add_u64 v[154:155], v[154:155], 0, s[6:7]
	s_mov_b32 m0, s4
	v_readfirstlane_b32 s4, v206
	ds_read_b128 v[0:3], v204
	ds_read_b128 v[4:7], v204 offset:1024
	ds_read_b128 v[8:11], v204 offset:2048
	ds_read_b128 v[12:15], v204 offset:3072
	ds_read_b128 v[16:19], v182
	ds_read_b128 v[20:23], v182 offset:1024
	ds_read_b128 v[164:167], v181
	ds_read_b128 v[168:171], v181 offset:1024
	ds_read_b128 v[208:211], v180
	ds_read_b128 v[212:215], v180 offset:1024
	ds_read_b128 v[216:219], v179
	ds_read_b128 v[220:223], v179 offset:1024
	global_load_lds_dwordx4 v[154:155], off
	v_lshl_add_u64 v[154:155], v[156:157], 0, s[6:7]
	s_mov_b32 m0, s4
	s_nop 0
	global_load_lds_dwordx4 v[154:155], off
	s_barrier
	s_waitcnt lgkmcnt(0)
	s_setprio 1
	v_mfma_f32_16x16x128_f8f6f4 v[24:27], v[16:23], v[0:7], v[24:27]
	v_mfma_f32_16x16x128_f8f6f4 v[28:31], v[16:23], v[8:15], v[28:31]
	v_mfma_f32_16x16x128_f8f6f4 v[32:35], v[164:171], v[0:7], v[32:35]
	v_mfma_f32_16x16x128_f8f6f4 v[36:39], v[164:171], v[8:15], v[36:39]
	v_mfma_f32_16x16x128_f8f6f4 v[40:43], v[208:215], v[0:7], v[40:43]
	v_mfma_f32_16x16x128_f8f6f4 v[44:47], v[208:215], v[8:15], v[44:47]
	v_mfma_f32_16x16x128_f8f6f4 v[48:51], v[216:223], v[0:7], v[48:51]
	v_mfma_f32_16x16x128_f8f6f4 v[52:55], v[216:223], v[8:15], v[52:55]
	s_setprio 0
	s_barrier
	ds_read_b128 v[154:157], v197
	ds_read_b128 v[158:161], v197 offset:1024
	ds_read_b128 v[192:195], v197 offset:2048
	ds_read_b128 v[196:199], v197 offset:3072
	s_barrier
	s_waitcnt lgkmcnt(0)
	s_setprio 1
	v_mfma_f32_16x16x128_f8f6f4 v[56:59], v[16:23], v[154:161], v[56:59]
	v_mfma_f32_16x16x128_f8f6f4 v[60:63], v[16:23], v[192:199], v[60:63]
	v_mfma_f32_16x16x128_f8f6f4 v[64:67], v[164:171], v[154:161], v[64:67]
	v_mfma_f32_16x16x128_f8f6f4 v[68:71], v[164:171], v[192:199], v[68:71]
	v_mfma_f32_16x16x128_f8f6f4 v[72:75], v[208:215], v[154:161], v[72:75]
	v_mfma_f32_16x16x128_f8f6f4 v[76:79], v[208:215], v[192:199], v[76:79]
	v_mfma_f32_16x16x128_f8f6f4 v[80:83], v[216:223], v[154:161], v[80:83]
	v_mfma_f32_16x16x128_f8f6f4 v[84:87], v[216:223], v[192:199], v[84:87]
	s_setprio 0
	s_barrier
	ds_read_b128 v[16:19], v182 offset:16384
	ds_read_b128 v[20:23], v182 offset:17408
	ds_read_b128 v[164:167], v181 offset:16384
	ds_read_b128 v[168:171], v181 offset:17408
	ds_read_b128 v[200:203], v180 offset:16384
	ds_read_b128 v[204:207], v180 offset:17408
	ds_read_b128 v[208:211], v179 offset:16384
	ds_read_b128 v[212:215], v179 offset:17408
	s_waitcnt vmcnt(4)
	s_barrier
	s_waitcnt lgkmcnt(0)
	s_setprio 1
	v_mfma_f32_16x16x128_f8f6f4 v[88:91], v[16:23], v[0:7], v[88:91]
	v_mfma_f32_16x16x128_f8f6f4 v[92:95], v[16:23], v[8:15], v[92:95]
	v_mfma_f32_16x16x128_f8f6f4 v[96:99], v[164:171], v[0:7], v[96:99]
	v_mfma_f32_16x16x128_f8f6f4 v[100:103], v[164:171], v[8:15], v[100:103]
	v_mfma_f32_16x16x128_f8f6f4 v[104:107], v[200:207], v[0:7], v[104:107]
	v_mfma_f32_16x16x128_f8f6f4 v[108:111], v[200:207], v[8:15], v[108:111]
	v_mfma_f32_16x16x128_f8f6f4 v[114:117], v[208:215], v[0:7], v[114:117]
	v_mfma_f32_16x16x128_f8f6f4 v[118:121], v[208:215], v[8:15], v[118:121]
	s_setprio 0
	s_setprio 1
	v_mfma_f32_16x16x128_f8f6f4 v[122:125], v[16:23], v[154:161], v[122:125]
	v_mfma_f32_16x16x128_f8f6f4 v[126:129], v[16:23], v[192:199], v[126:129]
	v_mfma_f32_16x16x128_f8f6f4 v[130:133], v[164:171], v[154:161], v[130:133]
	v_mfma_f32_16x16x128_f8f6f4 v[134:137], v[164:171], v[192:199], v[134:137]
	v_mfma_f32_16x16x128_f8f6f4 v[138:141], v[200:207], v[154:161], v[138:141]
	v_mfma_f32_16x16x128_f8f6f4 v[142:145], v[200:207], v[192:199], v[142:145]
	v_mfma_f32_16x16x128_f8f6f4 v[146:149], v[208:215], v[154:161], v[146:149]
	v_mfma_f32_16x16x128_f8f6f4 v[150:153], v[208:215], v[192:199], v[150:153]
	s_setprio 0
	s_barrier
	ds_read_b128 v[0:3], v184
	ds_read_b128 v[4:7], v184 offset:1024
	ds_read_b128 v[8:11], v184 offset:2048
	ds_read_b128 v[12:15], v184 offset:3072
	ds_read_b128 v[16:19], v182 offset:32768
	ds_read_b128 v[20:23], v182 offset:33792
	ds_read_b128 v[154:157], v181 offset:32768
	ds_read_b128 v[158:161], v181 offset:33792
	ds_read_b128 v[164:167], v180 offset:32768
	ds_read_b128 v[168:171], v180 offset:33792
	ds_read_b128 v[192:195], v179 offset:32768
	ds_read_b128 v[196:199], v179 offset:33792
	s_waitcnt vmcnt(2)
	s_barrier
	s_waitcnt lgkmcnt(0)
	s_setprio 1
	v_mfma_f32_16x16x128_f8f6f4 v[24:27], v[16:23], v[0:7], v[24:27]
	v_mfma_f32_16x16x128_f8f6f4 v[28:31], v[16:23], v[8:15], v[28:31]
	v_mfma_f32_16x16x128_f8f6f4 v[32:35], v[154:161], v[0:7], v[32:35]
	v_mfma_f32_16x16x128_f8f6f4 v[36:39], v[154:161], v[8:15], v[36:39]
	v_mfma_f32_16x16x128_f8f6f4 v[40:43], v[164:171], v[0:7], v[40:43]
	v_mfma_f32_16x16x128_f8f6f4 v[44:47], v[164:171], v[8:15], v[44:47]
	v_mfma_f32_16x16x128_f8f6f4 v[48:51], v[192:199], v[0:7], v[48:51]
	v_mfma_f32_16x16x128_f8f6f4 v[52:55], v[192:199], v[8:15], v[52:55]
	s_setprio 0
	s_barrier
	ds_read_b128 v[200:203], v183
	ds_read_b128 v[204:207], v183 offset:1024
	ds_read_b128 v[208:211], v183 offset:2048
	ds_read_b128 v[212:215], v183 offset:3072
	s_waitcnt vmcnt(0)
	s_barrier
	s_waitcnt lgkmcnt(0)
	s_setprio 1
	v_mfma_f32_16x16x128_f8f6f4 v[56:59], v[16:23], v[200:207], v[56:59]
	v_mfma_f32_16x16x128_f8f6f4 v[60:63], v[16:23], v[208:215], v[60:63]
	v_mfma_f32_16x16x128_f8f6f4 v[64:67], v[154:161], v[200:207], v[64:67]
	v_mfma_f32_16x16x128_f8f6f4 v[68:71], v[154:161], v[208:215], v[68:71]
	v_mfma_f32_16x16x128_f8f6f4 v[72:75], v[164:171], v[200:207], v[72:75]
	v_mfma_f32_16x16x128_f8f6f4 v[76:79], v[164:171], v[208:215], v[76:79]
	v_mfma_f32_16x16x128_f8f6f4 v[80:83], v[192:199], v[200:207], v[80:83]
	v_mfma_f32_16x16x128_f8f6f4 v[84:87], v[192:199], v[208:215], v[84:87]
	s_setprio 0
	s_barrier
	ds_read_b128 v[16:19], v182 offset:49152
	ds_read_b128 v[20:23], v182 offset:50176
	ds_read_b128 v[154:157], v181 offset:49152
	ds_read_b128 v[158:161], v181 offset:50176
	ds_read_b128 v[164:167], v180 offset:49152
	ds_read_b128 v[168:171], v180 offset:50176
	ds_read_b128 v[192:195], v179 offset:49152
	ds_read_b128 v[196:199], v179 offset:50176
	s_barrier
	s_waitcnt lgkmcnt(0)
	s_setprio 1
	v_mfma_f32_16x16x128_f8f6f4 v[88:91], v[16:23], v[0:7], v[88:91]
	v_mfma_f32_16x16x128_f8f6f4 v[92:95], v[16:23], v[8:15], v[92:95]
	v_mfma_f32_16x16x128_f8f6f4 v[96:99], v[154:161], v[0:7], v[96:99]
	v_mfma_f32_16x16x128_f8f6f4 v[100:103], v[154:161], v[8:15], v[100:103]
	v_mfma_f32_16x16x128_f8f6f4 v[104:107], v[164:171], v[0:7], v[104:107]
	v_mfma_f32_16x16x128_f8f6f4 v[108:111], v[164:171], v[8:15], v[108:111]
	v_mfma_f32_16x16x128_f8f6f4 v[114:117], v[192:199], v[0:7], v[114:117]
	v_mfma_f32_16x16x128_f8f6f4 v[118:121], v[192:199], v[8:15], v[118:121]
	s_setprio 0
	s_setprio 1
	v_mfma_f32_16x16x128_f8f6f4 v[122:125], v[16:23], v[200:207], v[122:125]
	v_mfma_f32_16x16x128_f8f6f4 v[126:129], v[16:23], v[208:215], v[126:129]
	v_mfma_f32_16x16x128_f8f6f4 v[130:133], v[154:161], v[200:207], v[130:133]
	v_mfma_f32_16x16x128_f8f6f4 v[134:137], v[154:161], v[208:215], v[134:137]
	v_mfma_f32_16x16x128_f8f6f4 v[138:141], v[164:171], v[200:207], v[138:141]
	v_mfma_f32_16x16x128_f8f6f4 v[142:145], v[164:171], v[208:215], v[142:145]
	v_mfma_f32_16x16x128_f8f6f4 v[146:149], v[192:199], v[200:207], v[146:149]
	v_mfma_f32_16x16x128_f8f6f4 v[150:153], v[192:199], v[208:215], v[150:153]
	s_setprio 0
	s_movk_i32 s4, 0x100
	v_cmp_gt_u32_e32 vcc, s4, v113
	s_barrier
	s_and_saveexec_b64 s[4:5], vcc
	s_cbranch_execz .LBB0_344
	s_barrier
